# stack: NA odd-step DMA issued in even step, NA K/V fragment reads clustered upfront, MLA zero-adds removed
# baseline (speedup 1.0000x reference)
.LBB0_772:
	s_min_i32 s98, s1, s81
	s_mov_b32 s99, s93
	s_lshl_b64 s[98:99], s[98:99], 16
	s_add_i32 s100, s1, -4
	s_and_b32 s100, s100, 2
	s_mulk_i32 s100, 0x3400
	v_lshl_add_u64 v[220:221], v[164:165], 0, s[98:99]
	s_add_i32 s101, s100, s75
	s_mov_b32 m0, s101
	s_nop 0
	global_load_lds_dwordx4 v[220:221], off
	s_and_b64 vcc, exec, s[4:5]
	s_cbranch_vccnz .Lna_skipK
	v_lshl_add_u64 v[220:221], v[166:167], 0, s[98:99]
	s_add_i32 s101, s100, 0x2000
	s_mov_b32 m0, s101
	s_nop 0
	global_load_lds_dwordx4 v[220:221], off
.Lna_skipK:
	s_mov_b32 s98, s92
	s_mov_b32 s99, s93
	s_lshl_b64 s[98:99], s[98:99], 7
	s_mul_i32 s100, s82, 0x2400
	v_lshl_add_u64 v[220:221], v[168:169], 0, s[98:99]
	s_add_i32 s101, s100, s80
	s_mov_b32 m0, s101
	s_nop 0
	global_load_lds_dwordx4 v[220:221], off
	s_and_b64 vcc, exec, s[4:5]
	s_cbranch_vccnz .Lna_skipV
	v_lshl_add_u64 v[220:221], v[170:171], 0, s[98:99]
	s_add_i32 s101, s100, 0xf000
	s_mov_b32 m0, s101
	s_nop 0
	global_load_lds_dwordx4 v[220:221], off

.LBB0_782:
	s_add_i32 s87, s1, -4
	s_add_i32 s0, s74, -3
	s_cmp_ge_i32 s0, s33
	s_cselect_b64 s[94:95], -1, 0
	s_cmp_lt_i32 s0, s88
	s_cselect_b64 s[96:97], -1, 0
	s_and_b64 s[94:95], s[94:95], s[96:97]
	s_add_i32 s0, s1, -3
	s_cmp_lt_i32 s87, s81
	s_cselect_b64 s[96:97], -1, 0
	s_and_b64 vcc, s[94:95], s[96:97]
	s_andn2_b64 vcc, exec, vcc
	s_cbranch_vccnz .LBB0_817
	s_and_b32 s90, s0, 3
	s_mulk_i32 s90, 0x3400
	v_add_u32_e32 v0, s90, v173
	ds_read_b128 v[64:67], v0 offset:4608
	ds_read_b128 v[68:71], v0
	ds_read_b128 v[72:75], v0 offset:32
	ds_read_b128 v[220:223], v0 offset:4640
	ds_read_b128 v[224:227], v0 offset:64
	ds_read_b128 v[228:231], v0 offset:4672
	ds_read_b128 v[232:235], v0 offset:96
	ds_read_b128 v[236:239], v0 offset:4704
	s_waitcnt lgkmcnt(7)
	v_mfma_f32_32x32x16_bf16 v[96:111], v[64:67], v[146:149], v[112:127]
	s_waitcnt lgkmcnt(6)
	v_mfma_f32_32x32x16_bf16 v[130:145], v[68:71], v[146:149], v[112:127]
	s_waitcnt lgkmcnt(5)
	v_mfma_f32_32x32x16_bf16 v[130:145], v[72:75], v[150:153], v[130:145]
	s_waitcnt lgkmcnt(4)
	v_mfma_f32_32x32x16_bf16 v[96:111], v[220:223], v[150:153], v[96:111]
	s_waitcnt lgkmcnt(3)
	v_mfma_f32_32x32x16_bf16 v[130:145], v[224:227], v[154:157], v[130:145]
	s_waitcnt lgkmcnt(2)
	v_mfma_f32_32x32x16_bf16 v[96:111], v[228:231], v[154:157], v[96:111]
	s_waitcnt lgkmcnt(1)
	v_mfma_f32_32x32x16_bf16 v[130:145], v[232:235], v[158:161], v[130:145]
	s_waitcnt lgkmcnt(0)
	v_mfma_f32_32x32x16_bf16 v[96:111], v[236:239], v[158:161], v[96:111]
	ds_read_b32 v0, v179 offset:128
	ds_read_b32 v64, v179
	ds_read_b32 v65, v179 offset:4
	ds_read_b32 v66, v179 offset:8
	ds_read_b32 v67, v179 offset:12
	ds_read_b32 v68, v179 offset:32
	ds_read_b32 v69, v179 offset:36
	ds_read_b32 v70, v179 offset:40
	ds_read_b32 v71, v179 offset:44
	ds_read_b32 v72, v179 offset:64
	ds_read_b32 v73, v179 offset:68
	ds_read_b32 v74, v179 offset:72
	ds_read_b32 v75, v179 offset:76
	ds_read_b32 v76, v179 offset:96
	ds_read_b32 v77, v179 offset:100
	ds_read_b32 v78, v179 offset:104
	ds_read_b32 v79, v179 offset:108
	s_waitcnt lgkmcnt(0)
	v_add_f32_e32 v64, v130, v64
	v_cndmask_b32_e64 v64, v177, v64, s[6:7]
	v_add_f32_e32 v65, v131, v65
	v_cndmask_b32_e64 v65, v177, v65, s[10:11]
	v_add_f32_e32 v66, v132, v66
	v_cndmask_b32_e64 v66, v177, v66, s[14:15]
	v_add_f32_e32 v67, v133, v67
	v_cndmask_b32_e64 v67, v177, v67, s[18:19]
	v_add_f32_e32 v68, v134, v68
	v_cndmask_b32_e64 v68, v177, v68, s[22:23]
	v_add_f32_e32 v69, v135, v69
	v_cndmask_b32_e64 v69, v177, v69, s[26:27]
	v_add_f32_e32 v70, v136, v70
	v_cndmask_b32_e64 v70, v177, v70, s[30:31]
	v_add_f32_e32 v71, v137, v71
	v_cndmask_b32_e64 v71, v177, v71, s[36:37]
	v_add_f32_e32 v72, v138, v72
	v_cndmask_b32_e64 v72, v177, v72, s[40:41]
	v_add_f32_e32 v73, v139, v73
	v_cndmask_b32_e64 v73, v177, v73, s[44:45]
	v_add_f32_e32 v74, v140, v74
	v_cndmask_b32_e64 v74, v177, v74, s[48:49]
	v_add_f32_e32 v75, v141, v75
	v_cndmask_b32_e64 v75, v177, v75, s[52:53]
	v_add_f32_e32 v76, v142, v76
	v_cndmask_b32_e64 v76, v177, v76, s[56:57]
	v_add_f32_e32 v77, v143, v77
	v_cndmask_b32_e64 v77, v177, v77, s[60:61]
	v_add_f32_e32 v78, v144, v78
	v_cndmask_b32_e64 v78, v177, v78, s[64:65]
	v_add_f32_e32 v79, v145, v79
	v_cndmask_b32_e64 v79, v177, v79, s[68:69]
	ds_read_b32 v3, v179 offset:132
	ds_read_b32 v129, v179 offset:136
	ds_read_b32 v130, v179 offset:140
	ds_read_b32 v131, v179 offset:160
	ds_read_b32 v132, v179 offset:164
	ds_read_b32 v133, v179 offset:168
	ds_read_b32 v134, v179 offset:172
	ds_read_b32 v135, v179 offset:192
	ds_read_b32 v136, v179 offset:196
	ds_read_b32 v137, v179 offset:200
	ds_read_b32 v138, v179 offset:204
	ds_read_b32 v139, v179 offset:224
	ds_read_b32 v140, v179 offset:228
	ds_read_b32 v142, v179 offset:232
	ds_read_b32 v141, v179 offset:236
	s_waitcnt lgkmcnt(14)
	v_add_f32_e32 v0, v96, v0
	v_cndmask_b32_e64 v96, v177, v0, s[8:9]
	v_add_f32_e32 v0, v97, v3
	v_cndmask_b32_e64 v97, v177, v0, s[12:13]
	s_waitcnt lgkmcnt(13)
	v_add_f32_e32 v0, v98, v129
	v_cndmask_b32_e64 v98, v177, v0, s[16:17]
	s_waitcnt lgkmcnt(12)
	v_add_f32_e32 v0, v99, v130
	v_cndmask_b32_e64 v99, v177, v0, s[20:21]
	s_waitcnt lgkmcnt(11)
	v_add_f32_e32 v0, v100, v131
	v_cndmask_b32_e64 v100, v177, v0, s[24:25]
	s_waitcnt lgkmcnt(10)
	v_add_f32_e32 v0, v101, v132
	v_cndmask_b32_e64 v101, v177, v0, s[28:29]
	s_waitcnt lgkmcnt(9)
	v_add_f32_e32 v0, v102, v133
	v_cndmask_b32_e64 v102, v177, v0, s[34:35]
	s_waitcnt lgkmcnt(8)
	v_add_f32_e32 v0, v103, v134
	v_cndmask_b32_e64 v103, v177, v0, s[38:39]
	s_waitcnt lgkmcnt(7)
	v_add_f32_e32 v0, v104, v135
	v_cndmask_b32_e64 v104, v177, v0, s[42:43]
	s_waitcnt lgkmcnt(6)
	v_add_f32_e32 v0, v105, v136
	v_cndmask_b32_e64 v105, v177, v0, s[46:47]
	s_waitcnt lgkmcnt(5)
	v_add_f32_e32 v0, v106, v137
	v_cndmask_b32_e64 v106, v177, v0, s[50:51]
	s_waitcnt lgkmcnt(4)
	v_add_f32_e32 v0, v107, v138
	v_cndmask_b32_e64 v107, v177, v0, s[54:55]
	s_waitcnt lgkmcnt(3)
	v_add_f32_e32 v0, v108, v139
	v_cndmask_b32_e64 v108, v177, v0, s[58:59]
	s_waitcnt lgkmcnt(2)
	v_add_f32_e32 v0, v109, v140
	v_cndmask_b32_e64 v109, v177, v0, s[62:63]
	s_waitcnt lgkmcnt(1)
	v_add_f32_e32 v0, v110, v142
	v_cndmask_b32_e64 v110, v177, v0, s[66:67]
	s_waitcnt lgkmcnt(0)
	v_add_f32_e32 v0, v111, v141
	v_cndmask_b32_e64 v111, v177, v0, s[70:71]
	v_max3_f32 v0, v64, v65, v96
	v_max3_f32 v3, v66, v67, v97
	s_nop 0
	v_max3_f32 v0, v0, v98, v99
	v_max3_f32 v3, v3, v70, v71
	s_nop 0
	v_max3_f32 v0, v0, v68, v69
	v_max3_f32 v3, v3, v102, v103
	s_nop 0
	v_max3_f32 v0, v0, v100, v101
	v_max3_f32 v3, v3, v74, v75
	s_nop 0
	v_max3_f32 v0, v0, v72, v73
	v_max3_f32 v3, v3, v106, v107
	s_nop 0
	v_max3_f32 v0, v0, v104, v105
	v_max3_f32 v3, v3, v78, v79
	s_nop 0
	v_max3_f32 v0, v0, v76, v77
	v_max3_f32 v3, v3, v110, v111
	s_nop 0
	v_max3_f32 v0, v0, v108, v109
	v_max_f32_e32 v3, v3, v3
	v_max_f32_e32 v0, v0, v0
	v_max_f32_e32 v0, v0, v3
	v_mov_b32_e32 v3, v0
	s_nop 1
	v_permlane32_swap_b32_e32 v0, v3
	v_max_f32_e32 v3, v3, v3
	v_max_f32_e32 v0, v0, v0
	v_max_f32_e32 v3, v0, v3
	s_and_b64 vcc, exec, s[72:73]
	s_cbranch_vccz .LBB0_818

.LBB0_818:
	v_exp_f32_e32 v16, v16
	v_exp_f32_e32 v80, v80
	v_exp_f32_e32 v0, v17
	v_exp_f32_e32 v188, v95
	v_exp_f32_e32 v18, v18
	v_add_f32_e32 v189, v80, v16
	v_exp_f32_e32 v82, v82
	v_pk_add_f32 v[130:131], v[188:189], v[0:1]
	v_exp_f32_e32 v192, v81
	v_pk_add_f32 v[190:191], v[130:131], v[130:131] op_sel_hi:[0,1]
	v_exp_f32_e32 v190, v19
	v_add_f32_e32 v193, v82, v18
	v_exp_f32_e32 v20, v20
	v_exp_f32_e32 v84, v84
	v_pk_add_f32 v[130:131], v[192:193], v[190:191]
	v_exp_f32_e32 v196, v89
	v_pk_add_f32 v[194:195], v[130:131], v[130:131] op_sel_hi:[0,1]
	v_exp_f32_e32 v194, v21
	v_add_f32_e32 v197, v84, v20
	v_exp_f32_e32 v22, v22
	v_exp_f32_e32 v86, v86
	v_pk_add_f32 v[130:131], v[196:197], v[194:195]
	v_exp_f32_e32 v200, v83
	v_pk_add_f32 v[198:199], v[130:131], v[130:131] op_sel_hi:[0,1]
	v_exp_f32_e32 v198, v23
	v_add_f32_e32 v201, v86, v22
	v_exp_f32_e32 v24, v24
	v_exp_f32_e32 v88, v88
	v_pk_add_f32 v[130:131], v[200:201], v[198:199]
	v_exp_f32_e32 v204, v91
	v_pk_add_f32 v[202:203], v[130:131], v[130:131] op_sel_hi:[0,1]
	v_exp_f32_e32 v202, v25
	v_add_f32_e32 v205, v88, v24
	v_exp_f32_e32 v26, v26
	v_exp_f32_e32 v90, v90
	v_pk_add_f32 v[130:131], v[204:205], v[202:203]
	v_exp_f32_e32 v210, v85
	v_pk_add_f32 v[208:209], v[130:131], v[130:131] op_sel_hi:[0,1]
	v_exp_f32_e32 v208, v27
	v_add_f32_e32 v211, v90, v26
	v_exp_f32_e32 v60, v60
	v_exp_f32_e32 v92, v92
	v_pk_add_f32 v[130:131], v[210:211], v[208:209]
	v_exp_f32_e32 v214, v93
	v_pk_add_f32 v[212:213], v[130:131], v[130:131] op_sel_hi:[0,1]
	v_exp_f32_e32 v212, v61
	v_add_f32_e32 v215, v92, v60
	s_and_b32 s72, s87, 2
	s_mulk_i32 s72, 0x2400
	v_pk_add_f32 v[130:131], v[214:215], v[212:213]
	v_add_u32_e32 v17, s72, v173
	v_pk_add_f32 v[216:217], v[130:131], v[130:131] op_sel_hi:[0,1]
	v_exp_f32_e32 v216, v63
	v_exp_f32_e32 v218, v87
	v_exp_f32_e32 v62, v62
	v_exp_f32_e32 v94, v94
	v_cvt_pk_bf16_f32 v130, v16, v0
	v_cvt_pk_bf16_f32 v131, v18, v190
	v_cvt_pk_bf16_f32 v132, v20, v194
	v_cvt_pk_bf16_f32 v133, v22, v198
	v_cvt_pk_bf16_f32 v134, v24, v202
	v_cvt_pk_bf16_f32 v135, v26, v208
	v_cvt_pk_bf16_f32 v136, v60, v212
	v_cvt_pk_bf16_f32 v137, v62, v216
	v_cvt_pk_bf16_f32 v138, v80, v188
	v_cvt_pk_bf16_f32 v139, v82, v192
	v_cvt_pk_bf16_f32 v140, v84, v196
	v_cvt_pk_bf16_f32 v141, v86, v200
	v_cvt_pk_bf16_f32 v142, v88, v204
	v_cvt_pk_bf16_f32 v143, v90, v210
	v_cvt_pk_bf16_f32 v144, v92, v214
	v_cvt_pk_bf16_f32 v145, v94, v218
	ds_read_b128 v[184:187], v17 offset:53248
	ds_read_b128 v[220:223], v17 offset:57856
	ds_read_b128 v[224:227], v17 offset:53280
	ds_read_b128 v[228:231], v17 offset:57888
	ds_read_b128 v[232:235], v17 offset:53312
	ds_read_b128 v[236:239], v17 offset:57920
	ds_read_b128 v[240:243], v17 offset:53344
	s_waitcnt lgkmcnt(6)
	v_mfma_f32_32x32x16_bf16 v[44:59], v[184:187], v[130:133], v[44:59]
	v_add_f32_e32 v219, v94, v62
	v_mov_b32_e32 v19, v190
	v_mov_b32_e32 v21, v194
	v_mov_b32_e32 v23, v198
	v_mov_b32_e32 v25, v202
	v_mov_b32_e32 v27, v208
	s_waitcnt lgkmcnt(5)
	v_mfma_f32_32x32x16_bf16 v[28:43], v[220:223], v[130:133], v[28:43]
	ds_read_b128 v[130:133], v17 offset:57952
	v_mov_b32_e32 v61, v212
	v_mov_b32_e32 v63, v216
	v_mov_b32_e32 v95, v188
	v_mov_b32_e32 v81, v192
	v_mov_b32_e32 v89, v196
	v_mov_b32_e32 v83, v200
	s_waitcnt lgkmcnt(5)
	v_mfma_f32_32x32x16_bf16 v[44:59], v[224:227], v[134:137], v[44:59]
	v_mov_b32_e32 v91, v204
	v_mov_b32_e32 v85, v210
	v_mov_b32_e32 v93, v214
	v_mov_b32_e32 v87, v218
	s_waitcnt lgkmcnt(4)
	v_mfma_f32_32x32x16_bf16 v[28:43], v[228:231], v[134:137], v[28:43]
	s_waitcnt lgkmcnt(3)
	v_mfma_f32_32x32x16_bf16 v[44:59], v[232:235], v[138:141], v[44:59]
	s_waitcnt lgkmcnt(2)
	v_mfma_f32_32x32x16_bf16 v[28:43], v[236:239], v[138:141], v[28:43]
	s_waitcnt lgkmcnt(1)
	v_mfma_f32_32x32x16_bf16 v[44:59], v[240:243], v[142:145], v[44:59]
	s_waitcnt lgkmcnt(0)
	v_mfma_f32_32x32x16_bf16 v[28:43], v[130:133], v[142:145], v[28:43]
	v_add_f32_e64 v130, v218, v216
	v_add_f32_e64 v131, v219, v217
	v_add_f32_e32 v17, v130, v131
	v_add_f32_e32 v178, v178, v17
	v_mov_b32_e32 v17, v0
	s_andn2_b64 vcc, exec, s[96:97]
	s_cbranch_vccnz .LBB0_767
.LBB0_819:
.LBB0_823:
	v_cndmask_b32_e64 v0, 0, 1, s[94:95]
	v_cmp_ne_u32_e64 s[72:73], 1, v0
	s_andn2_b64 vcc, exec, s[94:95]
	s_cbranch_vccnz .LBB0_829
	s_mov_b64 s[94:95], -1
	s_cmp_eq_u32 s89, 3
	v_mov_b32_e32 v0, v3
	s_cbranch_scc1 .LBB0_827
	v_cmp_lt_f32_e32 vcc, s3, v3
	s_cbranch_vccz .LBB0_866
	v_max_f32_e32 v0, v3, v3
	v_max_f32_e32 v0, 0, v0

.LBB0_829:
	s_add_i32 s74, s74, -2
	s_cmp_ge_i32 s74, s33
	s_cselect_b64 s[90:91], -1, 0
	s_cmp_lt_i32 s74, s88
	s_cselect_b64 s[94:95], -1, 0
	s_and_b64 s[90:91], s[90:91], s[94:95]
	s_cmp_le_i32 s85, s81
	s_cselect_b64 s[94:95], -1, 0
	v_mov_b64_e32 v[144:145], v[126:127]
	s_and_b64 s[90:91], s[90:91], s[94:95]
	v_mov_b64_e32 v[142:143], v[124:125]
	v_mov_b64_e32 v[140:141], v[122:123]
	v_mov_b64_e32 v[138:139], v[120:121]
	v_mov_b64_e32 v[136:137], v[118:119]
	v_mov_b64_e32 v[134:135], v[116:117]
	v_mov_b64_e32 v[132:133], v[114:115]
	v_mov_b64_e32 v[130:131], v[112:113]
	v_mov_b32_e32 v112, v4
	v_mov_b32_e32 v113, v5
	v_mov_b32_e32 v114, v6
	v_mov_b32_e32 v115, v7
	v_mov_b32_e32 v116, v8
	v_mov_b32_e32 v117, v9
	v_mov_b32_e32 v118, v10
	v_mov_b32_e32 v119, v11
	v_mov_b32_e32 v120, v12
	v_mov_b32_e32 v121, v13
	v_mov_b32_e32 v122, v14
	v_mov_b32_e32 v123, v15
	v_mov_b32_e32 v124, v181
	v_mov_b32_e32 v125, v182
	v_mov_b32_e32 v126, v183
	v_mov_b32_e32 v127, v128
	s_andn2_b64 vcc, exec, s[90:91]
	s_cbranch_vccnz .LBB0_863
	s_mulk_i32 s77, 0x3400
	v_add_u32_e32 v0, s77, v173
	ds_read_b128 v[4:7], v0 offset:4608
	ds_read_b128 v[8:11], v0
	ds_read_b128 v[12:15], v0 offset:32
	ds_read_b128 v[220:223], v0 offset:4640
	ds_read_b128 v[224:227], v0 offset:64
	ds_read_b128 v[228:231], v0 offset:4672
	ds_read_b128 v[232:235], v0 offset:96
	ds_read_b128 v[236:239], v0 offset:4704
	v_mov_b32_e32 v17, 0xff800000
	v_mov_b32_e32 v16, 0xff800000
	s_waitcnt lgkmcnt(6)
	v_mfma_f32_32x32x16_bf16 v[80:95], v[8:11], v[146:149], v[130:145]
	v_mfma_f32_32x32x16_bf16 v[130:145], v[4:7], v[146:149], v[130:145]
	s_waitcnt lgkmcnt(5)
	v_mfma_f32_32x32x16_bf16 v[80:95], v[12:15], v[150:153], v[80:95]
	s_waitcnt lgkmcnt(4)
	v_mfma_f32_32x32x16_bf16 v[130:145], v[220:223], v[150:153], v[130:145]
	s_waitcnt lgkmcnt(3)
	v_mfma_f32_32x32x16_bf16 v[80:95], v[224:227], v[154:157], v[80:95]
	s_waitcnt lgkmcnt(2)
	v_mfma_f32_32x32x16_bf16 v[130:145], v[228:231], v[154:157], v[130:145]
	s_waitcnt lgkmcnt(1)
	v_mfma_f32_32x32x16_bf16 v[80:95], v[232:235], v[158:161], v[80:95]
	s_waitcnt lgkmcnt(0)
	v_mfma_f32_32x32x16_bf16 v[130:145], v[236:239], v[158:161], v[130:145]
	ds_read_b32 v0, v179 offset:252
	ds_read_b32 v16, v179 offset:124
	ds_read_b32 v17, v179 offset:128
	ds_read_b32 v18, v179 offset:132
	ds_read_b32 v19, v179 offset:136
	ds_read_b32 v20, v179 offset:156
	ds_read_b32 v21, v179 offset:160
	ds_read_b32 v22, v179 offset:164
	ds_read_b32 v23, v179 offset:168
	ds_read_b32 v24, v179 offset:188
	ds_read_b32 v25, v179 offset:192
	ds_read_b32 v26, v179 offset:196
	ds_read_b32 v27, v179 offset:200
	ds_read_b32 v60, v179 offset:220
	ds_read_b32 v61, v179 offset:224
	ds_read_b32 v62, v179 offset:228
	ds_read_b32 v63, v179 offset:232
	s_waitcnt lgkmcnt(0)
	v_add_f32_e32 v16, v80, v16
	v_cndmask_b32_e64 v16, v177, v16, s[6:7]
	v_add_f32_e32 v17, v81, v17
	v_cndmask_b32_e64 v17, v177, v17, s[10:11]
	v_add_f32_e32 v18, v82, v18
	v_cndmask_b32_e64 v18, v177, v18, s[14:15]
	v_add_f32_e32 v19, v83, v19
	v_cndmask_b32_e64 v19, v177, v19, s[18:19]
	v_add_f32_e32 v20, v84, v20
	v_cndmask_b32_e64 v20, v177, v20, s[22:23]
	v_add_f32_e32 v21, v85, v21
	v_cndmask_b32_e64 v21, v177, v21, s[26:27]
	v_add_f32_e32 v22, v86, v22
	v_cndmask_b32_e64 v22, v177, v22, s[30:31]
	v_add_f32_e32 v23, v87, v23
	v_cndmask_b32_e64 v23, v177, v23, s[36:37]
	v_add_f32_e32 v24, v88, v24
	v_cndmask_b32_e64 v24, v177, v24, s[40:41]
	v_add_f32_e32 v25, v89, v25
	v_cndmask_b32_e64 v25, v177, v25, s[44:45]
	v_add_f32_e32 v26, v90, v26
	v_cndmask_b32_e64 v26, v177, v26, s[48:49]
	v_add_f32_e32 v27, v91, v27
	v_cndmask_b32_e64 v27, v177, v27, s[52:53]
	v_add_f32_e32 v60, v92, v60
	v_cndmask_b32_e64 v60, v177, v60, s[56:57]
	v_add_f32_e32 v61, v93, v61
	v_cndmask_b32_e64 v61, v177, v61, s[60:61]
	v_add_f32_e32 v62, v94, v62
	v_cndmask_b32_e64 v62, v177, v62, s[64:65]
	v_add_f32_e32 v63, v95, v63
	v_cndmask_b32_e64 v63, v177, v63, s[68:69]
	ds_read_b32 v4, v179 offset:256
	ds_read_b32 v5, v179 offset:260
	ds_read_b32 v6, v179 offset:264
	ds_read_b32 v7, v179 offset:284
	ds_read_b32 v8, v179 offset:288
	ds_read_b32 v9, v179 offset:292
	ds_read_b32 v10, v179 offset:296
	ds_read_b32 v11, v179 offset:316
	ds_read_b32 v12, v179 offset:320
	ds_read_b32 v13, v179 offset:324
	ds_read_b32 v14, v179 offset:328
	ds_read_b32 v15, v179 offset:348
	ds_read_b32 v80, v179 offset:352
	ds_read_b32 v82, v179 offset:356
	ds_read_b32 v81, v179 offset:360
	s_waitcnt lgkmcnt(14)
	v_add_f32_e32 v0, v130, v0
	v_add_f32_e32 v4, v131, v4
	s_waitcnt lgkmcnt(13)
	v_add_f32_e32 v5, v132, v5
	s_waitcnt lgkmcnt(12)
	v_add_f32_e32 v6, v133, v6
	s_waitcnt lgkmcnt(2)
	v_add_f32_e32 v87, v143, v80
	v_cndmask_b32_e64 v80, v177, v0, s[8:9]
	v_max3_f32 v0, v16, v17, v80
	s_waitcnt lgkmcnt(1)
	v_add_f32_e32 v94, v144, v82
	s_waitcnt lgkmcnt(0)
	v_add_f32_e32 v128, v145, v81
	v_cndmask_b32_e64 v82, v177, v5, s[16:17]
	v_cndmask_b32_e64 v81, v177, v6, s[20:21]
	v_max3_f32 v0, v0, v82, v81
	v_cndmask_b32_e64 v95, v177, v4, s[12:13]
	v_max3_f32 v4, v18, v19, v95
	v_add_f32_e32 v7, v134, v7
	v_add_f32_e32 v8, v135, v8
	v_add_f32_e32 v9, v136, v9
	v_add_f32_e32 v10, v137, v10
	v_max3_f32 v0, v0, v20, v21
	v_max3_f32 v4, v4, v22, v23
	v_cndmask_b32_e64 v84, v177, v7, s[24:25]
	v_cndmask_b32_e64 v89, v177, v8, s[28:29]
	v_max3_f32 v0, v0, v84, v89
	v_cndmask_b32_e64 v86, v177, v9, s[34:35]
	v_cndmask_b32_e64 v83, v177, v10, s[38:39]
	v_max3_f32 v4, v4, v86, v83
	v_add_f32_e32 v11, v138, v11
	v_add_f32_e32 v12, v139, v12
	v_add_f32_e32 v13, v140, v13
	v_add_f32_e32 v14, v141, v14
	v_max3_f32 v0, v0, v24, v25
	v_max3_f32 v4, v4, v26, v27
	v_cndmask_b32_e64 v88, v177, v11, s[42:43]
	v_cndmask_b32_e64 v91, v177, v12, s[46:47]
	v_max3_f32 v0, v0, v88, v91
	v_cndmask_b32_e64 v90, v177, v13, s[50:51]
	v_cndmask_b32_e64 v85, v177, v14, s[54:55]
	v_max3_f32 v4, v4, v90, v85
	v_add_f32_e32 v15, v142, v15
	v_max3_f32 v0, v0, v60, v61
	v_max3_f32 v4, v4, v62, v63
	v_cndmask_b32_e64 v92, v177, v15, s[58:59]
	v_cndmask_b32_e64 v93, v177, v87, s[62:63]
	v_max3_f32 v0, v0, v92, v93
	v_cndmask_b32_e64 v94, v177, v94, s[66:67]
	v_cndmask_b32_e64 v87, v177, v128, s[70:71]
	v_max3_f32 v4, v4, v94, v87
	v_max_f32_e32 v0, v0, v0
	v_max_f32_e32 v4, v4, v4
	v_max_f32_e32 v0, v0, v4
	v_mov_b32_e32 v4, v0
	s_nop 1
	v_permlane32_swap_b32_e32 v0, v4
	v_max_f32_e32 v4, v4, v4
	v_max_f32_e32 v0, v0, v0
	v_max_f32_e32 v180, v0, v4
.LBB0_863:
	s_and_b64 vcc, exec, s[72:73]
	s_cbranch_vccnz .LBB0_865
	v_exp_f32_e32 v64, v64
	v_exp_f32_e32 v96, v96
	v_exp_f32_e32 v136, v65
	v_exp_f32_e32 v0, v97
	v_exp_f32_e32 v66, v66
	v_add_f32_e32 v137, v64, v96
	v_exp_f32_e32 v98, v98
	v_pk_add_f32 v[4:5], v[136:137], v[0:1]
	v_exp_f32_e32 v140, v67
	v_pk_add_f32 v[138:139], v[4:5], v[4:5] op_sel_hi:[0,1]
	v_exp_f32_e32 v138, v99
	v_add_f32_e32 v141, v66, v98
	v_exp_f32_e32 v68, v68
	v_exp_f32_e32 v100, v100
	v_pk_add_f32 v[4:5], v[140:141], v[138:139]
	v_exp_f32_e32 v144, v69
	v_pk_add_f32 v[142:143], v[4:5], v[4:5] op_sel_hi:[0,1]
	v_exp_f32_e32 v142, v101
	v_add_f32_e32 v145, v68, v100
	v_exp_f32_e32 v70, v70
	v_exp_f32_e32 v102, v102
	v_pk_add_f32 v[4:5], v[144:145], v[142:143]
	v_exp_f32_e32 v184, v71
	v_pk_add_f32 v[182:183], v[4:5], v[4:5] op_sel_hi:[0,1]
	v_exp_f32_e32 v182, v103
	v_add_f32_e32 v185, v70, v102
	v_exp_f32_e32 v72, v72
	v_exp_f32_e32 v104, v104
	v_pk_add_f32 v[4:5], v[184:185], v[182:183]
	v_exp_f32_e32 v188, v73
	v_pk_add_f32 v[186:187], v[4:5], v[4:5] op_sel_hi:[0,1]
	v_exp_f32_e32 v186, v105
	v_add_f32_e32 v189, v72, v104
	v_exp_f32_e32 v74, v74
	v_exp_f32_e32 v106, v106
	v_pk_add_f32 v[4:5], v[188:189], v[186:187]
	v_exp_f32_e32 v192, v75
	v_pk_add_f32 v[190:191], v[4:5], v[4:5] op_sel_hi:[0,1]
	v_exp_f32_e32 v190, v107
	v_add_f32_e32 v193, v74, v106
	v_exp_f32_e32 v76, v76
	v_exp_f32_e32 v108, v108
	v_pk_add_f32 v[4:5], v[192:193], v[190:191]
	v_exp_f32_e32 v196, v77
	v_pk_add_f32 v[194:195], v[4:5], v[4:5] op_sel_hi:[0,1]
	v_exp_f32_e32 v194, v109
	v_add_f32_e32 v197, v76, v108
	s_and_b32 s0, s0, 3
	s_mulk_i32 s0, 0x2400
	v_pk_add_f32 v[4:5], v[196:197], v[194:195]
	v_add_u32_e32 v65, s0, v173
	v_pk_add_f32 v[198:199], v[4:5], v[4:5] op_sel_hi:[0,1]
	v_exp_f32_e32 v78, v78
	v_exp_f32_e32 v110, v110
	v_exp_f32_e32 v200, v79
	v_exp_f32_e32 v198, v111
	v_cvt_pk_bf16_f32 v4, v64, v136
	v_cvt_pk_bf16_f32 v5, v66, v140
	v_cvt_pk_bf16_f32 v6, v68, v144
	v_cvt_pk_bf16_f32 v7, v70, v184
	v_cvt_pk_bf16_f32 v8, v72, v188
	v_cvt_pk_bf16_f32 v9, v74, v192
	v_cvt_pk_bf16_f32 v10, v76, v196
	v_cvt_pk_bf16_f32 v11, v78, v200
	v_cvt_pk_bf16_f32 v12, v96, v0
	v_cvt_pk_bf16_f32 v13, v98, v138
	v_cvt_pk_bf16_f32 v14, v100, v142
	v_cvt_pk_bf16_f32 v15, v102, v182
	v_cvt_pk_bf16_f32 v128, v104, v186
	v_cvt_pk_bf16_f32 v129, v106, v190
	v_cvt_pk_bf16_f32 v130, v108, v194
	v_cvt_pk_bf16_f32 v131, v110, v198
	ds_read_b128 v[132:135], v65 offset:53248
	ds_read_b128 v[220:223], v65 offset:57856
	ds_read_b128 v[224:227], v65 offset:53280
	ds_read_b128 v[228:231], v65 offset:57888
	ds_read_b128 v[232:235], v65 offset:53312
	ds_read_b128 v[236:239], v65 offset:57920
	ds_read_b128 v[240:243], v65 offset:53344
	s_waitcnt lgkmcnt(6)
	v_mfma_f32_32x32x16_bf16 v[44:59], v[132:135], v[4:7], v[44:59]
	v_add_f32_e32 v201, v78, v110
	v_mov_b32_e32 v67, v140
	v_mov_b32_e32 v69, v144
	v_mov_b32_e32 v71, v184
	v_mov_b32_e32 v73, v188
	v_mov_b32_e32 v75, v192
	s_waitcnt lgkmcnt(5)
	v_mfma_f32_32x32x16_bf16 v[28:43], v[220:223], v[4:7], v[28:43]
	ds_read_b128 v[4:7], v65 offset:57952
	v_mov_b32_e32 v77, v196
	v_mov_b32_e32 v79, v200
	v_mov_b32_e32 v97, v0
	v_mov_b32_e32 v99, v138
	v_mov_b32_e32 v101, v142
	v_mov_b32_e32 v103, v182
	s_waitcnt lgkmcnt(5)
	v_mfma_f32_32x32x16_bf16 v[44:59], v[224:227], v[8:11], v[44:59]
	v_mov_b32_e32 v105, v186
	v_mov_b32_e32 v107, v190
	v_mov_b32_e32 v109, v194
	v_mov_b32_e32 v111, v198
	s_waitcnt lgkmcnt(4)
	v_mfma_f32_32x32x16_bf16 v[28:43], v[228:231], v[8:11], v[28:43]
	v_add_f32_e64 v8, v200, v198
	v_add_f32_e64 v9, v201, v199
	v_add_f32_e32 v8, v8, v9
	v_add_f32_e32 v178, v178, v8
	s_waitcnt lgkmcnt(3)
	v_mfma_f32_32x32x16_bf16 v[44:59], v[232:235], v[12:15], v[44:59]
	s_waitcnt lgkmcnt(2)
	v_mfma_f32_32x32x16_bf16 v[28:43], v[236:239], v[12:15], v[28:43]
	s_waitcnt lgkmcnt(1)
	v_mfma_f32_32x32x16_bf16 v[44:59], v[240:243], v[128:131], v[44:59]
	v_mov_b32_e32 v65, v136
	s_waitcnt lgkmcnt(0)
	v_mfma_f32_32x32x16_bf16 v[28:43], v[4:7], v[128:131], v[28:43]

.LBB0_893:
	ds_read_b128 v[118:121], v181 offset:32
	ds_read_b128 v[138:141], v181 offset:6688
	s_waitcnt lgkmcnt(3)
	v_mfma_f32_32x32x16_bf16 v[80:95], v[64:67], v[144:147], v[32:47]
	v_exp_f32_e32 v117, v122
	v_exp_f32_e32 v142, v123
	v_exp_f32_e32 v143, v124
	v_exp_f32_e32 v202, v125
	v_exp_f32_e32 v126, v126
	v_exp_f32_e32 v127, v127
	s_waitcnt lgkmcnt(2)
	v_mfma_f32_32x32x16_bf16 v[64:79], v[112:115], v[144:147], v[32:47]
	ds_read_b128 v[112:115], v181 offset:64
	ds_read_b128 v[122:125], v181 offset:6720
	s_waitcnt lgkmcnt(3)
	v_mfma_f32_32x32x16_bf16 v[80:95], v[118:121], v[148:151], v[80:95]
	v_cvt_pk_bf16_f32 v118, v117, v142
	v_add_f32_e32 v117, v143, v117
	v_add_f32_e32 v120, v202, v142
	v_add_f32_e32 v117, v126, v117
	s_waitcnt lgkmcnt(2)
	v_mfma_f32_32x32x16_bf16 v[64:79], v[138:141], v[148:151], v[64:79]
	v_add_f32_e32 v121, v127, v120
	v_exp_f32_e32 v203, v128
	v_exp_f32_e32 v204, v129
	v_exp_f32_e32 v205, v130
	v_exp_f32_e32 v213, v131
	v_exp_f32_e32 v214, v132
	v_exp_f32_e32 v215, v133
	v_cvt_pk_bf16_f32 v119, v143, v202
	v_cvt_pk_bf16_f32 v120, v126, v127
	ds_read_b128 v[126:129], v181 offset:96
	ds_read_b128 v[130:133], v181 offset:6752
	s_waitcnt lgkmcnt(3)
	v_mfma_f32_32x32x16_bf16 v[80:95], v[112:115], v[152:155], v[80:95]
	v_add_f32_e32 v112, v203, v117
	v_add_f32_e32 v113, v204, v121
	v_add_f32_e32 v114, v205, v112
	v_add_f32_e32 v113, v213, v113
	v_add_f32_e32 v114, v214, v114
	v_add_f32_e32 v115, v215, v113
	s_waitcnt lgkmcnt(2)
	v_mfma_f32_32x32x16_bf16 v[64:79], v[122:125], v[152:155], v[64:79]
	v_exp_f32_e32 v138, v134
	v_exp_f32_e32 v139, v135
	v_exp_f32_e32 v140, v136
	v_exp_f32_e32 v141, v137
	v_cvt_pk_bf16_f32 v121, v203, v204
	v_cvt_pk_bf16_f32 v112, v205, v213
	v_cvt_pk_bf16_f32 v113, v214, v215
	ds_read_b128 v[122:125], v181 offset:128
	ds_read_b128 v[134:137], v181 offset:6784
	s_waitcnt lgkmcnt(3)
	v_mfma_f32_32x32x16_bf16 v[80:95], v[126:129], v[156:159], v[80:95]
	v_exp_f32_e32 v117, v96
	v_exp_f32_e32 v142, v97
	v_add_f32_e32 v96, v138, v114
	v_add_f32_e32 v97, v139, v115
	v_exp_f32_e32 v203, v100
	v_exp_f32_e32 v204, v101
	s_waitcnt lgkmcnt(2)
	v_mfma_f32_32x32x16_bf16 v[64:79], v[130:133], v[156:159], v[64:79]
	v_add_f32_e32 v100, v140, v96
	v_add_f32_e32 v101, v141, v97
	v_exp_f32_e32 v143, v98
	v_exp_f32_e32 v202, v99
	v_cvt_pk_bf16_f32 v114, v138, v139
	v_cvt_pk_bf16_f32 v115, v140, v141
	ds_read_b128 v[96:99], v181 offset:160
	ds_read_b128 v[126:129], v181 offset:6816
	s_waitcnt lgkmcnt(3)
	v_mfma_f32_32x32x16_bf16 v[80:95], v[122:125], v[160:163], v[80:95]
	v_exp_f32_e32 v130, v102
	v_add_f32_e32 v102, v117, v100
	v_add_f32_e32 v101, v142, v101
	v_exp_f32_e32 v131, v104
	v_add_f32_e32 v102, v143, v102
	v_add_f32_e32 v104, v202, v101
	s_waitcnt lgkmcnt(2)
	v_mfma_f32_32x32x16_bf16 v[64:79], v[134:137], v[160:163], v[64:79]
	v_cvt_pk_bf16_f32 v100, v117, v142
	v_add_f32_e32 v117, v203, v102
	v_add_f32_e32 v134, v204, v104
	v_exp_f32_e32 v103, v103
	v_exp_f32_e32 v132, v105
	v_exp_f32_e32 v133, v106
	v_exp_f32_e32 v138, v107
	v_cvt_pk_bf16_f32 v101, v143, v202
	v_cvt_pk_bf16_f32 v102, v203, v204
	ds_read_b128 v[104:107], v211 offset:27648
	ds_read_b128 v[122:125], v211 offset:32256
	s_waitcnt lgkmcnt(3)
	v_mfma_f32_32x32x16_bf16 v[80:95], v[96:99], v[164:167], v[80:95]
	v_add_f32_e32 v96, v130, v117
	v_add_f32_e32 v97, v103, v134
	v_add_f32_e32 v98, v131, v96
	v_add_f32_e32 v97, v132, v97
	v_add_f32_e32 v98, v133, v98
	v_add_f32_e32 v99, v138, v97
	s_waitcnt lgkmcnt(2)
	v_mfma_f32_32x32x16_bf16 v[64:79], v[126:129], v[164:167], v[64:79]
	v_exp_f32_e32 v135, v108
	v_exp_f32_e32 v136, v109
	v_exp_f32_e32 v137, v110
	v_exp_f32_e32 v139, v111
	v_cvt_pk_bf16_f32 v103, v130, v103
	v_cvt_pk_bf16_f32 v96, v131, v132
	v_cvt_pk_bf16_f32 v97, v133, v138
	ds_read_b128 v[108:111], v211 offset:27680
	ds_read_b128 v[126:129], v211 offset:32288
	s_waitcnt lgkmcnt(3)
	v_mfma_f32_32x32x16_bf16 v[0:15], v[104:107], v[118:121], v[0:15]
	v_add_f32_e32 v104, v135, v98
	v_add_f32_e32 v99, v136, v99
	v_add_f32_e32 v117, v137, v104
	v_add_f32_e32 v130, v139, v99
	v_cvt_pk_bf16_f32 v98, v135, v136
	v_cvt_pk_bf16_f32 v99, v137, v139
	s_waitcnt lgkmcnt(2)
	v_mfma_f32_32x32x16_bf16 v[16:31], v[122:125], v[118:121], v[16:31]
	ds_read_b128 v[104:107], v211 offset:27712
	s_waitcnt lgkmcnt(2)
	v_mfma_f32_32x32x16_bf16 v[0:15], v[108:111], v[112:115], v[0:15]
	ds_read_b128 v[108:111], v211 offset:32320
	s_waitcnt lgkmcnt(2)
	v_mfma_f32_32x32x16_bf16 v[16:31], v[126:129], v[112:115], v[16:31]
	ds_read_b128 v[112:115], v211 offset:27744
	ds_read_b128 v[118:121], v211 offset:32352
	s_waitcnt lgkmcnt(3)
	v_mfma_f32_32x32x16_bf16 v[0:15], v[104:107], v[100:103], v[0:15]
	s_waitcnt lgkmcnt(2)
	v_mfma_f32_32x32x16_bf16 v[16:31], v[108:111], v[100:103], v[16:31]
	s_waitcnt lgkmcnt(1)
	v_mfma_f32_32x32x16_bf16 v[0:15], v[112:115], v[96:99], v[0:15]
	v_add_f32_e32 v221, v117, v130
	v_add_f32_e32 v116, v116, v221
	s_waitcnt lgkmcnt(0)
	v_mfma_f32_32x32x16_bf16 v[16:31], v[118:121], v[96:99], v[16:31]
	s_waitcnt vmcnt(0)
	s_add_u32 s10, s10, 0x400
	s_addc_u32 s11, s11, 0
	v_lshl_add_u64 v[200:201], v[200:201], 0, v[168:169]
	s_cmpk_lt_u32 s16, 0x78
	v_lshl_add_u64 v[196:197], v[196:197], 0, v[198:199]
	s_barrier
	s_cbranch_scc0 .LBB0_873

.LBB0_905:
	ds_read_b128 v[118:121], v181 offset:13344
	ds_read_b128 v[122:125], v181 offset:20000
	s_waitcnt lgkmcnt(3)
	v_mfma_f32_32x32x16_bf16 v[128:143], v[96:99], v[144:147], v[32:47]
	v_exp_f32_e32 v117, v80
	v_exp_f32_e32 v126, v81
	v_exp_f32_e32 v127, v82
	v_exp_f32_e32 v213, v83
	v_exp_f32_e32 v214, v84
	v_exp_f32_e32 v215, v85
	s_waitcnt lgkmcnt(2)
	v_mfma_f32_32x32x16_bf16 v[96:111], v[112:115], v[144:147], v[32:47]
	ds_read_b128 v[80:83], v181 offset:13376
	ds_read_b128 v[112:115], v181 offset:20032
	s_waitcnt lgkmcnt(3)
	v_mfma_f32_32x32x16_bf16 v[128:143], v[118:121], v[148:151], v[128:143]
	v_exp_f32_e32 v216, v86
	v_exp_f32_e32 v217, v88
	v_add_f32_e32 v88, v127, v117
	v_add_f32_e32 v86, v213, v126
	s_waitcnt lgkmcnt(2)
	v_mfma_f32_32x32x16_bf16 v[96:111], v[122:125], v[148:151], v[96:111]
	v_cvt_pk_bf16_f32 v84, v117, v126
	v_add_f32_e32 v117, v214, v88
	v_add_f32_e32 v122, v215, v86
	v_exp_f32_e32 v87, v87
	v_exp_f32_e32 v218, v89
	v_exp_f32_e32 v219, v90
	v_exp_f32_e32 v220, v91
	v_cvt_pk_bf16_f32 v85, v127, v213
	v_cvt_pk_bf16_f32 v86, v214, v215
	ds_read_b128 v[88:91], v181 offset:13408
	ds_read_b128 v[118:121], v181 offset:20064
	s_waitcnt lgkmcnt(3)
	v_mfma_f32_32x32x16_bf16 v[128:143], v[80:83], v[152:155], v[128:143]
	v_add_f32_e32 v80, v216, v117
	v_add_f32_e32 v81, v87, v122
	v_add_f32_e32 v82, v217, v80
	v_add_f32_e32 v81, v218, v81
	v_add_f32_e32 v82, v219, v82
	v_add_f32_e32 v83, v220, v81
	s_waitcnt lgkmcnt(2)
	v_mfma_f32_32x32x16_bf16 v[96:111], v[112:115], v[152:155], v[96:111]
	v_exp_f32_e32 v123, v92
	v_exp_f32_e32 v124, v93
	v_exp_f32_e32 v125, v94
	v_exp_f32_e32 v126, v95
	v_cvt_pk_bf16_f32 v87, v216, v87
	v_cvt_pk_bf16_f32 v80, v217, v218
	v_cvt_pk_bf16_f32 v81, v219, v220
	ds_read_b128 v[92:95], v181 offset:13440
	ds_read_b128 v[112:115], v181 offset:20096
	s_waitcnt lgkmcnt(3)
	v_mfma_f32_32x32x16_bf16 v[128:143], v[88:91], v[156:159], v[128:143]
	v_exp_f32_e32 v117, v64
	v_exp_f32_e32 v122, v65
	v_add_f32_e32 v64, v123, v82
	v_add_f32_e32 v65, v124, v83
	v_exp_f32_e32 v214, v68
	v_exp_f32_e32 v215, v69
	s_waitcnt lgkmcnt(2)
	v_mfma_f32_32x32x16_bf16 v[96:111], v[118:121], v[156:159], v[96:111]
	v_add_f32_e32 v68, v125, v64
	v_add_f32_e32 v69, v126, v65
	v_exp_f32_e32 v127, v66
	v_exp_f32_e32 v213, v67
	v_cvt_pk_bf16_f32 v82, v123, v124
	v_cvt_pk_bf16_f32 v83, v125, v126
	ds_read_b128 v[64:67], v181 offset:13472
	ds_read_b128 v[88:91], v181 offset:20128
	s_waitcnt lgkmcnt(3)
	v_mfma_f32_32x32x16_bf16 v[128:143], v[92:95], v[160:163], v[128:143]
	v_exp_f32_e32 v118, v70
	v_add_f32_e32 v70, v117, v68
	v_add_f32_e32 v69, v122, v69
	v_exp_f32_e32 v119, v72
	v_add_f32_e32 v70, v127, v70
	v_add_f32_e32 v72, v213, v69
	s_waitcnt lgkmcnt(2)
	v_mfma_f32_32x32x16_bf16 v[96:111], v[112:115], v[160:163], v[96:111]
	v_add_f32_e32 v112, v214, v70
	v_add_f32_e32 v113, v215, v72
	v_exp_f32_e32 v71, v71
	v_exp_f32_e32 v120, v73
	v_exp_f32_e32 v121, v74
	v_exp_f32_e32 v123, v75
	v_cvt_pk_bf16_f32 v68, v117, v122
	v_cvt_pk_bf16_f32 v69, v127, v213
	v_cvt_pk_bf16_f32 v70, v214, v215
	ds_read_b128 v[72:75], v210 offset:53248
	ds_read_b128 v[92:95], v210 offset:57856
	s_waitcnt lgkmcnt(3)
	v_mfma_f32_32x32x16_bf16 v[128:143], v[64:67], v[164:167], v[128:143]
	v_add_f32_e32 v64, v118, v112
	v_add_f32_e32 v65, v71, v113
	v_add_f32_e32 v66, v119, v64
	v_add_f32_e32 v65, v120, v65
	v_add_f32_e32 v66, v121, v66
	v_add_f32_e32 v67, v123, v65
	s_waitcnt lgkmcnt(2)
	v_mfma_f32_32x32x16_bf16 v[96:111], v[88:91], v[164:167], v[96:111]
	v_exp_f32_e32 v114, v76
	v_exp_f32_e32 v115, v77
	v_exp_f32_e32 v117, v78
	v_exp_f32_e32 v122, v79
	v_cvt_pk_bf16_f32 v71, v118, v71
	v_cvt_pk_bf16_f32 v64, v119, v120
	v_cvt_pk_bf16_f32 v65, v121, v123
	ds_read_b128 v[76:79], v210 offset:53280
	ds_read_b128 v[88:91], v210 offset:57888
	s_waitcnt lgkmcnt(3)
	v_mfma_f32_32x32x16_bf16 v[0:15], v[72:75], v[84:87], v[0:15]
	v_add_f32_e32 v72, v114, v66
	v_add_f32_e32 v67, v115, v67
	v_add_f32_e32 v112, v117, v72
	v_add_f32_e32 v113, v122, v67
	v_cvt_pk_bf16_f32 v66, v114, v115
	v_cvt_pk_bf16_f32 v67, v117, v122
	s_waitcnt lgkmcnt(2)
	v_mfma_f32_32x32x16_bf16 v[16:31], v[92:95], v[84:87], v[16:31]
	ds_read_b128 v[72:75], v210 offset:53312
	s_waitcnt lgkmcnt(2)
	v_mfma_f32_32x32x16_bf16 v[0:15], v[76:79], v[80:83], v[0:15]
	ds_read_b128 v[76:79], v210 offset:57920
	s_waitcnt lgkmcnt(2)
	v_mfma_f32_32x32x16_bf16 v[16:31], v[88:91], v[80:83], v[16:31]
	ds_read_b128 v[80:83], v210 offset:53344
	ds_read_b128 v[88:91], v210 offset:57952
	s_waitcnt lgkmcnt(3)
	v_mfma_f32_32x32x16_bf16 v[0:15], v[72:75], v[68:71], v[0:15]
	s_waitcnt lgkmcnt(2)
	v_mfma_f32_32x32x16_bf16 v[16:31], v[76:79], v[68:71], v[16:31]
	s_waitcnt lgkmcnt(1)
	v_mfma_f32_32x32x16_bf16 v[0:15], v[80:83], v[64:67], v[0:15]
	v_add_f32_e32 v221, v112, v113
	v_add_f32_e32 v86, v116, v221
	s_waitcnt lgkmcnt(0)
	v_mfma_f32_32x32x16_bf16 v[16:31], v[88:91], v[64:67], v[16:31]
	ds_read_b128 v[64:67], v181 offset:26624
	ds_read_b128 v[80:83], v181 offset:33280
	v_cmp_lt_f32_e32 vcc, s58, v221
	s_cbranch_vccz .LBB0_907
	v_mov_b32_e32 v222, v221
	v_mov_b32_e32 v223, v221
	s_nop 1
	v_permlane32_swap_b32_e32 v222, v223
	v_add_f32_e32 v222, v222, v223
	v_log_f32_e32 v222, v222
	s_nop 0
	v_max_f32_e32 v33, 0, v222
	v_exp_f32_e64 v34, -v33
	v_add_f32_e32 v212, v212, v33
	v_xor_b32_e32 v32, 0x80000000, v212
	v_sub_f32_e32 v143, v143, v33
	v_pk_mul_f32 v[14:15], v[14:15], v[34:35] op_sel_hi:[1,0]
	v_pk_mul_f32 v[12:13], v[12:13], v[34:35] op_sel_hi:[1,0]
	v_pk_mul_f32 v[10:11], v[10:11], v[34:35] op_sel_hi:[1,0]
	v_pk_mul_f32 v[8:9], v[8:9], v[34:35] op_sel_hi:[1,0]
	v_pk_mul_f32 v[6:7], v[6:7], v[34:35] op_sel_hi:[1,0]
	v_pk_mul_f32 v[4:5], v[4:5], v[34:35] op_sel_hi:[1,0]
	v_pk_mul_f32 v[2:3], v[2:3], v[34:35] op_sel_hi:[1,0]
	v_pk_mul_f32 v[0:1], v[0:1], v[34:35] op_sel_hi:[1,0]
	v_pk_mul_f32 v[30:31], v[30:31], v[34:35] op_sel_hi:[1,0]
	v_pk_mul_f32 v[28:29], v[28:29], v[34:35] op_sel_hi:[1,0]
	v_pk_mul_f32 v[26:27], v[26:27], v[34:35] op_sel_hi:[1,0]
	v_pk_mul_f32 v[24:25], v[24:25], v[34:35] op_sel_hi:[1,0]
	v_pk_mul_f32 v[22:23], v[22:23], v[34:35] op_sel_hi:[1,0]
	v_pk_mul_f32 v[20:21], v[20:21], v[34:35] op_sel_hi:[1,0]
	v_pk_mul_f32 v[18:19], v[18:19], v[34:35] op_sel_hi:[1,0]
	v_pk_mul_f32 v[16:17], v[16:17], v[34:35] op_sel_hi:[1,0]
	v_sub_f32_e32 v142, v142, v33
	v_sub_f32_e32 v141, v141, v33
	v_sub_f32_e32 v140, v140, v33
	v_sub_f32_e32 v139, v139, v33
	v_sub_f32_e32 v138, v138, v33
	v_sub_f32_e32 v137, v137, v33
	v_sub_f32_e32 v136, v136, v33
	v_sub_f32_e32 v135, v135, v33
	v_sub_f32_e32 v134, v134, v33
	v_sub_f32_e32 v133, v133, v33
	v_sub_f32_e32 v132, v132, v33
	v_sub_f32_e32 v131, v131, v33
	v_sub_f32_e32 v130, v130, v33
	v_sub_f32_e32 v129, v129, v33
	v_sub_f32_e32 v128, v128, v33
	v_sub_f32_e32 v111, v111, v33
	v_sub_f32_e32 v110, v110, v33
	v_sub_f32_e32 v109, v109, v33
	v_sub_f32_e32 v108, v108, v33
	v_sub_f32_e32 v107, v107, v33
	v_sub_f32_e32 v106, v106, v33
	v_sub_f32_e32 v105, v105, v33
	v_sub_f32_e32 v104, v104, v33
	v_sub_f32_e32 v103, v103, v33
	v_sub_f32_e32 v102, v102, v33
	v_sub_f32_e32 v101, v101, v33
	v_sub_f32_e32 v100, v100, v33
	v_sub_f32_e32 v99, v99, v33
	v_sub_f32_e32 v98, v98, v33
	v_sub_f32_e32 v97, v97, v33
	v_sub_f32_e32 v96, v96, v33
	v_mul_f32_e32 v86, v86, v34
	v_mov_b32_e32 v33, v32
	v_mov_b32_e32 v34, v32
	v_mov_b32_e32 v35, v32
	v_mov_b32_e32 v36, v32
	v_mov_b32_e32 v37, v32
	v_mov_b32_e32 v38, v32
	v_mov_b32_e32 v39, v32
	v_mov_b32_e32 v40, v32
	v_mov_b32_e32 v41, v32
	v_mov_b32_e32 v42, v32
	v_mov_b32_e32 v43, v32
	v_mov_b32_e32 v44, v32
	v_mov_b32_e32 v45, v32
	v_mov_b32_e32 v46, v32
	v_mov_b32_e32 v47, v32
	v_mov_b32_e32 v48, v32
	v_mov_b32_e32 v49, v32
	v_mov_b32_e32 v50, v32
	v_mov_b32_e32 v51, v32
	v_mov_b32_e32 v52, v32
	v_mov_b32_e32 v53, v32
	v_mov_b32_e32 v54, v32
	v_mov_b32_e32 v55, v32
	v_mov_b32_e32 v56, v32
	v_mov_b32_e32 v57, v32
	v_mov_b32_e32 v58, v32
	v_mov_b32_e32 v59, v32
	v_mov_b32_e32 v60, v32
	v_mov_b32_e32 v61, v32
	v_mov_b32_e32 v62, v32
	v_mov_b32_e32 v63, v32

.LBB0_911:
	ds_read_b128 v[88:91], v181 offset:26656
	ds_read_b128 v[92:95], v181 offset:33312
	s_waitcnt lgkmcnt(3)
	v_mfma_f32_32x32x16_bf16 v[112:127], v[64:67], v[144:147], v[32:47]
	v_exp_f32_e32 v87, v128
	v_exp_f32_e32 v213, v129
	v_exp_f32_e32 v214, v130
	v_exp_f32_e32 v215, v131
	v_exp_f32_e32 v132, v132
	v_exp_f32_e32 v133, v133
	s_waitcnt lgkmcnt(2)
	v_mfma_f32_32x32x16_bf16 v[64:79], v[80:83], v[144:147], v[32:47]
	ds_read_b128 v[80:83], v181 offset:26688
	ds_read_b128 v[128:131], v181 offset:33344
	s_waitcnt lgkmcnt(3)
	v_mfma_f32_32x32x16_bf16 v[112:127], v[88:91], v[148:151], v[112:127]
	v_cvt_pk_bf16_f32 v88, v87, v213
	v_add_f32_e32 v87, v214, v87
	v_add_f32_e32 v90, v215, v213
	v_add_f32_e32 v87, v132, v87
	s_waitcnt lgkmcnt(2)
	v_mfma_f32_32x32x16_bf16 v[64:79], v[92:95], v[148:151], v[64:79]
	v_add_f32_e32 v91, v133, v90
	v_exp_f32_e32 v216, v134
	v_exp_f32_e32 v217, v135
	v_exp_f32_e32 v136, v136
	v_exp_f32_e32 v137, v137
	v_exp_f32_e32 v138, v138
	v_exp_f32_e32 v139, v139
	v_cvt_pk_bf16_f32 v89, v214, v215
	v_cvt_pk_bf16_f32 v90, v132, v133
	ds_read_b128 v[92:95], v181 offset:26720
	ds_read_b128 v[132:135], v181 offset:33376
	s_waitcnt lgkmcnt(3)
	v_mfma_f32_32x32x16_bf16 v[112:127], v[80:83], v[152:155], v[112:127]
	v_add_f32_e32 v80, v216, v87
	v_add_f32_e32 v81, v217, v91
	v_add_f32_e32 v82, v136, v80
	v_add_f32_e32 v81, v137, v81
	v_add_f32_e32 v82, v138, v82
	v_add_f32_e32 v83, v139, v81
	s_waitcnt lgkmcnt(2)
	v_mfma_f32_32x32x16_bf16 v[64:79], v[128:131], v[152:155], v[64:79]
	v_exp_f32_e32 v140, v140
	v_exp_f32_e32 v141, v141
	v_exp_f32_e32 v142, v142
	v_exp_f32_e32 v143, v143
	v_cvt_pk_bf16_f32 v91, v216, v217
	v_cvt_pk_bf16_f32 v80, v136, v137
	v_cvt_pk_bf16_f32 v81, v138, v139
	ds_read_b128 v[128:131], v181 offset:26752
	ds_read_b128 v[136:139], v181 offset:33408
	s_waitcnt lgkmcnt(3)
	v_mfma_f32_32x32x16_bf16 v[112:127], v[92:95], v[156:159], v[112:127]
	v_exp_f32_e32 v87, v96
	v_add_f32_e32 v92, v140, v82
	v_add_f32_e32 v83, v141, v83
	v_exp_f32_e32 v216, v100
	v_exp_f32_e32 v217, v101
	v_add_f32_e32 v100, v142, v92
	s_waitcnt lgkmcnt(2)
	v_mfma_f32_32x32x16_bf16 v[64:79], v[132:135], v[156:159], v[64:79]
	v_add_f32_e32 v101, v143, v83
	v_exp_f32_e32 v213, v97
	v_exp_f32_e32 v214, v98
	v_exp_f32_e32 v215, v99
	v_cvt_pk_bf16_f32 v82, v140, v141
	v_cvt_pk_bf16_f32 v83, v142, v143
	ds_read_b128 v[92:95], v181 offset:26784
	ds_read_b128 v[96:99], v181 offset:33440
	s_waitcnt lgkmcnt(3)
	v_mfma_f32_32x32x16_bf16 v[112:127], v[128:131], v[160:163], v[112:127]
	v_exp_f32_e32 v132, v102
	v_add_f32_e32 v102, v87, v100
	v_add_f32_e32 v101, v213, v101
	v_cvt_pk_bf16_f32 v100, v87, v213
	v_add_f32_e32 v87, v214, v102
	v_add_f32_e32 v102, v215, v101
	s_waitcnt lgkmcnt(2)
	v_mfma_f32_32x32x16_bf16 v[64:79], v[136:139], v[160:163], v[64:79]
	v_add_f32_e32 v87, v216, v87
	v_add_f32_e32 v136, v217, v102
	v_exp_f32_e32 v103, v103
	v_exp_f32_e32 v133, v104
	v_exp_f32_e32 v134, v105
	v_exp_f32_e32 v135, v106
	v_exp_f32_e32 v140, v107
	v_cvt_pk_bf16_f32 v101, v214, v215
	v_cvt_pk_bf16_f32 v102, v216, v217
	ds_read_b128 v[104:107], v210 offset:62464
	ds_read_b128 v[128:131], v211 offset:13824
	s_waitcnt lgkmcnt(3)
	v_mfma_f32_32x32x16_bf16 v[112:127], v[92:95], v[164:167], v[112:127]
	v_add_f32_e32 v87, v132, v87
	v_add_f32_e32 v92, v103, v136
	v_add_f32_e32 v87, v133, v87
	v_add_f32_e32 v93, v134, v92
	v_add_f32_e32 v87, v135, v87
	v_add_f32_e32 v94, v140, v93
	s_waitcnt lgkmcnt(2)
	v_mfma_f32_32x32x16_bf16 v[64:79], v[96:99], v[164:167], v[64:79]
	v_exp_f32_e32 v137, v108
	v_exp_f32_e32 v138, v109
	v_exp_f32_e32 v139, v110
	v_exp_f32_e32 v141, v111
	v_cvt_pk_bf16_f32 v103, v132, v103
	v_cvt_pk_bf16_f32 v92, v133, v134
	v_cvt_pk_bf16_f32 v93, v135, v140
	ds_read_b128 v[96:99], v210 offset:62496
	ds_read_b128 v[108:111], v211 offset:13856
	s_waitcnt lgkmcnt(3)
	v_mfma_f32_32x32x16_bf16 v[0:15], v[104:107], v[88:91], v[0:15]
	v_add_f32_e32 v87, v137, v87
	v_add_f32_e32 v95, v138, v94
	v_add_f32_e32 v132, v139, v87
	v_add_f32_e32 v133, v141, v95
	v_cvt_pk_bf16_f32 v94, v137, v138
	v_cvt_pk_bf16_f32 v95, v139, v141
	s_waitcnt lgkmcnt(2)
	v_mfma_f32_32x32x16_bf16 v[16:31], v[128:131], v[88:91], v[16:31]
	ds_read_b128 v[88:91], v210 offset:62528
	s_waitcnt lgkmcnt(2)
	v_mfma_f32_32x32x16_bf16 v[0:15], v[96:99], v[80:83], v[0:15]
	ds_read_b128 v[96:99], v211 offset:13888
	s_waitcnt lgkmcnt(2)
	v_mfma_f32_32x32x16_bf16 v[16:31], v[108:111], v[80:83], v[16:31]
	ds_read_b128 v[80:83], v210 offset:62560
	ds_read_b128 v[104:107], v211 offset:13920
	s_waitcnt lgkmcnt(3)
	v_mfma_f32_32x32x16_bf16 v[0:15], v[88:91], v[100:103], v[0:15]
	s_waitcnt lgkmcnt(2)
	v_mfma_f32_32x32x16_bf16 v[16:31], v[96:99], v[100:103], v[16:31]
	s_waitcnt lgkmcnt(1)
	v_mfma_f32_32x32x16_bf16 v[0:15], v[80:83], v[92:95], v[0:15]
	v_add_f32_e32 v221, v132, v133
	v_add_f32_e32 v102, v86, v221
	s_waitcnt lgkmcnt(0)
	v_mfma_f32_32x32x16_bf16 v[16:31], v[104:107], v[92:95], v[16:31]
	s_waitcnt vmcnt(0)
	s_barrier
	ds_read_b128 v[80:83], v181 offset:39936
	ds_read_b128 v[96:99], v181 offset:46592
	v_cmp_lt_f32_e32 vcc, s58, v221
	s_cbranch_vccz .LBB0_913
	v_mov_b32_e32 v222, v221
	v_mov_b32_e32 v223, v221
	s_nop 1
	v_permlane32_swap_b32_e32 v222, v223
	v_add_f32_e32 v222, v222, v223
	v_log_f32_e32 v222, v222
	s_nop 0
	v_max_f32_e32 v33, 0, v222
	v_exp_f32_e64 v34, -v33
	v_add_f32_e32 v212, v212, v33
	v_xor_b32_e32 v32, 0x80000000, v212
	v_sub_f32_e32 v127, v127, v33
	v_pk_mul_f32 v[14:15], v[14:15], v[34:35] op_sel_hi:[1,0]
	v_pk_mul_f32 v[12:13], v[12:13], v[34:35] op_sel_hi:[1,0]
	v_pk_mul_f32 v[10:11], v[10:11], v[34:35] op_sel_hi:[1,0]
	v_pk_mul_f32 v[8:9], v[8:9], v[34:35] op_sel_hi:[1,0]
	v_pk_mul_f32 v[6:7], v[6:7], v[34:35] op_sel_hi:[1,0]
	v_pk_mul_f32 v[4:5], v[4:5], v[34:35] op_sel_hi:[1,0]
	v_pk_mul_f32 v[2:3], v[2:3], v[34:35] op_sel_hi:[1,0]
	v_pk_mul_f32 v[0:1], v[0:1], v[34:35] op_sel_hi:[1,0]
	v_pk_mul_f32 v[30:31], v[30:31], v[34:35] op_sel_hi:[1,0]
	v_pk_mul_f32 v[28:29], v[28:29], v[34:35] op_sel_hi:[1,0]
	v_pk_mul_f32 v[26:27], v[26:27], v[34:35] op_sel_hi:[1,0]
	v_pk_mul_f32 v[24:25], v[24:25], v[34:35] op_sel_hi:[1,0]
	v_pk_mul_f32 v[22:23], v[22:23], v[34:35] op_sel_hi:[1,0]
	v_pk_mul_f32 v[20:21], v[20:21], v[34:35] op_sel_hi:[1,0]
	v_pk_mul_f32 v[18:19], v[18:19], v[34:35] op_sel_hi:[1,0]
	v_pk_mul_f32 v[16:17], v[16:17], v[34:35] op_sel_hi:[1,0]
	v_sub_f32_e32 v126, v126, v33
	v_sub_f32_e32 v125, v125, v33
	v_sub_f32_e32 v124, v124, v33
	v_sub_f32_e32 v123, v123, v33
	v_sub_f32_e32 v122, v122, v33
	v_sub_f32_e32 v121, v121, v33
	v_sub_f32_e32 v120, v120, v33
	v_sub_f32_e32 v119, v119, v33
	v_sub_f32_e32 v118, v118, v33
	v_sub_f32_e32 v117, v117, v33
	v_sub_f32_e32 v116, v116, v33
	v_sub_f32_e32 v115, v115, v33
	v_sub_f32_e32 v114, v114, v33
	v_sub_f32_e32 v113, v113, v33
	v_sub_f32_e32 v112, v112, v33
	v_sub_f32_e32 v79, v79, v33
	v_sub_f32_e32 v78, v78, v33
	v_sub_f32_e32 v77, v77, v33
	v_sub_f32_e32 v76, v76, v33
	v_sub_f32_e32 v75, v75, v33
	v_sub_f32_e32 v74, v74, v33
	v_sub_f32_e32 v73, v73, v33
	v_sub_f32_e32 v72, v72, v33
	v_sub_f32_e32 v71, v71, v33
	v_sub_f32_e32 v70, v70, v33
	v_sub_f32_e32 v69, v69, v33
	v_sub_f32_e32 v68, v68, v33
	v_sub_f32_e32 v67, v67, v33
	v_sub_f32_e32 v66, v66, v33
	v_sub_f32_e32 v65, v65, v33
	v_sub_f32_e32 v64, v64, v33
	v_mul_f32_e32 v102, v102, v34
	v_mov_b32_e32 v33, v32
	v_mov_b32_e32 v34, v32
	v_mov_b32_e32 v35, v32
	v_mov_b32_e32 v36, v32
	v_mov_b32_e32 v37, v32
	v_mov_b32_e32 v38, v32
	v_mov_b32_e32 v39, v32
	v_mov_b32_e32 v40, v32
	v_mov_b32_e32 v41, v32
	v_mov_b32_e32 v42, v32
	v_mov_b32_e32 v43, v32
	v_mov_b32_e32 v44, v32
	v_mov_b32_e32 v45, v32
	v_mov_b32_e32 v46, v32
	v_mov_b32_e32 v47, v32
	v_mov_b32_e32 v48, v32
	v_mov_b32_e32 v49, v32
	v_mov_b32_e32 v50, v32
	v_mov_b32_e32 v51, v32
	v_mov_b32_e32 v52, v32
	v_mov_b32_e32 v53, v32
	v_mov_b32_e32 v54, v32
	v_mov_b32_e32 v55, v32
	v_mov_b32_e32 v56, v32
	v_mov_b32_e32 v57, v32
	v_mov_b32_e32 v58, v32
	v_mov_b32_e32 v59, v32
	v_mov_b32_e32 v60, v32
	v_mov_b32_e32 v61, v32
	v_mov_b32_e32 v62, v32
	v_mov_b32_e32 v63, v32

.LBB0_917:
	ds_read_b128 v[104:107], v181 offset:39968
	ds_read_b128 v[108:111], v181 offset:46624
	s_waitcnt lgkmcnt(3)
	v_mfma_f32_32x32x16_bf16 v[128:143], v[80:83], v[144:147], v[32:47]
	v_exp_f32_e32 v103, v112
	v_exp_f32_e32 v213, v113
	v_exp_f32_e32 v214, v114
	v_exp_f32_e32 v215, v115
	v_exp_f32_e32 v116, v116
	v_exp_f32_e32 v117, v117
	s_waitcnt lgkmcnt(2)
	v_mfma_f32_32x32x16_bf16 v[80:95], v[96:99], v[144:147], v[32:47]
	ds_read_b128 v[96:99], v181 offset:40000
	ds_read_b128 v[112:115], v181 offset:46656
	s_waitcnt lgkmcnt(3)
	v_mfma_f32_32x32x16_bf16 v[128:143], v[104:107], v[148:151], v[128:143]
	v_cvt_pk_bf16_f32 v104, v103, v213
	v_add_f32_e32 v103, v214, v103
	v_add_f32_e32 v106, v215, v213
	v_add_f32_e32 v103, v116, v103
	s_waitcnt lgkmcnt(2)
	v_mfma_f32_32x32x16_bf16 v[80:95], v[108:111], v[148:151], v[80:95]
	v_add_f32_e32 v107, v117, v106
	v_exp_f32_e32 v216, v118
	v_exp_f32_e32 v217, v119
	v_exp_f32_e32 v120, v120
	v_exp_f32_e32 v121, v121
	v_exp_f32_e32 v122, v122
	v_exp_f32_e32 v123, v123
	v_cvt_pk_bf16_f32 v105, v214, v215
	v_cvt_pk_bf16_f32 v106, v116, v117
	ds_read_b128 v[108:111], v181 offset:40032
	ds_read_b128 v[116:119], v181 offset:46688
	s_waitcnt lgkmcnt(3)
	v_mfma_f32_32x32x16_bf16 v[128:143], v[96:99], v[152:155], v[128:143]
	v_add_f32_e32 v96, v216, v103
	v_add_f32_e32 v97, v217, v107
	v_add_f32_e32 v98, v120, v96
	v_add_f32_e32 v97, v121, v97
	v_add_f32_e32 v98, v122, v98
	v_add_f32_e32 v99, v123, v97
	s_waitcnt lgkmcnt(2)
	v_mfma_f32_32x32x16_bf16 v[80:95], v[112:115], v[152:155], v[80:95]
	v_exp_f32_e32 v124, v124
	v_exp_f32_e32 v125, v125
	v_exp_f32_e32 v126, v126
	v_exp_f32_e32 v127, v127
	v_cvt_pk_bf16_f32 v107, v216, v217
	v_cvt_pk_bf16_f32 v96, v120, v121
	v_cvt_pk_bf16_f32 v97, v122, v123
	ds_read_b128 v[112:115], v181 offset:40064
	ds_read_b128 v[120:123], v181 offset:46720
	s_waitcnt lgkmcnt(3)
	v_mfma_f32_32x32x16_bf16 v[128:143], v[108:111], v[156:159], v[128:143]
	v_exp_f32_e32 v103, v64
	v_exp_f32_e32 v213, v65
	v_add_f32_e32 v64, v124, v98
	v_add_f32_e32 v65, v125, v99
	v_exp_f32_e32 v216, v68
	v_exp_f32_e32 v217, v69
	s_waitcnt lgkmcnt(2)
	v_mfma_f32_32x32x16_bf16 v[80:95], v[116:119], v[156:159], v[80:95]
	v_add_f32_e32 v68, v126, v64
	v_add_f32_e32 v69, v127, v65
	v_exp_f32_e32 v214, v66
	v_exp_f32_e32 v215, v67
	v_cvt_pk_bf16_f32 v98, v124, v125
	v_cvt_pk_bf16_f32 v99, v126, v127
	ds_read_b128 v[64:67], v181 offset:40096
	ds_read_b128 v[108:111], v181 offset:46752
	s_waitcnt lgkmcnt(3)
	v_mfma_f32_32x32x16_bf16 v[128:143], v[112:115], v[160:163], v[128:143]
	v_exp_f32_e32 v118, v73
	v_exp_f32_e32 v116, v70
	v_add_f32_e32 v70, v103, v68
	v_add_f32_e32 v69, v213, v69
	v_exp_f32_e32 v117, v72
	v_add_f32_e32 v70, v214, v70
	s_waitcnt lgkmcnt(2)
	v_mfma_f32_32x32x16_bf16 v[80:95], v[120:123], v[160:163], v[80:95]
	v_add_f32_e32 v72, v215, v69
	v_cvt_pk_bf16_f32 v68, v103, v213
	v_add_f32_e32 v103, v216, v70
	v_add_f32_e32 v120, v217, v72
	v_exp_f32_e32 v71, v71
	v_exp_f32_e32 v119, v74
	v_exp_f32_e32 v124, v75
	v_cvt_pk_bf16_f32 v69, v214, v215
	v_cvt_pk_bf16_f32 v70, v216, v217
	ds_read_b128 v[72:75], v211 offset:18432
	ds_read_b128 v[112:115], v211 offset:23040
	s_waitcnt lgkmcnt(3)
	v_mfma_f32_32x32x16_bf16 v[128:143], v[64:67], v[164:167], v[128:143]
	v_add_f32_e32 v64, v116, v103
	v_add_f32_e32 v65, v71, v120
	v_add_f32_e32 v66, v117, v64
	v_add_f32_e32 v65, v118, v65
	v_add_f32_e32 v66, v119, v66
	v_add_f32_e32 v67, v124, v65
	s_waitcnt lgkmcnt(2)
	v_mfma_f32_32x32x16_bf16 v[80:95], v[108:111], v[164:167], v[80:95]
	v_exp_f32_e32 v121, v76
	v_exp_f32_e32 v122, v77
	v_exp_f32_e32 v123, v78
	v_exp_f32_e32 v125, v79
	v_cvt_pk_bf16_f32 v71, v116, v71
	v_cvt_pk_bf16_f32 v64, v117, v118
	v_cvt_pk_bf16_f32 v65, v119, v124
	ds_read_b128 v[76:79], v211 offset:18464
	ds_read_b128 v[108:111], v211 offset:23072
	s_waitcnt lgkmcnt(3)
	v_mfma_f32_32x32x16_bf16 v[0:15], v[72:75], v[104:107], v[0:15]
	v_add_f32_e32 v72, v121, v66
	v_add_f32_e32 v67, v122, v67
	v_add_f32_e32 v103, v123, v72
	v_add_f32_e32 v116, v125, v67
	v_cvt_pk_bf16_f32 v66, v121, v122
	v_cvt_pk_bf16_f32 v67, v123, v125
	s_waitcnt lgkmcnt(2)
	v_mfma_f32_32x32x16_bf16 v[16:31], v[112:115], v[104:107], v[16:31]
	ds_read_b128 v[72:75], v211 offset:18496
	s_waitcnt lgkmcnt(2)
	v_mfma_f32_32x32x16_bf16 v[0:15], v[76:79], v[96:99], v[0:15]
	ds_read_b128 v[76:79], v211 offset:23104
	s_waitcnt lgkmcnt(2)
	v_mfma_f32_32x32x16_bf16 v[16:31], v[108:111], v[96:99], v[16:31]
	ds_read_b128 v[96:99], v211 offset:18528
	ds_read_b128 v[104:107], v211 offset:23136
	s_waitcnt lgkmcnt(3)
	v_mfma_f32_32x32x16_bf16 v[0:15], v[72:75], v[68:71], v[0:15]
	s_waitcnt lgkmcnt(2)
	v_mfma_f32_32x32x16_bf16 v[16:31], v[76:79], v[68:71], v[16:31]
	s_waitcnt lgkmcnt(1)
	v_mfma_f32_32x32x16_bf16 v[0:15], v[96:99], v[64:67], v[0:15]
	v_add_f32_e32 v221, v103, v116
	v_add_f32_e32 v118, v102, v221
	s_waitcnt lgkmcnt(0)
	v_mfma_f32_32x32x16_bf16 v[16:31], v[104:107], v[64:67], v[16:31]
	ds_read_b128 v[64:67], v181
	ds_read_b128 v[112:115], v181 offset:6656
	v_cmp_lt_f32_e32 vcc, s58, v221
	s_cbranch_vccz .LBB0_919
	v_mov_b32_e32 v222, v221
	v_mov_b32_e32 v223, v221
	s_nop 1
	v_permlane32_swap_b32_e32 v222, v223
	v_add_f32_e32 v222, v222, v223
	v_log_f32_e32 v222, v222
	s_nop 0
	v_max_f32_e32 v33, 0, v222
	v_exp_f32_e64 v34, -v33
	v_add_f32_e32 v212, v212, v33
	v_xor_b32_e32 v32, 0x80000000, v212
	v_sub_f32_e32 v143, v143, v33
	v_pk_mul_f32 v[14:15], v[14:15], v[34:35] op_sel_hi:[1,0]
	v_pk_mul_f32 v[12:13], v[12:13], v[34:35] op_sel_hi:[1,0]
	v_pk_mul_f32 v[10:11], v[10:11], v[34:35] op_sel_hi:[1,0]
	v_pk_mul_f32 v[8:9], v[8:9], v[34:35] op_sel_hi:[1,0]
	v_pk_mul_f32 v[6:7], v[6:7], v[34:35] op_sel_hi:[1,0]
	v_pk_mul_f32 v[4:5], v[4:5], v[34:35] op_sel_hi:[1,0]
	v_pk_mul_f32 v[2:3], v[2:3], v[34:35] op_sel_hi:[1,0]
	v_pk_mul_f32 v[0:1], v[0:1], v[34:35] op_sel_hi:[1,0]
	v_pk_mul_f32 v[30:31], v[30:31], v[34:35] op_sel_hi:[1,0]
	v_pk_mul_f32 v[28:29], v[28:29], v[34:35] op_sel_hi:[1,0]
	v_pk_mul_f32 v[26:27], v[26:27], v[34:35] op_sel_hi:[1,0]
	v_pk_mul_f32 v[24:25], v[24:25], v[34:35] op_sel_hi:[1,0]
	v_pk_mul_f32 v[22:23], v[22:23], v[34:35] op_sel_hi:[1,0]
	v_pk_mul_f32 v[20:21], v[20:21], v[34:35] op_sel_hi:[1,0]
	v_pk_mul_f32 v[18:19], v[18:19], v[34:35] op_sel_hi:[1,0]
	v_pk_mul_f32 v[16:17], v[16:17], v[34:35] op_sel_hi:[1,0]
	v_sub_f32_e32 v142, v142, v33
	v_sub_f32_e32 v141, v141, v33
	v_sub_f32_e32 v140, v140, v33
	v_sub_f32_e32 v139, v139, v33
	v_sub_f32_e32 v138, v138, v33
	v_sub_f32_e32 v137, v137, v33
	v_sub_f32_e32 v136, v136, v33
	v_sub_f32_e32 v135, v135, v33
	v_sub_f32_e32 v134, v134, v33
	v_sub_f32_e32 v133, v133, v33
	v_sub_f32_e32 v132, v132, v33
	v_sub_f32_e32 v131, v131, v33
	v_sub_f32_e32 v130, v130, v33
	v_sub_f32_e32 v129, v129, v33
	v_sub_f32_e32 v128, v128, v33
	v_sub_f32_e32 v95, v95, v33
	v_sub_f32_e32 v94, v94, v33
	v_sub_f32_e32 v93, v93, v33
	v_sub_f32_e32 v92, v92, v33
	v_sub_f32_e32 v91, v91, v33
	v_sub_f32_e32 v90, v90, v33
	v_sub_f32_e32 v89, v89, v33
	v_sub_f32_e32 v88, v88, v33
	v_sub_f32_e32 v87, v87, v33
	v_sub_f32_e32 v86, v86, v33
	v_sub_f32_e32 v85, v85, v33
	v_sub_f32_e32 v84, v84, v33
	v_sub_f32_e32 v83, v83, v33
	v_sub_f32_e32 v82, v82, v33
	v_sub_f32_e32 v81, v81, v33
	v_sub_f32_e32 v80, v80, v33
	v_mul_f32_e32 v118, v118, v34
	v_mov_b32_e32 v33, v32
	v_mov_b32_e32 v34, v32
	v_mov_b32_e32 v35, v32
	v_mov_b32_e32 v36, v32
	v_mov_b32_e32 v37, v32
	v_mov_b32_e32 v38, v32
	v_mov_b32_e32 v39, v32
	v_mov_b32_e32 v40, v32
	v_mov_b32_e32 v41, v32
	v_mov_b32_e32 v42, v32
	v_mov_b32_e32 v43, v32
	v_mov_b32_e32 v44, v32
	v_mov_b32_e32 v45, v32
	v_mov_b32_e32 v46, v32
	v_mov_b32_e32 v47, v32
	v_mov_b32_e32 v48, v32
	v_mov_b32_e32 v49, v32
	v_mov_b32_e32 v50, v32
	v_mov_b32_e32 v51, v32
	v_mov_b32_e32 v52, v32
	v_mov_b32_e32 v53, v32
	v_mov_b32_e32 v54, v32
	v_mov_b32_e32 v55, v32
	v_mov_b32_e32 v56, v32
	v_mov_b32_e32 v57, v32
	v_mov_b32_e32 v58, v32
	v_mov_b32_e32 v59, v32
	v_mov_b32_e32 v60, v32
	v_mov_b32_e32 v61, v32
	v_mov_b32_e32 v62, v32
	v_mov_b32_e32 v63, v32

.LBB0_923:
	ds_read_b128 v[120:123], v181 offset:32
	ds_read_b128 v[124:127], v181 offset:6688
	s_waitcnt lgkmcnt(3)
	v_mfma_f32_32x32x16_bf16 v[96:111], v[64:67], v[144:147], v[32:47]
	v_exp_f32_e32 v119, v128
	v_exp_f32_e32 v213, v129
	v_exp_f32_e32 v214, v130
	v_exp_f32_e32 v215, v131
	v_exp_f32_e32 v132, v132
	v_exp_f32_e32 v133, v133
	s_waitcnt lgkmcnt(2)
	v_mfma_f32_32x32x16_bf16 v[64:79], v[112:115], v[144:147], v[32:47]
	ds_read_b128 v[112:115], v181 offset:64
	ds_read_b128 v[128:131], v181 offset:6720
	s_waitcnt lgkmcnt(3)
	v_mfma_f32_32x32x16_bf16 v[96:111], v[120:123], v[148:151], v[96:111]
	v_cvt_pk_bf16_f32 v120, v119, v213
	v_add_f32_e32 v119, v214, v119
	v_add_f32_e32 v122, v215, v213
	v_add_f32_e32 v119, v132, v119
	s_waitcnt lgkmcnt(2)
	v_mfma_f32_32x32x16_bf16 v[64:79], v[124:127], v[148:151], v[64:79]
	v_add_f32_e32 v123, v133, v122
	v_exp_f32_e32 v216, v134
	v_exp_f32_e32 v217, v135
	v_exp_f32_e32 v136, v136
	v_exp_f32_e32 v137, v137
	v_exp_f32_e32 v138, v138
	v_exp_f32_e32 v139, v139
	v_cvt_pk_bf16_f32 v121, v214, v215
	v_cvt_pk_bf16_f32 v122, v132, v133
	ds_read_b128 v[124:127], v181 offset:96
	ds_read_b128 v[132:135], v181 offset:6752
	s_waitcnt lgkmcnt(3)
	v_mfma_f32_32x32x16_bf16 v[96:111], v[112:115], v[152:155], v[96:111]
	v_add_f32_e32 v112, v216, v119
	v_add_f32_e32 v113, v217, v123
	v_add_f32_e32 v114, v136, v112
	v_add_f32_e32 v113, v137, v113
	v_add_f32_e32 v114, v138, v114
	v_add_f32_e32 v115, v139, v113
	s_waitcnt lgkmcnt(2)
	v_mfma_f32_32x32x16_bf16 v[64:79], v[128:131], v[152:155], v[64:79]
	v_exp_f32_e32 v140, v140
	v_exp_f32_e32 v141, v141
	v_exp_f32_e32 v142, v142
	v_exp_f32_e32 v143, v143
	v_cvt_pk_bf16_f32 v123, v216, v217
	v_cvt_pk_bf16_f32 v112, v136, v137
	v_cvt_pk_bf16_f32 v113, v138, v139
	ds_read_b128 v[128:131], v181 offset:128
	ds_read_b128 v[136:139], v181 offset:6784
	s_waitcnt lgkmcnt(3)
	v_mfma_f32_32x32x16_bf16 v[96:111], v[124:127], v[156:159], v[96:111]
	v_exp_f32_e32 v119, v80
	v_exp_f32_e32 v213, v81
	v_add_f32_e32 v80, v140, v114
	v_add_f32_e32 v81, v141, v115
	v_exp_f32_e32 v216, v84
	v_exp_f32_e32 v217, v85
	s_waitcnt lgkmcnt(2)
	v_mfma_f32_32x32x16_bf16 v[64:79], v[132:135], v[156:159], v[64:79]
	v_add_f32_e32 v84, v142, v80
	v_add_f32_e32 v85, v143, v81
	v_exp_f32_e32 v214, v82
	v_exp_f32_e32 v215, v83
	v_cvt_pk_bf16_f32 v114, v140, v141
	v_cvt_pk_bf16_f32 v115, v142, v143
	ds_read_b128 v[80:83], v181 offset:160
	ds_read_b128 v[124:127], v181 offset:6816
	s_waitcnt lgkmcnt(3)
	v_mfma_f32_32x32x16_bf16 v[96:111], v[128:131], v[160:163], v[96:111]
	v_exp_f32_e32 v132, v86
	v_add_f32_e32 v86, v119, v84
	v_add_f32_e32 v85, v213, v85
	v_exp_f32_e32 v133, v88
	v_add_f32_e32 v86, v214, v86
	v_add_f32_e32 v88, v215, v85
	s_waitcnt lgkmcnt(2)
	v_mfma_f32_32x32x16_bf16 v[64:79], v[136:139], v[160:163], v[64:79]
	v_cvt_pk_bf16_f32 v84, v119, v213
	v_add_f32_e32 v119, v216, v86
	v_add_f32_e32 v136, v217, v88
	v_exp_f32_e32 v87, v87
	v_exp_f32_e32 v134, v89
	v_exp_f32_e32 v135, v90
	v_exp_f32_e32 v140, v91
	v_cvt_pk_bf16_f32 v85, v214, v215
	v_cvt_pk_bf16_f32 v86, v216, v217
	ds_read_b128 v[88:91], v211 offset:27648
	ds_read_b128 v[128:131], v211 offset:32256
	s_waitcnt lgkmcnt(3)
	v_mfma_f32_32x32x16_bf16 v[96:111], v[80:83], v[164:167], v[96:111]
	v_add_f32_e32 v80, v132, v119
	v_add_f32_e32 v81, v87, v136
	v_add_f32_e32 v82, v133, v80
	v_add_f32_e32 v81, v134, v81
	v_add_f32_e32 v82, v135, v82
	v_add_f32_e32 v83, v140, v81
	s_waitcnt lgkmcnt(2)
	v_mfma_f32_32x32x16_bf16 v[64:79], v[124:127], v[164:167], v[64:79]
	v_exp_f32_e32 v137, v92
	v_exp_f32_e32 v138, v93
	v_exp_f32_e32 v139, v94
	v_exp_f32_e32 v141, v95
	v_cvt_pk_bf16_f32 v87, v132, v87
	v_cvt_pk_bf16_f32 v80, v133, v134
	v_cvt_pk_bf16_f32 v81, v135, v140
	ds_read_b128 v[92:95], v211 offset:27680
	ds_read_b128 v[124:127], v211 offset:32288
	s_waitcnt lgkmcnt(3)
	v_mfma_f32_32x32x16_bf16 v[0:15], v[88:91], v[120:123], v[0:15]
	v_add_f32_e32 v88, v137, v82
	v_add_f32_e32 v83, v138, v83
	v_add_f32_e32 v119, v139, v88
	v_add_f32_e32 v132, v141, v83
	v_cvt_pk_bf16_f32 v82, v137, v138
	v_cvt_pk_bf16_f32 v83, v139, v141
	s_waitcnt lgkmcnt(2)
	v_mfma_f32_32x32x16_bf16 v[16:31], v[128:131], v[120:123], v[16:31]
	ds_read_b128 v[88:91], v211 offset:27712
	s_waitcnt lgkmcnt(2)
	v_mfma_f32_32x32x16_bf16 v[0:15], v[92:95], v[112:115], v[0:15]
	ds_read_b128 v[92:95], v211 offset:32320
	s_waitcnt lgkmcnt(2)
	v_mfma_f32_32x32x16_bf16 v[16:31], v[124:127], v[112:115], v[16:31]
	ds_read_b128 v[112:115], v211 offset:27744
	ds_read_b128 v[120:123], v211 offset:32352
	s_waitcnt lgkmcnt(3)
	v_mfma_f32_32x32x16_bf16 v[0:15], v[88:91], v[84:87], v[0:15]
	s_waitcnt lgkmcnt(2)
	v_mfma_f32_32x32x16_bf16 v[16:31], v[92:95], v[84:87], v[16:31]
	s_waitcnt lgkmcnt(1)
	v_mfma_f32_32x32x16_bf16 v[0:15], v[112:115], v[80:83], v[0:15]
	v_add_f32_e32 v221, v119, v132
	v_add_f32_e32 v118, v118, v221
	s_waitcnt lgkmcnt(0)
	v_mfma_f32_32x32x16_bf16 v[16:31], v[120:123], v[80:83], v[16:31]
	s_waitcnt vmcnt(0)
	s_barrier
	ds_read_b128 v[80:83], v181 offset:13312
	ds_read_b128 v[112:115], v181 offset:19968
	v_cmp_lt_f32_e32 vcc, s58, v221
	s_cbranch_vccz .LBB0_925
	v_mov_b32_e32 v222, v221
	v_mov_b32_e32 v223, v221
	s_nop 1
	v_permlane32_swap_b32_e32 v222, v223
	v_add_f32_e32 v222, v222, v223
	v_log_f32_e32 v222, v222
	s_nop 0
	v_max_f32_e32 v33, 0, v222
	v_exp_f32_e64 v34, -v33
	v_add_f32_e32 v212, v212, v33
	v_xor_b32_e32 v32, 0x80000000, v212
	v_sub_f32_e32 v111, v111, v33
	v_pk_mul_f32 v[14:15], v[14:15], v[34:35] op_sel_hi:[1,0]
	v_pk_mul_f32 v[12:13], v[12:13], v[34:35] op_sel_hi:[1,0]
	v_pk_mul_f32 v[10:11], v[10:11], v[34:35] op_sel_hi:[1,0]
	v_pk_mul_f32 v[8:9], v[8:9], v[34:35] op_sel_hi:[1,0]
	v_pk_mul_f32 v[6:7], v[6:7], v[34:35] op_sel_hi:[1,0]
	v_pk_mul_f32 v[4:5], v[4:5], v[34:35] op_sel_hi:[1,0]
	v_pk_mul_f32 v[2:3], v[2:3], v[34:35] op_sel_hi:[1,0]
	v_pk_mul_f32 v[0:1], v[0:1], v[34:35] op_sel_hi:[1,0]
	v_pk_mul_f32 v[30:31], v[30:31], v[34:35] op_sel_hi:[1,0]
	v_pk_mul_f32 v[28:29], v[28:29], v[34:35] op_sel_hi:[1,0]
	v_pk_mul_f32 v[26:27], v[26:27], v[34:35] op_sel_hi:[1,0]
	v_pk_mul_f32 v[24:25], v[24:25], v[34:35] op_sel_hi:[1,0]
	v_pk_mul_f32 v[22:23], v[22:23], v[34:35] op_sel_hi:[1,0]
	v_pk_mul_f32 v[20:21], v[20:21], v[34:35] op_sel_hi:[1,0]
	v_pk_mul_f32 v[18:19], v[18:19], v[34:35] op_sel_hi:[1,0]
	v_pk_mul_f32 v[16:17], v[16:17], v[34:35] op_sel_hi:[1,0]
	v_sub_f32_e32 v110, v110, v33
	v_sub_f32_e32 v109, v109, v33
	v_sub_f32_e32 v108, v108, v33
	v_sub_f32_e32 v107, v107, v33
	v_sub_f32_e32 v106, v106, v33
	v_sub_f32_e32 v105, v105, v33
	v_sub_f32_e32 v104, v104, v33
	v_sub_f32_e32 v103, v103, v33
	v_sub_f32_e32 v102, v102, v33
	v_sub_f32_e32 v101, v101, v33
	v_sub_f32_e32 v100, v100, v33
	v_sub_f32_e32 v99, v99, v33
	v_sub_f32_e32 v98, v98, v33
	v_sub_f32_e32 v97, v97, v33
	v_sub_f32_e32 v96, v96, v33
	v_sub_f32_e32 v79, v79, v33
	v_sub_f32_e32 v78, v78, v33
	v_sub_f32_e32 v77, v77, v33
	v_sub_f32_e32 v76, v76, v33
	v_sub_f32_e32 v75, v75, v33
	v_sub_f32_e32 v74, v74, v33
	v_sub_f32_e32 v73, v73, v33
	v_sub_f32_e32 v72, v72, v33
	v_sub_f32_e32 v71, v71, v33
	v_sub_f32_e32 v70, v70, v33
	v_sub_f32_e32 v69, v69, v33
	v_sub_f32_e32 v68, v68, v33
	v_sub_f32_e32 v67, v67, v33
	v_sub_f32_e32 v66, v66, v33
	v_sub_f32_e32 v65, v65, v33
	v_sub_f32_e32 v64, v64, v33
	v_mul_f32_e32 v118, v118, v34
	v_mov_b32_e32 v33, v32
	v_mov_b32_e32 v34, v32
	v_mov_b32_e32 v35, v32
	v_mov_b32_e32 v36, v32
	v_mov_b32_e32 v37, v32
	v_mov_b32_e32 v38, v32
	v_mov_b32_e32 v39, v32
	v_mov_b32_e32 v40, v32
	v_mov_b32_e32 v41, v32
	v_mov_b32_e32 v42, v32
	v_mov_b32_e32 v43, v32
	v_mov_b32_e32 v44, v32
	v_mov_b32_e32 v45, v32
	v_mov_b32_e32 v46, v32
	v_mov_b32_e32 v47, v32
	v_mov_b32_e32 v48, v32
	v_mov_b32_e32 v49, v32
	v_mov_b32_e32 v50, v32
	v_mov_b32_e32 v51, v32
	v_mov_b32_e32 v52, v32
	v_mov_b32_e32 v53, v32
	v_mov_b32_e32 v54, v32
	v_mov_b32_e32 v55, v32
	v_mov_b32_e32 v56, v32
	v_mov_b32_e32 v57, v32
	v_mov_b32_e32 v58, v32
	v_mov_b32_e32 v59, v32
	v_mov_b32_e32 v60, v32
	v_mov_b32_e32 v61, v32
	v_mov_b32_e32 v62, v32
	v_mov_b32_e32 v63, v32

.LBB0_929:
	ds_read_b128 v[138:141], v181 offset:13344
	ds_read_b128 v[214:217], v181 offset:20000
	s_waitcnt lgkmcnt(3)
	v_mfma_f32_32x32x16_bf16 v[122:137], v[80:83], v[144:147], v[32:47]
	v_exp_f32_e32 v116, v96
	v_exp_f32_e32 v117, v97
	v_exp_f32_e32 v119, v98
	v_exp_f32_e32 v120, v99
	v_exp_f32_e32 v121, v100
	v_exp_f32_e32 v142, v101
	s_waitcnt lgkmcnt(2)
	v_mfma_f32_32x32x16_bf16 v[80:95], v[112:115], v[144:147], v[32:47]
	ds_read_b128 v[96:99], v181 offset:13376
	ds_read_b128 v[112:115], v181 offset:20032
	s_waitcnt lgkmcnt(3)
	v_mfma_f32_32x32x16_bf16 v[122:137], v[138:141], v[148:151], v[122:137]
	v_exp_f32_e32 v143, v102
	v_exp_f32_e32 v213, v104
	v_add_f32_e32 v104, v119, v116
	v_add_f32_e32 v102, v120, v117
	s_waitcnt lgkmcnt(2)
	v_mfma_f32_32x32x16_bf16 v[80:95], v[214:217], v[148:151], v[80:95]
	v_cvt_pk_bf16_f32 v100, v116, v117
	v_add_f32_e32 v116, v121, v104
	v_add_f32_e32 v117, v142, v102
	v_exp_f32_e32 v103, v103
	v_exp_f32_e32 v218, v105
	v_exp_f32_e32 v219, v106
	v_exp_f32_e32 v220, v107
	v_cvt_pk_bf16_f32 v101, v119, v120
	v_cvt_pk_bf16_f32 v102, v121, v142
	ds_read_b128 v[104:107], v181 offset:13408
	ds_read_b128 v[138:141], v181 offset:20064
	s_waitcnt lgkmcnt(3)
	v_mfma_f32_32x32x16_bf16 v[122:137], v[96:99], v[152:155], v[122:137]
	v_add_f32_e32 v96, v143, v116
	v_add_f32_e32 v97, v103, v117
	v_add_f32_e32 v98, v213, v96
	v_add_f32_e32 v97, v218, v97
	v_add_f32_e32 v98, v219, v98
	v_add_f32_e32 v99, v220, v97
	s_waitcnt lgkmcnt(2)
	v_mfma_f32_32x32x16_bf16 v[80:95], v[112:115], v[152:155], v[80:95]
	v_exp_f32_e32 v119, v108
	v_exp_f32_e32 v120, v109
	v_exp_f32_e32 v121, v110
	v_exp_f32_e32 v142, v111
	v_cvt_pk_bf16_f32 v103, v143, v103
	v_cvt_pk_bf16_f32 v96, v213, v218
	v_cvt_pk_bf16_f32 v97, v219, v220
	ds_read_b128 v[108:111], v181 offset:13440
	ds_read_b128 v[112:115], v181 offset:20096
	s_waitcnt lgkmcnt(3)
	v_mfma_f32_32x32x16_bf16 v[122:137], v[104:107], v[156:159], v[122:137]
	v_exp_f32_e32 v116, v64
	v_exp_f32_e32 v117, v65
	v_add_f32_e32 v64, v119, v98
	v_add_f32_e32 v65, v120, v99
	v_exp_f32_e32 v214, v68
	v_exp_f32_e32 v215, v69
	s_waitcnt lgkmcnt(2)
	v_mfma_f32_32x32x16_bf16 v[80:95], v[138:141], v[156:159], v[80:95]
	v_add_f32_e32 v68, v121, v64
	v_add_f32_e32 v69, v142, v65
	v_exp_f32_e32 v143, v66
	v_exp_f32_e32 v213, v67
	v_cvt_pk_bf16_f32 v98, v119, v120
	v_cvt_pk_bf16_f32 v99, v121, v142
	ds_read_b128 v[64:67], v181 offset:13472
	ds_read_b128 v[104:107], v181 offset:20128
	s_waitcnt lgkmcnt(3)
	v_mfma_f32_32x32x16_bf16 v[122:137], v[108:111], v[160:163], v[122:137]
	v_exp_f32_e32 v119, v70
	v_add_f32_e32 v70, v116, v68
	v_add_f32_e32 v69, v117, v69
	v_exp_f32_e32 v120, v72
	v_add_f32_e32 v70, v143, v70
	v_add_f32_e32 v72, v213, v69
	s_waitcnt lgkmcnt(2)
	v_mfma_f32_32x32x16_bf16 v[80:95], v[112:115], v[160:163], v[80:95]
	v_add_f32_e32 v112, v214, v70
	v_add_f32_e32 v113, v215, v72
	v_exp_f32_e32 v71, v71
	v_exp_f32_e32 v121, v73
	v_exp_f32_e32 v138, v74
	v_exp_f32_e32 v139, v75
	v_cvt_pk_bf16_f32 v68, v116, v117
	v_cvt_pk_bf16_f32 v69, v143, v213
	v_cvt_pk_bf16_f32 v70, v214, v215
	ds_read_b128 v[72:75], v210 offset:53248
	ds_read_b128 v[108:111], v210 offset:57856
	s_waitcnt lgkmcnt(3)
	v_mfma_f32_32x32x16_bf16 v[122:137], v[64:67], v[164:167], v[122:137]
	v_add_f32_e32 v64, v119, v112
	v_add_f32_e32 v65, v71, v113
	v_add_f32_e32 v66, v120, v64
	v_add_f32_e32 v65, v121, v65
	v_add_f32_e32 v66, v138, v66
	v_add_f32_e32 v67, v139, v65
	s_waitcnt lgkmcnt(2)
	v_mfma_f32_32x32x16_bf16 v[80:95], v[104:107], v[164:167], v[80:95]
	v_exp_f32_e32 v114, v76
	v_exp_f32_e32 v115, v77
	v_exp_f32_e32 v116, v78
	v_exp_f32_e32 v117, v79
	v_cvt_pk_bf16_f32 v71, v119, v71
	v_cvt_pk_bf16_f32 v64, v120, v121
	v_cvt_pk_bf16_f32 v65, v138, v139
	ds_read_b128 v[76:79], v210 offset:53280
	ds_read_b128 v[104:107], v210 offset:57888
	s_waitcnt lgkmcnt(3)
	v_mfma_f32_32x32x16_bf16 v[0:15], v[72:75], v[100:103], v[0:15]
	v_add_f32_e32 v72, v114, v66
	v_add_f32_e32 v67, v115, v67
	v_add_f32_e32 v112, v116, v72
	v_add_f32_e32 v113, v117, v67
	v_cvt_pk_bf16_f32 v66, v114, v115
	v_cvt_pk_bf16_f32 v67, v116, v117
	s_waitcnt lgkmcnt(2)
	v_mfma_f32_32x32x16_bf16 v[16:31], v[108:111], v[100:103], v[16:31]
	ds_read_b128 v[72:75], v210 offset:53312
	s_waitcnt lgkmcnt(2)
	v_mfma_f32_32x32x16_bf16 v[0:15], v[76:79], v[96:99], v[0:15]
	ds_read_b128 v[76:79], v210 offset:57920
	s_waitcnt lgkmcnt(2)
	v_mfma_f32_32x32x16_bf16 v[16:31], v[104:107], v[96:99], v[16:31]
	ds_read_b128 v[96:99], v210 offset:53344
	ds_read_b128 v[102:105], v210 offset:57952
	s_waitcnt lgkmcnt(3)
	v_mfma_f32_32x32x16_bf16 v[0:15], v[72:75], v[68:71], v[0:15]
	s_waitcnt lgkmcnt(2)
	v_mfma_f32_32x32x16_bf16 v[16:31], v[76:79], v[68:71], v[16:31]
	s_waitcnt lgkmcnt(1)
	v_mfma_f32_32x32x16_bf16 v[0:15], v[96:99], v[64:67], v[0:15]
	v_add_f32_e32 v221, v112, v113
	v_add_f32_e32 v100, v118, v221
	s_waitcnt lgkmcnt(0)
	v_mfma_f32_32x32x16_bf16 v[16:31], v[102:105], v[64:67], v[16:31]
	ds_read_b128 v[64:67], v181 offset:26624
	ds_read_b128 v[96:99], v181 offset:33280
	v_cmp_lt_f32_e32 vcc, s58, v221
	s_cbranch_vccz .LBB0_931
	v_mov_b32_e32 v222, v221
	v_mov_b32_e32 v223, v221
	s_nop 1
	v_permlane32_swap_b32_e32 v222, v223
	v_add_f32_e32 v222, v222, v223
	v_log_f32_e32 v222, v222
	s_nop 0
	v_max_f32_e32 v33, 0, v222
	v_exp_f32_e64 v34, -v33
	v_add_f32_e32 v212, v212, v33
	v_xor_b32_e32 v32, 0x80000000, v212
	v_sub_f32_e32 v137, v137, v33
	v_pk_mul_f32 v[14:15], v[14:15], v[34:35] op_sel_hi:[1,0]
	v_pk_mul_f32 v[12:13], v[12:13], v[34:35] op_sel_hi:[1,0]
	v_pk_mul_f32 v[10:11], v[10:11], v[34:35] op_sel_hi:[1,0]
	v_pk_mul_f32 v[8:9], v[8:9], v[34:35] op_sel_hi:[1,0]
	v_pk_mul_f32 v[6:7], v[6:7], v[34:35] op_sel_hi:[1,0]
	v_pk_mul_f32 v[4:5], v[4:5], v[34:35] op_sel_hi:[1,0]
	v_pk_mul_f32 v[2:3], v[2:3], v[34:35] op_sel_hi:[1,0]
	v_pk_mul_f32 v[0:1], v[0:1], v[34:35] op_sel_hi:[1,0]
	v_pk_mul_f32 v[30:31], v[30:31], v[34:35] op_sel_hi:[1,0]
	v_pk_mul_f32 v[28:29], v[28:29], v[34:35] op_sel_hi:[1,0]
	v_pk_mul_f32 v[26:27], v[26:27], v[34:35] op_sel_hi:[1,0]
	v_pk_mul_f32 v[24:25], v[24:25], v[34:35] op_sel_hi:[1,0]
	v_pk_mul_f32 v[22:23], v[22:23], v[34:35] op_sel_hi:[1,0]
	v_pk_mul_f32 v[20:21], v[20:21], v[34:35] op_sel_hi:[1,0]
	v_pk_mul_f32 v[18:19], v[18:19], v[34:35] op_sel_hi:[1,0]
	v_pk_mul_f32 v[16:17], v[16:17], v[34:35] op_sel_hi:[1,0]
	v_sub_f32_e32 v136, v136, v33
	v_sub_f32_e32 v135, v135, v33
	v_sub_f32_e32 v134, v134, v33
	v_sub_f32_e32 v133, v133, v33
	v_sub_f32_e32 v132, v132, v33
	v_sub_f32_e32 v131, v131, v33
	v_sub_f32_e32 v130, v130, v33
	v_sub_f32_e32 v129, v129, v33
	v_sub_f32_e32 v128, v128, v33
	v_sub_f32_e32 v127, v127, v33
	v_sub_f32_e32 v126, v126, v33
	v_sub_f32_e32 v125, v125, v33
	v_sub_f32_e32 v124, v124, v33
	v_sub_f32_e32 v123, v123, v33
	v_sub_f32_e32 v122, v122, v33
	v_sub_f32_e32 v95, v95, v33
	v_sub_f32_e32 v94, v94, v33
	v_sub_f32_e32 v93, v93, v33
	v_sub_f32_e32 v92, v92, v33
	v_sub_f32_e32 v91, v91, v33
	v_sub_f32_e32 v90, v90, v33
	v_sub_f32_e32 v89, v89, v33
	v_sub_f32_e32 v88, v88, v33
	v_sub_f32_e32 v87, v87, v33
	v_sub_f32_e32 v86, v86, v33
	v_sub_f32_e32 v85, v85, v33
	v_sub_f32_e32 v84, v84, v33
	v_sub_f32_e32 v83, v83, v33
	v_sub_f32_e32 v82, v82, v33
	v_sub_f32_e32 v81, v81, v33
	v_sub_f32_e32 v80, v80, v33
	v_mul_f32_e32 v100, v100, v34
	v_mov_b32_e32 v33, v32
	v_mov_b32_e32 v34, v32
	v_mov_b32_e32 v35, v32
	v_mov_b32_e32 v36, v32
	v_mov_b32_e32 v37, v32
	v_mov_b32_e32 v38, v32
	v_mov_b32_e32 v39, v32
	v_mov_b32_e32 v40, v32
	v_mov_b32_e32 v41, v32
	v_mov_b32_e32 v42, v32
	v_mov_b32_e32 v43, v32
	v_mov_b32_e32 v44, v32
	v_mov_b32_e32 v45, v32
	v_mov_b32_e32 v46, v32
	v_mov_b32_e32 v47, v32
	v_mov_b32_e32 v48, v32
	v_mov_b32_e32 v49, v32
	v_mov_b32_e32 v50, v32
	v_mov_b32_e32 v51, v32
	v_mov_b32_e32 v52, v32
	v_mov_b32_e32 v53, v32
	v_mov_b32_e32 v54, v32
	v_mov_b32_e32 v55, v32
	v_mov_b32_e32 v56, v32
	v_mov_b32_e32 v57, v32
	v_mov_b32_e32 v58, v32
	v_mov_b32_e32 v59, v32
	v_mov_b32_e32 v60, v32
	v_mov_b32_e32 v61, v32
	v_mov_b32_e32 v62, v32
	v_mov_b32_e32 v63, v32

.LBB0_935:
	ds_read_b128 v[102:105], v181 offset:26656
	ds_read_b128 v[138:141], v181 offset:33312
	s_waitcnt lgkmcnt(3)
	v_mfma_f32_32x32x16_bf16 v[106:121], v[64:67], v[144:147], v[32:47]
	v_exp_f32_e32 v101, v122
	v_exp_f32_e32 v142, v123
	v_exp_f32_e32 v143, v124
	v_exp_f32_e32 v202, v125
	v_exp_f32_e32 v126, v126
	v_exp_f32_e32 v127, v127
	s_waitcnt lgkmcnt(2)
	v_mfma_f32_32x32x16_bf16 v[64:79], v[96:99], v[144:147], v[32:47]
	ds_read_b128 v[96:99], v181 offset:26688
	ds_read_b128 v[122:125], v181 offset:33344
	s_waitcnt lgkmcnt(3)
	v_mfma_f32_32x32x16_bf16 v[106:121], v[102:105], v[148:151], v[106:121]
	v_cvt_pk_bf16_f32 v102, v101, v142
	v_add_f32_e32 v101, v143, v101
	v_add_f32_e32 v104, v202, v142
	v_add_f32_e32 v101, v126, v101
	s_waitcnt lgkmcnt(2)
	v_mfma_f32_32x32x16_bf16 v[64:79], v[138:141], v[148:151], v[64:79]
	v_add_f32_e32 v105, v127, v104
	v_exp_f32_e32 v203, v128
	v_exp_f32_e32 v204, v129
	v_exp_f32_e32 v205, v130
	v_exp_f32_e32 v213, v131
	v_exp_f32_e32 v214, v132
	v_exp_f32_e32 v215, v133
	v_cvt_pk_bf16_f32 v103, v143, v202
	v_cvt_pk_bf16_f32 v104, v126, v127
	ds_read_b128 v[126:129], v181 offset:26720
	ds_read_b128 v[130:133], v181 offset:33376
	s_waitcnt lgkmcnt(3)
	v_mfma_f32_32x32x16_bf16 v[106:121], v[96:99], v[152:155], v[106:121]
	v_add_f32_e32 v96, v203, v101
	v_add_f32_e32 v97, v204, v105
	v_add_f32_e32 v98, v205, v96
	v_add_f32_e32 v97, v213, v97
	v_add_f32_e32 v98, v214, v98
	v_add_f32_e32 v99, v215, v97
	s_waitcnt lgkmcnt(2)
	v_mfma_f32_32x32x16_bf16 v[64:79], v[122:125], v[152:155], v[64:79]
	v_exp_f32_e32 v138, v134
	v_exp_f32_e32 v139, v135
	v_exp_f32_e32 v140, v136
	v_exp_f32_e32 v141, v137
	v_cvt_pk_bf16_f32 v105, v203, v204
	v_cvt_pk_bf16_f32 v96, v205, v213
	v_cvt_pk_bf16_f32 v97, v214, v215
	ds_read_b128 v[122:125], v181 offset:26752
	ds_read_b128 v[134:137], v181 offset:33408
	s_waitcnt lgkmcnt(3)
	v_mfma_f32_32x32x16_bf16 v[106:121], v[126:129], v[156:159], v[106:121]
	v_exp_f32_e32 v101, v80
	v_exp_f32_e32 v142, v81
	v_add_f32_e32 v80, v138, v98
	v_add_f32_e32 v81, v139, v99
	v_exp_f32_e32 v203, v84
	v_exp_f32_e32 v204, v85
	s_waitcnt lgkmcnt(2)
	v_mfma_f32_32x32x16_bf16 v[64:79], v[130:133], v[156:159], v[64:79]
	v_add_f32_e32 v84, v140, v80
	v_add_f32_e32 v85, v141, v81
	v_exp_f32_e32 v143, v82
	v_exp_f32_e32 v202, v83
	v_cvt_pk_bf16_f32 v98, v138, v139
	v_cvt_pk_bf16_f32 v99, v140, v141
	ds_read_b128 v[80:83], v181 offset:26784
	ds_read_b128 v[126:129], v181 offset:33440
	s_waitcnt lgkmcnt(3)
	v_mfma_f32_32x32x16_bf16 v[106:121], v[122:125], v[160:163], v[106:121]
	v_exp_f32_e32 v87, v87
	v_exp_f32_e32 v130, v86
	v_add_f32_e32 v86, v101, v84
	v_add_f32_e32 v85, v142, v85
	v_exp_f32_e32 v131, v88
	v_add_f32_e32 v86, v143, v86
	s_waitcnt lgkmcnt(2)
	v_mfma_f32_32x32x16_bf16 v[64:79], v[134:137], v[160:163], v[64:79]
	v_add_f32_e32 v88, v202, v85
	v_cvt_pk_bf16_f32 v84, v101, v142
	v_add_f32_e32 v101, v203, v86
	v_add_f32_e32 v134, v204, v88
	v_exp_f32_e32 v132, v89
	v_exp_f32_e32 v133, v90
	v_exp_f32_e32 v138, v91
	v_cvt_pk_bf16_f32 v85, v143, v202
	v_cvt_pk_bf16_f32 v86, v203, v204
	ds_read_b128 v[88:91], v210 offset:62464
	ds_read_b128 v[122:125], v211 offset:13824
	s_waitcnt lgkmcnt(3)
	v_mfma_f32_32x32x16_bf16 v[106:121], v[80:83], v[164:167], v[106:121]
	v_add_f32_e32 v80, v130, v101
	v_add_f32_e32 v81, v87, v134
	v_add_f32_e32 v82, v131, v80
	v_add_f32_e32 v81, v132, v81
	v_add_f32_e32 v82, v133, v82
	v_add_f32_e32 v83, v138, v81
	s_waitcnt lgkmcnt(2)
	v_mfma_f32_32x32x16_bf16 v[64:79], v[126:129], v[164:167], v[64:79]
	v_exp_f32_e32 v135, v92
	v_exp_f32_e32 v136, v93
	v_exp_f32_e32 v137, v94
	v_exp_f32_e32 v139, v95
	v_cvt_pk_bf16_f32 v87, v130, v87
	v_cvt_pk_bf16_f32 v80, v131, v132
	v_cvt_pk_bf16_f32 v81, v133, v138
	ds_read_b128 v[92:95], v210 offset:62496
	ds_read_b128 v[126:129], v211 offset:13856
	s_waitcnt lgkmcnt(3)
	v_mfma_f32_32x32x16_bf16 v[0:15], v[88:91], v[102:105], v[0:15]
	v_add_f32_e32 v88, v135, v82
	v_add_f32_e32 v83, v136, v83
	v_add_f32_e32 v101, v137, v88
	v_add_f32_e32 v130, v139, v83
	v_cvt_pk_bf16_f32 v82, v135, v136
	v_cvt_pk_bf16_f32 v83, v137, v139
	s_waitcnt lgkmcnt(2)
	v_mfma_f32_32x32x16_bf16 v[16:31], v[122:125], v[102:105], v[16:31]
	ds_read_b128 v[88:91], v210 offset:62528
	s_waitcnt lgkmcnt(2)
	v_mfma_f32_32x32x16_bf16 v[0:15], v[92:95], v[96:99], v[0:15]
	ds_read_b128 v[92:95], v211 offset:13888
	s_waitcnt lgkmcnt(2)
	v_mfma_f32_32x32x16_bf16 v[16:31], v[126:129], v[96:99], v[16:31]
	ds_read_b128 v[96:99], v210 offset:62560
	ds_read_b128 v[102:105], v211 offset:13920
	s_waitcnt lgkmcnt(3)
	v_mfma_f32_32x32x16_bf16 v[0:15], v[88:91], v[84:87], v[0:15]
	s_waitcnt lgkmcnt(2)
	v_mfma_f32_32x32x16_bf16 v[16:31], v[92:95], v[84:87], v[16:31]
	s_waitcnt lgkmcnt(1)
	v_mfma_f32_32x32x16_bf16 v[0:15], v[96:99], v[80:83], v[0:15]
	v_add_f32_e32 v221, v101, v130
	v_add_f32_e32 v88, v100, v221
	s_waitcnt lgkmcnt(0)
	v_mfma_f32_32x32x16_bf16 v[16:31], v[102:105], v[80:83], v[16:31]
	s_waitcnt vmcnt(0)
	s_barrier
	ds_read_b128 v[84:87], v181 offset:39936
	ds_read_b128 v[80:83], v181 offset:46592
	v_cmp_lt_f32_e32 vcc, s58, v221
	s_cbranch_vccz .LBB0_937
	v_mov_b32_e32 v222, v221
	v_mov_b32_e32 v223, v221
	s_nop 1
	v_permlane32_swap_b32_e32 v222, v223
	v_add_f32_e32 v222, v222, v223
	v_log_f32_e32 v222, v222
	s_nop 0
	v_max_f32_e32 v33, 0, v222
	v_exp_f32_e64 v34, -v33
	v_add_f32_e32 v212, v212, v33
	v_xor_b32_e32 v32, 0x80000000, v212
	v_sub_f32_e32 v121, v121, v33
	v_pk_mul_f32 v[14:15], v[14:15], v[34:35] op_sel_hi:[1,0]
	v_pk_mul_f32 v[12:13], v[12:13], v[34:35] op_sel_hi:[1,0]
	v_pk_mul_f32 v[10:11], v[10:11], v[34:35] op_sel_hi:[1,0]
	v_pk_mul_f32 v[8:9], v[8:9], v[34:35] op_sel_hi:[1,0]
	v_pk_mul_f32 v[6:7], v[6:7], v[34:35] op_sel_hi:[1,0]
	v_pk_mul_f32 v[4:5], v[4:5], v[34:35] op_sel_hi:[1,0]
	v_pk_mul_f32 v[2:3], v[2:3], v[34:35] op_sel_hi:[1,0]
	v_pk_mul_f32 v[0:1], v[0:1], v[34:35] op_sel_hi:[1,0]
	v_pk_mul_f32 v[30:31], v[30:31], v[34:35] op_sel_hi:[1,0]
	v_pk_mul_f32 v[28:29], v[28:29], v[34:35] op_sel_hi:[1,0]
	v_pk_mul_f32 v[26:27], v[26:27], v[34:35] op_sel_hi:[1,0]
	v_pk_mul_f32 v[24:25], v[24:25], v[34:35] op_sel_hi:[1,0]
	v_pk_mul_f32 v[22:23], v[22:23], v[34:35] op_sel_hi:[1,0]
	v_pk_mul_f32 v[20:21], v[20:21], v[34:35] op_sel_hi:[1,0]
	v_pk_mul_f32 v[18:19], v[18:19], v[34:35] op_sel_hi:[1,0]
	v_pk_mul_f32 v[16:17], v[16:17], v[34:35] op_sel_hi:[1,0]
	v_sub_f32_e32 v120, v120, v33
	v_sub_f32_e32 v119, v119, v33
	v_sub_f32_e32 v118, v118, v33
	v_sub_f32_e32 v117, v117, v33
	v_sub_f32_e32 v116, v116, v33
	v_sub_f32_e32 v115, v115, v33
	v_sub_f32_e32 v114, v114, v33
	v_sub_f32_e32 v113, v113, v33
	v_sub_f32_e32 v112, v112, v33
	v_sub_f32_e32 v111, v111, v33
	v_sub_f32_e32 v110, v110, v33
	v_sub_f32_e32 v109, v109, v33
	v_sub_f32_e32 v108, v108, v33
	v_sub_f32_e32 v107, v107, v33
	v_sub_f32_e32 v106, v106, v33
	v_sub_f32_e32 v79, v79, v33
	v_sub_f32_e32 v78, v78, v33
	v_sub_f32_e32 v77, v77, v33
	v_sub_f32_e32 v76, v76, v33
	v_sub_f32_e32 v75, v75, v33
	v_sub_f32_e32 v74, v74, v33
	v_sub_f32_e32 v73, v73, v33
	v_sub_f32_e32 v72, v72, v33
	v_sub_f32_e32 v71, v71, v33
	v_sub_f32_e32 v70, v70, v33
	v_sub_f32_e32 v69, v69, v33
	v_sub_f32_e32 v68, v68, v33
	v_sub_f32_e32 v67, v67, v33
	v_sub_f32_e32 v66, v66, v33
	v_sub_f32_e32 v65, v65, v33
	v_sub_f32_e32 v64, v64, v33
	v_mul_f32_e32 v88, v88, v34
	v_mov_b32_e32 v33, v32
	v_mov_b32_e32 v34, v32
	v_mov_b32_e32 v35, v32
	v_mov_b32_e32 v36, v32
	v_mov_b32_e32 v37, v32
	v_mov_b32_e32 v38, v32
	v_mov_b32_e32 v39, v32
	v_mov_b32_e32 v40, v32
	v_mov_b32_e32 v41, v32
	v_mov_b32_e32 v42, v32
	v_mov_b32_e32 v43, v32
	v_mov_b32_e32 v44, v32
	v_mov_b32_e32 v45, v32
	v_mov_b32_e32 v46, v32
	v_mov_b32_e32 v47, v32
	v_mov_b32_e32 v48, v32
	v_mov_b32_e32 v49, v32
	v_mov_b32_e32 v50, v32
	v_mov_b32_e32 v51, v32
	v_mov_b32_e32 v52, v32
	v_mov_b32_e32 v53, v32
	v_mov_b32_e32 v54, v32
	v_mov_b32_e32 v55, v32
	v_mov_b32_e32 v56, v32
	v_mov_b32_e32 v57, v32
	v_mov_b32_e32 v58, v32
	v_mov_b32_e32 v59, v32
	v_mov_b32_e32 v60, v32
	v_mov_b32_e32 v61, v32
	v_mov_b32_e32 v62, v32
	v_mov_b32_e32 v63, v32

.LBB0_941:
	s_waitcnt lgkmcnt(1)
	v_mfma_f32_32x32x16_bf16 v[122:137], v[84:87], v[144:147], v[32:47]
	v_exp_f32_e32 v89, v106
	v_exp_f32_e32 v94, v107
	v_exp_f32_e32 v95, v108
	v_exp_f32_e32 v142, v109
	v_exp_f32_e32 v143, v110
	v_exp_f32_e32 v202, v111
	ds_read_b128 v[84:87], v181 offset:39968
	ds_read_b128 v[90:93], v181 offset:46624
	s_waitcnt lgkmcnt(2)
	v_mfma_f32_32x32x16_bf16 v[96:111], v[80:83], v[144:147], v[32:47]
	ds_read_b128 v[80:83], v181 offset:40000
	ds_read_b128 v[138:141], v181 offset:46656
	s_waitcnt lgkmcnt(3)
	v_mfma_f32_32x32x16_bf16 v[122:137], v[84:87], v[148:151], v[122:137]
	v_exp_f32_e32 v116, v116
	v_add_f32_e32 v87, v95, v89
	v_add_f32_e32 v86, v142, v94
	v_cvt_pk_bf16_f32 v84, v89, v94
	s_waitcnt lgkmcnt(2)
	v_mfma_f32_32x32x16_bf16 v[96:111], v[90:93], v[148:151], v[96:111]
	v_add_f32_e32 v87, v143, v87
	v_add_f32_e32 v89, v202, v86
	v_exp_f32_e32 v203, v112
	v_exp_f32_e32 v204, v113
	v_exp_f32_e32 v205, v114
	v_exp_f32_e32 v213, v115
	v_exp_f32_e32 v117, v117
	v_cvt_pk_bf16_f32 v85, v95, v142
	v_cvt_pk_bf16_f32 v86, v143, v202
	ds_read_b128 v[90:93], v181 offset:40032
	ds_read_b128 v[112:115], v181 offset:46688
	s_waitcnt lgkmcnt(3)
	v_mfma_f32_32x32x16_bf16 v[122:137], v[80:83], v[152:155], v[122:137]
	v_add_f32_e32 v80, v203, v87
	v_add_f32_e32 v81, v204, v89
	v_add_f32_e32 v82, v205, v80
	v_add_f32_e32 v81, v213, v81
	v_add_f32_e32 v82, v116, v82
	v_add_f32_e32 v83, v117, v81
	s_waitcnt lgkmcnt(2)
	v_mfma_f32_32x32x16_bf16 v[96:111], v[138:141], v[152:155], v[96:111]
	v_exp_f32_e32 v94, v118
	v_exp_f32_e32 v95, v119
	v_exp_f32_e32 v120, v120
	v_exp_f32_e32 v121, v121
	v_cvt_pk_bf16_f32 v87, v203, v204
	v_cvt_pk_bf16_f32 v80, v205, v213
	v_cvt_pk_bf16_f32 v81, v116, v117
	ds_read_b128 v[116:119], v181 offset:40064
	ds_read_b128 v[138:141], v181 offset:46720
	s_waitcnt lgkmcnt(3)
	v_mfma_f32_32x32x16_bf16 v[122:137], v[90:93], v[156:159], v[122:137]
	v_exp_f32_e32 v89, v64
	v_exp_f32_e32 v142, v65
	v_add_f32_e32 v64, v94, v82
	v_add_f32_e32 v65, v95, v83
	v_exp_f32_e32 v203, v68
	v_exp_f32_e32 v204, v69
	s_waitcnt lgkmcnt(2)
	v_mfma_f32_32x32x16_bf16 v[96:111], v[112:115], v[156:159], v[96:111]
	v_add_f32_e32 v68, v120, v64
	v_add_f32_e32 v69, v121, v65
	v_exp_f32_e32 v143, v66
	v_exp_f32_e32 v202, v67
	v_cvt_pk_bf16_f32 v82, v94, v95
	v_cvt_pk_bf16_f32 v83, v120, v121
	ds_read_b128 v[64:67], v181 offset:40096
	ds_read_b128 v[90:93], v181 offset:46752
	s_waitcnt lgkmcnt(3)
	v_mfma_f32_32x32x16_bf16 v[122:137], v[116:119], v[160:163], v[122:137]
	v_exp_f32_e32 v116, v74
	v_exp_f32_e32 v94, v70
	v_add_f32_e32 v70, v89, v68
	v_add_f32_e32 v69, v142, v69
	v_exp_f32_e32 v95, v72
	v_add_f32_e32 v70, v143, v70
	s_waitcnt lgkmcnt(2)
	v_mfma_f32_32x32x16_bf16 v[96:111], v[138:141], v[160:163], v[96:111]
	v_add_f32_e32 v72, v202, v69
	v_cvt_pk_bf16_f32 v68, v89, v142
	v_add_f32_e32 v89, v203, v70
	v_add_f32_e32 v118, v204, v72
	v_exp_f32_e32 v71, v71
	v_exp_f32_e32 v120, v73
	v_exp_f32_e32 v117, v75
	v_cvt_pk_bf16_f32 v69, v143, v202
	v_cvt_pk_bf16_f32 v70, v203, v204
	ds_read_b128 v[72:75], v211 offset:18432
	ds_read_b128 v[112:115], v211 offset:23040
	s_waitcnt lgkmcnt(3)
	v_mfma_f32_32x32x16_bf16 v[122:137], v[64:67], v[164:167], v[122:137]
	v_add_f32_e32 v64, v94, v89
	v_add_f32_e32 v65, v71, v118
	v_add_f32_e32 v66, v95, v64
	v_add_f32_e32 v65, v120, v65
	v_add_f32_e32 v66, v116, v66
	v_add_f32_e32 v67, v117, v65
	s_waitcnt lgkmcnt(2)
	v_mfma_f32_32x32x16_bf16 v[96:111], v[90:93], v[164:167], v[96:111]
	v_exp_f32_e32 v119, v76
	v_exp_f32_e32 v121, v77
	v_exp_f32_e32 v138, v78
	v_exp_f32_e32 v139, v79
	v_cvt_pk_bf16_f32 v71, v94, v71
	v_cvt_pk_bf16_f32 v64, v95, v120
	v_cvt_pk_bf16_f32 v65, v116, v117
	ds_read_b128 v[76:79], v211 offset:18464
	ds_read_b128 v[90:93], v211 offset:23072
	s_waitcnt lgkmcnt(3)
	v_mfma_f32_32x32x16_bf16 v[0:15], v[72:75], v[84:87], v[0:15]
	v_add_f32_e32 v72, v119, v66
	v_add_f32_e32 v67, v121, v67
	v_add_f32_e32 v89, v138, v72
	v_add_f32_e32 v94, v139, v67
	v_cvt_pk_bf16_f32 v66, v119, v121
	v_cvt_pk_bf16_f32 v67, v138, v139
	s_waitcnt lgkmcnt(2)
	v_mfma_f32_32x32x16_bf16 v[16:31], v[112:115], v[84:87], v[16:31]
	ds_read_b128 v[72:75], v211 offset:18496
	s_waitcnt lgkmcnt(2)
	v_mfma_f32_32x32x16_bf16 v[0:15], v[76:79], v[80:83], v[0:15]
	ds_read_b128 v[76:79], v211 offset:23104
	s_waitcnt lgkmcnt(2)
	v_mfma_f32_32x32x16_bf16 v[16:31], v[90:93], v[80:83], v[16:31]
	ds_read_b128 v[80:83], v211 offset:18528
	ds_read_b128 v[84:87], v211 offset:23136
	s_waitcnt lgkmcnt(3)
	v_mfma_f32_32x32x16_bf16 v[0:15], v[72:75], v[68:71], v[0:15]
	s_waitcnt lgkmcnt(2)
	v_mfma_f32_32x32x16_bf16 v[16:31], v[76:79], v[68:71], v[16:31]
	s_waitcnt lgkmcnt(1)
	v_mfma_f32_32x32x16_bf16 v[0:15], v[80:83], v[64:67], v[0:15]
	v_add_f32_e32 v221, v89, v94
	v_add_f32_e32 v116, v88, v221
	s_waitcnt lgkmcnt(0)
	v_mfma_f32_32x32x16_bf16 v[16:31], v[84:87], v[64:67], v[16:31]
	ds_read_b128 v[64:67], v181
	ds_read_b128 v[112:115], v181 offset:6656
	v_cmp_lt_f32_e32 vcc, s58, v221
	s_cbranch_vccz .LBB0_943
	v_mov_b32_e32 v222, v221
	v_mov_b32_e32 v223, v221
	s_nop 1
	v_permlane32_swap_b32_e32 v222, v223
	v_add_f32_e32 v222, v222, v223
	v_log_f32_e32 v222, v222
	s_nop 0
	v_max_f32_e32 v33, 0, v222
	v_exp_f32_e64 v34, -v33
	v_add_f32_e32 v212, v212, v33
	v_xor_b32_e32 v32, 0x80000000, v212
	v_sub_f32_e32 v137, v137, v33
	v_pk_mul_f32 v[14:15], v[14:15], v[34:35] op_sel_hi:[1,0]
	v_pk_mul_f32 v[12:13], v[12:13], v[34:35] op_sel_hi:[1,0]
	v_pk_mul_f32 v[10:11], v[10:11], v[34:35] op_sel_hi:[1,0]
	v_pk_mul_f32 v[8:9], v[8:9], v[34:35] op_sel_hi:[1,0]
	v_pk_mul_f32 v[6:7], v[6:7], v[34:35] op_sel_hi:[1,0]
	v_pk_mul_f32 v[4:5], v[4:5], v[34:35] op_sel_hi:[1,0]
	v_pk_mul_f32 v[2:3], v[2:3], v[34:35] op_sel_hi:[1,0]
	v_pk_mul_f32 v[0:1], v[0:1], v[34:35] op_sel_hi:[1,0]
	v_pk_mul_f32 v[30:31], v[30:31], v[34:35] op_sel_hi:[1,0]
	v_pk_mul_f32 v[28:29], v[28:29], v[34:35] op_sel_hi:[1,0]
	v_pk_mul_f32 v[26:27], v[26:27], v[34:35] op_sel_hi:[1,0]
	v_pk_mul_f32 v[24:25], v[24:25], v[34:35] op_sel_hi:[1,0]
	v_pk_mul_f32 v[22:23], v[22:23], v[34:35] op_sel_hi:[1,0]
	v_pk_mul_f32 v[20:21], v[20:21], v[34:35] op_sel_hi:[1,0]
	v_pk_mul_f32 v[18:19], v[18:19], v[34:35] op_sel_hi:[1,0]
	v_pk_mul_f32 v[16:17], v[16:17], v[34:35] op_sel_hi:[1,0]
	v_sub_f32_e32 v136, v136, v33
	v_sub_f32_e32 v135, v135, v33
	v_sub_f32_e32 v134, v134, v33
	v_sub_f32_e32 v133, v133, v33
	v_sub_f32_e32 v132, v132, v33
	v_sub_f32_e32 v131, v131, v33
	v_sub_f32_e32 v130, v130, v33
	v_sub_f32_e32 v129, v129, v33
	v_sub_f32_e32 v128, v128, v33
	v_sub_f32_e32 v127, v127, v33
	v_sub_f32_e32 v126, v126, v33
	v_sub_f32_e32 v125, v125, v33
	v_sub_f32_e32 v124, v124, v33
	v_sub_f32_e32 v123, v123, v33
	v_sub_f32_e32 v122, v122, v33
	v_sub_f32_e32 v111, v111, v33
	v_sub_f32_e32 v110, v110, v33
	v_sub_f32_e32 v109, v109, v33
	v_sub_f32_e32 v108, v108, v33
	v_sub_f32_e32 v107, v107, v33
	v_sub_f32_e32 v106, v106, v33
	v_sub_f32_e32 v105, v105, v33
	v_sub_f32_e32 v104, v104, v33
	v_sub_f32_e32 v103, v103, v33
	v_sub_f32_e32 v102, v102, v33
	v_sub_f32_e32 v101, v101, v33
	v_sub_f32_e32 v100, v100, v33
	v_sub_f32_e32 v99, v99, v33
	v_sub_f32_e32 v98, v98, v33
	v_sub_f32_e32 v97, v97, v33
	v_sub_f32_e32 v96, v96, v33
	v_mul_f32_e32 v116, v116, v34
	v_mov_b32_e32 v33, v32
	v_mov_b32_e32 v34, v32
	v_mov_b32_e32 v35, v32
	v_mov_b32_e32 v36, v32
	v_mov_b32_e32 v37, v32
	v_mov_b32_e32 v38, v32
	v_mov_b32_e32 v39, v32
	v_mov_b32_e32 v40, v32
	v_mov_b32_e32 v41, v32
	v_mov_b32_e32 v42, v32
	v_mov_b32_e32 v43, v32
	v_mov_b32_e32 v44, v32
	v_mov_b32_e32 v45, v32
	v_mov_b32_e32 v46, v32
	v_mov_b32_e32 v47, v32
	v_mov_b32_e32 v48, v32
	v_mov_b32_e32 v49, v32
	v_mov_b32_e32 v50, v32
	v_mov_b32_e32 v51, v32
	v_mov_b32_e32 v52, v32
	v_mov_b32_e32 v53, v32
	v_mov_b32_e32 v54, v32
	v_mov_b32_e32 v55, v32
	v_mov_b32_e32 v56, v32
	v_mov_b32_e32 v57, v32
	v_mov_b32_e32 v58, v32
	v_mov_b32_e32 v59, v32
	v_mov_b32_e32 v60, v32
	v_mov_b32_e32 v61, v32
	v_mov_b32_e32 v62, v32
	v_mov_b32_e32 v63, v32

; template <bool NA>
; __device__ __forceinline__ void attn_unit(LAS unsigned char* lds, const bf16_t* Q, const bf16_t* Kg, const bf16_t* Kr, const bf16_t* Vt, bf16_t* O,
;                                           int h, int seqrow0, int q0, int t0, int NT, int rows, int g0, const float* rpb_h, int wid) {
;     ...
;         for (int t = 0; t < NT; t += 8) {
;             A_STEP(sA0, sA1, tmA, sB0, sB1, tmB, t);
;             A_STEP(sB0, sB1, tmB, sA0, sA1, tmA, t + 1);
;             A_STEP(sA0, sA1, tmA, sB0, sB1, tmB, t + 2);
;             A_STEP(sB0, sB1, tmB, sA0, sA1, tmA, t + 3);
;             A_STEP(sA0, sA1, tmA, sB0, sB1, tmB, t + 4);
;             A_STEP(sB0, sB1, tmB, sA0, sA1, tmA, t + 5);
;             A_STEP(sA0, sA1, tmA, sB0, sB1, tmB, t + 6);
;             A_STEP(sB0, sB1, tmB, sA0, sA1, tmA, t + 7);
;         }
.LBB0_970:
	ds_read_b128 v[118:121], v181 offset:32
	ds_read_b128 v[138:141], v181 offset:6688
	s_waitcnt lgkmcnt(3)
	v_mfma_f32_32x32x16_bf16 v[80:95], v[64:67], v[144:147], v[32:47]
	v_exp_f32_e32 v117, v122
	v_exp_f32_e32 v142, v123
	v_exp_f32_e32 v143, v124
	v_exp_f32_e32 v202, v125
	v_exp_f32_e32 v126, v126
	v_exp_f32_e32 v127, v127
	s_waitcnt lgkmcnt(2)
	v_mfma_f32_32x32x16_bf16 v[64:79], v[112:115], v[144:147], v[32:47]
	ds_read_b128 v[112:115], v181 offset:64
	ds_read_b128 v[122:125], v181 offset:6720
	s_waitcnt lgkmcnt(3)
	v_mfma_f32_32x32x16_bf16 v[80:95], v[118:121], v[148:151], v[80:95]
	v_cvt_pk_bf16_f32 v118, v117, v142
	v_add_f32_e32 v117, v143, v117
	v_add_f32_e32 v120, v202, v142
	v_add_f32_e32 v117, v126, v117
	s_waitcnt lgkmcnt(2)
	v_mfma_f32_32x32x16_bf16 v[64:79], v[138:141], v[148:151], v[64:79]
	v_add_f32_e32 v121, v127, v120
	v_exp_f32_e32 v203, v128
	v_exp_f32_e32 v204, v129
	v_exp_f32_e32 v205, v130
	v_exp_f32_e32 v213, v131
	v_exp_f32_e32 v214, v132
	v_exp_f32_e32 v215, v133
	v_cvt_pk_bf16_f32 v119, v143, v202
	v_cvt_pk_bf16_f32 v120, v126, v127
	ds_read_b128 v[126:129], v181 offset:96
	ds_read_b128 v[130:133], v181 offset:6752
	s_waitcnt lgkmcnt(3)
	v_mfma_f32_32x32x16_bf16 v[80:95], v[112:115], v[152:155], v[80:95]
	v_add_f32_e32 v112, v203, v117
	v_add_f32_e32 v113, v204, v121
	v_add_f32_e32 v114, v205, v112
	v_add_f32_e32 v113, v213, v113
	v_add_f32_e32 v114, v214, v114
	v_add_f32_e32 v115, v215, v113
	s_waitcnt lgkmcnt(2)
	v_mfma_f32_32x32x16_bf16 v[64:79], v[122:125], v[152:155], v[64:79]
	v_exp_f32_e32 v138, v134
	v_exp_f32_e32 v139, v135
	v_exp_f32_e32 v140, v136
	v_exp_f32_e32 v141, v137
	v_cvt_pk_bf16_f32 v121, v203, v204
	v_cvt_pk_bf16_f32 v112, v205, v213
	v_cvt_pk_bf16_f32 v113, v214, v215
	ds_read_b128 v[122:125], v181 offset:128
	ds_read_b128 v[134:137], v181 offset:6784
	s_waitcnt lgkmcnt(3)
	v_mfma_f32_32x32x16_bf16 v[80:95], v[126:129], v[156:159], v[80:95]
	v_exp_f32_e32 v117, v96
	v_exp_f32_e32 v142, v97
	v_add_f32_e32 v96, v138, v114
	v_add_f32_e32 v97, v139, v115
	v_exp_f32_e32 v203, v100
	v_exp_f32_e32 v204, v101
	s_waitcnt lgkmcnt(2)
	v_mfma_f32_32x32x16_bf16 v[64:79], v[130:133], v[156:159], v[64:79]
	v_add_f32_e32 v100, v140, v96
	v_add_f32_e32 v101, v141, v97
	v_exp_f32_e32 v143, v98
	v_exp_f32_e32 v202, v99
	v_cvt_pk_bf16_f32 v114, v138, v139
	v_cvt_pk_bf16_f32 v115, v140, v141
	ds_read_b128 v[96:99], v181 offset:160
	ds_read_b128 v[126:129], v181 offset:6816
	s_waitcnt lgkmcnt(3)
	v_mfma_f32_32x32x16_bf16 v[80:95], v[122:125], v[160:163], v[80:95]
	v_exp_f32_e32 v130, v102
	v_add_f32_e32 v102, v117, v100
	v_add_f32_e32 v101, v142, v101
	v_exp_f32_e32 v131, v104
	v_add_f32_e32 v102, v143, v102
	v_add_f32_e32 v104, v202, v101
	s_waitcnt lgkmcnt(2)
	v_mfma_f32_32x32x16_bf16 v[64:79], v[134:137], v[160:163], v[64:79]
	v_cvt_pk_bf16_f32 v100, v117, v142
	v_add_f32_e32 v117, v203, v102
	v_add_f32_e32 v134, v204, v104
	v_exp_f32_e32 v103, v103
	v_exp_f32_e32 v132, v105
	v_exp_f32_e32 v133, v106
	v_exp_f32_e32 v138, v107
	v_cvt_pk_bf16_f32 v101, v143, v202
	v_cvt_pk_bf16_f32 v102, v203, v204
	ds_read_b128 v[104:107], v211 offset:27648
	ds_read_b128 v[122:125], v211 offset:32256
	s_waitcnt lgkmcnt(3)
	v_mfma_f32_32x32x16_bf16 v[80:95], v[96:99], v[164:167], v[80:95]
	v_add_f32_e32 v96, v130, v117
	v_add_f32_e32 v97, v103, v134
	v_add_f32_e32 v98, v131, v96
	v_add_f32_e32 v97, v132, v97
	v_add_f32_e32 v98, v133, v98
	v_add_f32_e32 v99, v138, v97
	s_waitcnt lgkmcnt(2)
	v_mfma_f32_32x32x16_bf16 v[64:79], v[126:129], v[164:167], v[64:79]
	v_exp_f32_e32 v135, v108
	v_exp_f32_e32 v136, v109
	v_exp_f32_e32 v137, v110
	v_exp_f32_e32 v139, v111
	v_cvt_pk_bf16_f32 v103, v130, v103
	v_cvt_pk_bf16_f32 v96, v131, v132
	v_cvt_pk_bf16_f32 v97, v133, v138
	ds_read_b128 v[108:111], v211 offset:27680
	ds_read_b128 v[126:129], v211 offset:32288
	s_waitcnt lgkmcnt(3)
	v_mfma_f32_32x32x16_bf16 v[0:15], v[104:107], v[118:121], v[0:15]
	v_add_f32_e32 v104, v135, v98
	v_add_f32_e32 v99, v136, v99
	v_add_f32_e32 v117, v137, v104
	v_add_f32_e32 v130, v139, v99
	v_cvt_pk_bf16_f32 v98, v135, v136
	v_cvt_pk_bf16_f32 v99, v137, v139
	s_waitcnt lgkmcnt(2)
	v_mfma_f32_32x32x16_bf16 v[16:31], v[122:125], v[118:121], v[16:31]
	ds_read_b128 v[104:107], v211 offset:27712
	s_waitcnt lgkmcnt(2)
	v_mfma_f32_32x32x16_bf16 v[0:15], v[108:111], v[112:115], v[0:15]
	ds_read_b128 v[108:111], v211 offset:32320
	s_waitcnt lgkmcnt(2)
	v_mfma_f32_32x32x16_bf16 v[16:31], v[126:129], v[112:115], v[16:31]
	ds_read_b128 v[112:115], v211 offset:27744
	ds_read_b128 v[118:121], v211 offset:32352
	s_waitcnt lgkmcnt(3)
	v_mfma_f32_32x32x16_bf16 v[0:15], v[104:107], v[100:103], v[0:15]
	s_waitcnt lgkmcnt(2)
	v_mfma_f32_32x32x16_bf16 v[16:31], v[108:111], v[100:103], v[16:31]
	s_waitcnt lgkmcnt(1)
	v_mfma_f32_32x32x16_bf16 v[0:15], v[112:115], v[96:99], v[0:15]
	v_add_f32_e32 v221, v117, v130
	v_add_f32_e32 v116, v116, v221
	s_waitcnt lgkmcnt(0)
	v_mfma_f32_32x32x16_bf16 v[16:31], v[118:121], v[96:99], v[16:31]
	s_waitcnt vmcnt(0)
	s_add_u32 s10, s10, 0x400
	s_addc_u32 s11, s11, 0
	v_lshl_add_u64 v[200:201], v[200:201], 0, v[168:169]
	s_cmpk_lt_u32 s16, 0xf8
	v_lshl_add_u64 v[196:197], v[196:197], 0, v[198:199]
	s_barrier
	s_cbranch_scc0 .LBB0_950

.LBB0_982:
	ds_read_b128 v[118:121], v181 offset:13344
	ds_read_b128 v[122:125], v181 offset:20000
	s_waitcnt lgkmcnt(3)
	v_mfma_f32_32x32x16_bf16 v[128:143], v[96:99], v[144:147], v[32:47]
	v_exp_f32_e32 v117, v80
	v_exp_f32_e32 v126, v81
	v_exp_f32_e32 v127, v82
	v_exp_f32_e32 v213, v83
	v_exp_f32_e32 v214, v84
	v_exp_f32_e32 v215, v85
	s_waitcnt lgkmcnt(2)
	v_mfma_f32_32x32x16_bf16 v[96:111], v[112:115], v[144:147], v[32:47]
	ds_read_b128 v[80:83], v181 offset:13376
	ds_read_b128 v[112:115], v181 offset:20032
	s_waitcnt lgkmcnt(3)
	v_mfma_f32_32x32x16_bf16 v[128:143], v[118:121], v[148:151], v[128:143]
	v_exp_f32_e32 v216, v86
	v_exp_f32_e32 v217, v88
	v_add_f32_e32 v88, v127, v117
	v_add_f32_e32 v86, v213, v126
	s_waitcnt lgkmcnt(2)
	v_mfma_f32_32x32x16_bf16 v[96:111], v[122:125], v[148:151], v[96:111]
	v_cvt_pk_bf16_f32 v84, v117, v126
	v_add_f32_e32 v117, v214, v88
	v_add_f32_e32 v122, v215, v86
	v_exp_f32_e32 v87, v87
	v_exp_f32_e32 v218, v89
	v_exp_f32_e32 v219, v90
	v_exp_f32_e32 v220, v91
	v_cvt_pk_bf16_f32 v85, v127, v213
	v_cvt_pk_bf16_f32 v86, v214, v215
	ds_read_b128 v[88:91], v181 offset:13408
	ds_read_b128 v[118:121], v181 offset:20064
	s_waitcnt lgkmcnt(3)
	v_mfma_f32_32x32x16_bf16 v[128:143], v[80:83], v[152:155], v[128:143]
	v_add_f32_e32 v80, v216, v117
	v_add_f32_e32 v81, v87, v122
	v_add_f32_e32 v82, v217, v80
	v_add_f32_e32 v81, v218, v81
	v_add_f32_e32 v82, v219, v82
	v_add_f32_e32 v83, v220, v81
	s_waitcnt lgkmcnt(2)
	v_mfma_f32_32x32x16_bf16 v[96:111], v[112:115], v[152:155], v[96:111]
	v_exp_f32_e32 v123, v92
	v_exp_f32_e32 v124, v93
	v_exp_f32_e32 v125, v94
	v_exp_f32_e32 v126, v95
	v_cvt_pk_bf16_f32 v87, v216, v87
	v_cvt_pk_bf16_f32 v80, v217, v218
	v_cvt_pk_bf16_f32 v81, v219, v220
	ds_read_b128 v[92:95], v181 offset:13440
	ds_read_b128 v[112:115], v181 offset:20096
	s_waitcnt lgkmcnt(3)
	v_mfma_f32_32x32x16_bf16 v[128:143], v[88:91], v[156:159], v[128:143]
	v_exp_f32_e32 v117, v64
	v_exp_f32_e32 v122, v65
	v_add_f32_e32 v64, v123, v82
	v_add_f32_e32 v65, v124, v83
	v_exp_f32_e32 v214, v68
	v_exp_f32_e32 v215, v69
	s_waitcnt lgkmcnt(2)
	v_mfma_f32_32x32x16_bf16 v[96:111], v[118:121], v[156:159], v[96:111]
	v_add_f32_e32 v68, v125, v64
	v_add_f32_e32 v69, v126, v65
	v_exp_f32_e32 v127, v66
	v_exp_f32_e32 v213, v67
	v_cvt_pk_bf16_f32 v82, v123, v124
	v_cvt_pk_bf16_f32 v83, v125, v126
	ds_read_b128 v[64:67], v181 offset:13472
	ds_read_b128 v[88:91], v181 offset:20128
	s_waitcnt lgkmcnt(3)
	v_mfma_f32_32x32x16_bf16 v[128:143], v[92:95], v[160:163], v[128:143]
	v_exp_f32_e32 v118, v70
	v_add_f32_e32 v70, v117, v68
	v_add_f32_e32 v69, v122, v69
	v_exp_f32_e32 v119, v72
	v_add_f32_e32 v70, v127, v70
	v_add_f32_e32 v72, v213, v69
	s_waitcnt lgkmcnt(2)
	v_mfma_f32_32x32x16_bf16 v[96:111], v[112:115], v[160:163], v[96:111]
	v_add_f32_e32 v112, v214, v70
	v_add_f32_e32 v113, v215, v72
	v_exp_f32_e32 v71, v71
	v_exp_f32_e32 v120, v73
	v_exp_f32_e32 v121, v74
	v_exp_f32_e32 v123, v75
	v_cvt_pk_bf16_f32 v68, v117, v122
	v_cvt_pk_bf16_f32 v69, v127, v213
	v_cvt_pk_bf16_f32 v70, v214, v215
	ds_read_b128 v[72:75], v210 offset:53248
	ds_read_b128 v[92:95], v210 offset:57856
	s_waitcnt lgkmcnt(3)
	v_mfma_f32_32x32x16_bf16 v[128:143], v[64:67], v[164:167], v[128:143]
	v_add_f32_e32 v64, v118, v112
	v_add_f32_e32 v65, v71, v113
	v_add_f32_e32 v66, v119, v64
	v_add_f32_e32 v65, v120, v65
	v_add_f32_e32 v66, v121, v66
	v_add_f32_e32 v67, v123, v65
	s_waitcnt lgkmcnt(2)
	v_mfma_f32_32x32x16_bf16 v[96:111], v[88:91], v[164:167], v[96:111]
	v_exp_f32_e32 v114, v76
	v_exp_f32_e32 v115, v77
	v_exp_f32_e32 v117, v78
	v_exp_f32_e32 v122, v79
	v_cvt_pk_bf16_f32 v71, v118, v71
	v_cvt_pk_bf16_f32 v64, v119, v120
	v_cvt_pk_bf16_f32 v65, v121, v123
	ds_read_b128 v[76:79], v210 offset:53280
	ds_read_b128 v[88:91], v210 offset:57888
	s_waitcnt lgkmcnt(3)
	v_mfma_f32_32x32x16_bf16 v[0:15], v[72:75], v[84:87], v[0:15]
	v_add_f32_e32 v72, v114, v66
	v_add_f32_e32 v67, v115, v67
	v_add_f32_e32 v112, v117, v72
	v_add_f32_e32 v113, v122, v67
	v_cvt_pk_bf16_f32 v66, v114, v115
	v_cvt_pk_bf16_f32 v67, v117, v122
	s_waitcnt lgkmcnt(2)
	v_mfma_f32_32x32x16_bf16 v[16:31], v[92:95], v[84:87], v[16:31]
	ds_read_b128 v[72:75], v210 offset:53312
	s_waitcnt lgkmcnt(2)
	v_mfma_f32_32x32x16_bf16 v[0:15], v[76:79], v[80:83], v[0:15]
	ds_read_b128 v[76:79], v210 offset:57920
	s_waitcnt lgkmcnt(2)
	v_mfma_f32_32x32x16_bf16 v[16:31], v[88:91], v[80:83], v[16:31]
	ds_read_b128 v[80:83], v210 offset:53344
	ds_read_b128 v[88:91], v210 offset:57952
	s_waitcnt lgkmcnt(3)
	v_mfma_f32_32x32x16_bf16 v[0:15], v[72:75], v[68:71], v[0:15]
	s_waitcnt lgkmcnt(2)
	v_mfma_f32_32x32x16_bf16 v[16:31], v[76:79], v[68:71], v[16:31]
	s_waitcnt lgkmcnt(1)
	v_mfma_f32_32x32x16_bf16 v[0:15], v[80:83], v[64:67], v[0:15]
	v_add_f32_e32 v221, v112, v113
	v_add_f32_e32 v86, v116, v221
	s_waitcnt lgkmcnt(0)
	v_mfma_f32_32x32x16_bf16 v[16:31], v[88:91], v[64:67], v[16:31]
	ds_read_b128 v[64:67], v181 offset:26624
	ds_read_b128 v[80:83], v181 offset:33280
	v_cmp_lt_f32_e32 vcc, s59, v221
	s_cbranch_vccz .LBB0_984
	v_mov_b32_e32 v222, v221
	v_mov_b32_e32 v223, v221
	s_nop 1
	v_permlane32_swap_b32_e32 v222, v223
	v_add_f32_e32 v222, v222, v223
	v_log_f32_e32 v222, v222
	s_nop 0
	v_max_f32_e32 v33, 0, v222
	v_exp_f32_e64 v34, -v33
	v_add_f32_e32 v212, v212, v33
	v_xor_b32_e32 v32, 0x80000000, v212
	v_sub_f32_e32 v143, v143, v33
	v_pk_mul_f32 v[14:15], v[14:15], v[34:35] op_sel_hi:[1,0]
	v_pk_mul_f32 v[12:13], v[12:13], v[34:35] op_sel_hi:[1,0]
	v_pk_mul_f32 v[10:11], v[10:11], v[34:35] op_sel_hi:[1,0]
	v_pk_mul_f32 v[8:9], v[8:9], v[34:35] op_sel_hi:[1,0]
	v_pk_mul_f32 v[6:7], v[6:7], v[34:35] op_sel_hi:[1,0]
	v_pk_mul_f32 v[4:5], v[4:5], v[34:35] op_sel_hi:[1,0]
	v_pk_mul_f32 v[2:3], v[2:3], v[34:35] op_sel_hi:[1,0]
	v_pk_mul_f32 v[0:1], v[0:1], v[34:35] op_sel_hi:[1,0]
	v_pk_mul_f32 v[30:31], v[30:31], v[34:35] op_sel_hi:[1,0]
	v_pk_mul_f32 v[28:29], v[28:29], v[34:35] op_sel_hi:[1,0]
	v_pk_mul_f32 v[26:27], v[26:27], v[34:35] op_sel_hi:[1,0]
	v_pk_mul_f32 v[24:25], v[24:25], v[34:35] op_sel_hi:[1,0]
	v_pk_mul_f32 v[22:23], v[22:23], v[34:35] op_sel_hi:[1,0]
	v_pk_mul_f32 v[20:21], v[20:21], v[34:35] op_sel_hi:[1,0]
	v_pk_mul_f32 v[18:19], v[18:19], v[34:35] op_sel_hi:[1,0]
	v_pk_mul_f32 v[16:17], v[16:17], v[34:35] op_sel_hi:[1,0]
	v_sub_f32_e32 v142, v142, v33
	v_sub_f32_e32 v141, v141, v33
	v_sub_f32_e32 v140, v140, v33
	v_sub_f32_e32 v139, v139, v33
	v_sub_f32_e32 v138, v138, v33
	v_sub_f32_e32 v137, v137, v33
	v_sub_f32_e32 v136, v136, v33
	v_sub_f32_e32 v135, v135, v33
	v_sub_f32_e32 v134, v134, v33
	v_sub_f32_e32 v133, v133, v33
	v_sub_f32_e32 v132, v132, v33
	v_sub_f32_e32 v131, v131, v33
	v_sub_f32_e32 v130, v130, v33
	v_sub_f32_e32 v129, v129, v33
	v_sub_f32_e32 v128, v128, v33
	v_sub_f32_e32 v111, v111, v33
	v_sub_f32_e32 v110, v110, v33
	v_sub_f32_e32 v109, v109, v33
	v_sub_f32_e32 v108, v108, v33
	v_sub_f32_e32 v107, v107, v33
	v_sub_f32_e32 v106, v106, v33
	v_sub_f32_e32 v105, v105, v33
	v_sub_f32_e32 v104, v104, v33
	v_sub_f32_e32 v103, v103, v33
	v_sub_f32_e32 v102, v102, v33
	v_sub_f32_e32 v101, v101, v33
	v_sub_f32_e32 v100, v100, v33
	v_sub_f32_e32 v99, v99, v33
	v_sub_f32_e32 v98, v98, v33
	v_sub_f32_e32 v97, v97, v33
	v_sub_f32_e32 v96, v96, v33
	v_mul_f32_e32 v86, v86, v34
	v_mov_b32_e32 v33, v32
	v_mov_b32_e32 v34, v32
	v_mov_b32_e32 v35, v32
	v_mov_b32_e32 v36, v32
	v_mov_b32_e32 v37, v32
	v_mov_b32_e32 v38, v32
	v_mov_b32_e32 v39, v32
	v_mov_b32_e32 v40, v32
	v_mov_b32_e32 v41, v32
	v_mov_b32_e32 v42, v32
	v_mov_b32_e32 v43, v32
	v_mov_b32_e32 v44, v32
	v_mov_b32_e32 v45, v32
	v_mov_b32_e32 v46, v32
	v_mov_b32_e32 v47, v32
	v_mov_b32_e32 v48, v32
	v_mov_b32_e32 v49, v32
	v_mov_b32_e32 v50, v32
	v_mov_b32_e32 v51, v32
	v_mov_b32_e32 v52, v32
	v_mov_b32_e32 v53, v32
	v_mov_b32_e32 v54, v32
	v_mov_b32_e32 v55, v32
	v_mov_b32_e32 v56, v32
	v_mov_b32_e32 v57, v32
	v_mov_b32_e32 v58, v32
	v_mov_b32_e32 v59, v32
	v_mov_b32_e32 v60, v32
	v_mov_b32_e32 v61, v32
	v_mov_b32_e32 v62, v32
	v_mov_b32_e32 v63, v32

.LBB0_988:
	ds_read_b128 v[88:91], v181 offset:26656
	ds_read_b128 v[92:95], v181 offset:33312
	s_waitcnt lgkmcnt(3)
	v_mfma_f32_32x32x16_bf16 v[112:127], v[64:67], v[144:147], v[32:47]
	v_exp_f32_e32 v87, v128
	v_exp_f32_e32 v213, v129
	v_exp_f32_e32 v214, v130
	v_exp_f32_e32 v215, v131
	v_exp_f32_e32 v132, v132
	v_exp_f32_e32 v133, v133
	s_waitcnt lgkmcnt(2)
	v_mfma_f32_32x32x16_bf16 v[64:79], v[80:83], v[144:147], v[32:47]
	ds_read_b128 v[80:83], v181 offset:26688
	ds_read_b128 v[128:131], v181 offset:33344
	s_waitcnt lgkmcnt(3)
	v_mfma_f32_32x32x16_bf16 v[112:127], v[88:91], v[148:151], v[112:127]
	v_cvt_pk_bf16_f32 v88, v87, v213
	v_add_f32_e32 v87, v214, v87
	v_add_f32_e32 v90, v215, v213
	v_add_f32_e32 v87, v132, v87
	s_waitcnt lgkmcnt(2)
	v_mfma_f32_32x32x16_bf16 v[64:79], v[92:95], v[148:151], v[64:79]
	v_add_f32_e32 v91, v133, v90
	v_exp_f32_e32 v216, v134
	v_exp_f32_e32 v217, v135
	v_exp_f32_e32 v136, v136
	v_exp_f32_e32 v137, v137
	v_exp_f32_e32 v138, v138
	v_exp_f32_e32 v139, v139
	v_cvt_pk_bf16_f32 v89, v214, v215
	v_cvt_pk_bf16_f32 v90, v132, v133
	ds_read_b128 v[92:95], v181 offset:26720
	ds_read_b128 v[132:135], v181 offset:33376
	s_waitcnt lgkmcnt(3)
	v_mfma_f32_32x32x16_bf16 v[112:127], v[80:83], v[152:155], v[112:127]
	v_add_f32_e32 v80, v216, v87
	v_add_f32_e32 v81, v217, v91
	v_add_f32_e32 v82, v136, v80
	v_add_f32_e32 v81, v137, v81
	v_add_f32_e32 v82, v138, v82
	v_add_f32_e32 v83, v139, v81
	s_waitcnt lgkmcnt(2)
	v_mfma_f32_32x32x16_bf16 v[64:79], v[128:131], v[152:155], v[64:79]
	v_exp_f32_e32 v140, v140
	v_exp_f32_e32 v141, v141
	v_exp_f32_e32 v142, v142
	v_exp_f32_e32 v143, v143
	v_cvt_pk_bf16_f32 v91, v216, v217
	v_cvt_pk_bf16_f32 v80, v136, v137
	v_cvt_pk_bf16_f32 v81, v138, v139
	ds_read_b128 v[128:131], v181 offset:26752
	ds_read_b128 v[136:139], v181 offset:33408
	s_waitcnt lgkmcnt(3)
	v_mfma_f32_32x32x16_bf16 v[112:127], v[92:95], v[156:159], v[112:127]
	v_exp_f32_e32 v87, v96
	v_add_f32_e32 v92, v140, v82
	v_add_f32_e32 v83, v141, v83
	v_exp_f32_e32 v216, v100
	v_exp_f32_e32 v217, v101
	v_add_f32_e32 v100, v142, v92
	s_waitcnt lgkmcnt(2)
	v_mfma_f32_32x32x16_bf16 v[64:79], v[132:135], v[156:159], v[64:79]
	v_add_f32_e32 v101, v143, v83
	v_exp_f32_e32 v213, v97
	v_exp_f32_e32 v214, v98
	v_exp_f32_e32 v215, v99
	v_cvt_pk_bf16_f32 v82, v140, v141
	v_cvt_pk_bf16_f32 v83, v142, v143
	ds_read_b128 v[92:95], v181 offset:26784
	ds_read_b128 v[96:99], v181 offset:33440
	s_waitcnt lgkmcnt(3)
	v_mfma_f32_32x32x16_bf16 v[112:127], v[128:131], v[160:163], v[112:127]
	v_exp_f32_e32 v132, v102
	v_add_f32_e32 v102, v87, v100
	v_add_f32_e32 v101, v213, v101
	v_cvt_pk_bf16_f32 v100, v87, v213
	v_add_f32_e32 v87, v214, v102
	v_add_f32_e32 v102, v215, v101
	s_waitcnt lgkmcnt(2)
	v_mfma_f32_32x32x16_bf16 v[64:79], v[136:139], v[160:163], v[64:79]
	v_add_f32_e32 v87, v216, v87
	v_add_f32_e32 v136, v217, v102
	v_exp_f32_e32 v103, v103
	v_exp_f32_e32 v133, v104
	v_exp_f32_e32 v134, v105
	v_exp_f32_e32 v135, v106
	v_exp_f32_e32 v140, v107
	v_cvt_pk_bf16_f32 v101, v214, v215
	v_cvt_pk_bf16_f32 v102, v216, v217
	ds_read_b128 v[104:107], v210 offset:62464
	ds_read_b128 v[128:131], v211 offset:13824
	s_waitcnt lgkmcnt(3)
	v_mfma_f32_32x32x16_bf16 v[112:127], v[92:95], v[164:167], v[112:127]
	v_add_f32_e32 v87, v132, v87
	v_add_f32_e32 v92, v103, v136
	v_add_f32_e32 v87, v133, v87
	v_add_f32_e32 v93, v134, v92
	v_add_f32_e32 v87, v135, v87
	v_add_f32_e32 v94, v140, v93
	s_waitcnt lgkmcnt(2)
	v_mfma_f32_32x32x16_bf16 v[64:79], v[96:99], v[164:167], v[64:79]
	v_exp_f32_e32 v137, v108
	v_exp_f32_e32 v138, v109
	v_exp_f32_e32 v139, v110
	v_exp_f32_e32 v141, v111
	v_cvt_pk_bf16_f32 v103, v132, v103
	v_cvt_pk_bf16_f32 v92, v133, v134
	v_cvt_pk_bf16_f32 v93, v135, v140
	ds_read_b128 v[96:99], v210 offset:62496
	ds_read_b128 v[108:111], v211 offset:13856
	s_waitcnt lgkmcnt(3)
	v_mfma_f32_32x32x16_bf16 v[0:15], v[104:107], v[88:91], v[0:15]
	v_add_f32_e32 v87, v137, v87
	v_add_f32_e32 v95, v138, v94
	v_add_f32_e32 v132, v139, v87
	v_add_f32_e32 v133, v141, v95
	v_cvt_pk_bf16_f32 v94, v137, v138
	v_cvt_pk_bf16_f32 v95, v139, v141
	s_waitcnt lgkmcnt(2)
	v_mfma_f32_32x32x16_bf16 v[16:31], v[128:131], v[88:91], v[16:31]
	ds_read_b128 v[88:91], v210 offset:62528
	s_waitcnt lgkmcnt(2)
	v_mfma_f32_32x32x16_bf16 v[0:15], v[96:99], v[80:83], v[0:15]
	ds_read_b128 v[96:99], v211 offset:13888
	s_waitcnt lgkmcnt(2)
	v_mfma_f32_32x32x16_bf16 v[16:31], v[108:111], v[80:83], v[16:31]
	ds_read_b128 v[80:83], v210 offset:62560
	ds_read_b128 v[104:107], v211 offset:13920
	s_waitcnt lgkmcnt(3)
	v_mfma_f32_32x32x16_bf16 v[0:15], v[88:91], v[100:103], v[0:15]
	s_waitcnt lgkmcnt(2)
	v_mfma_f32_32x32x16_bf16 v[16:31], v[96:99], v[100:103], v[16:31]
	s_waitcnt lgkmcnt(1)
	v_mfma_f32_32x32x16_bf16 v[0:15], v[80:83], v[92:95], v[0:15]
	v_add_f32_e32 v221, v132, v133
	v_add_f32_e32 v102, v86, v221
	s_waitcnt lgkmcnt(0)
	v_mfma_f32_32x32x16_bf16 v[16:31], v[104:107], v[92:95], v[16:31]
	s_waitcnt vmcnt(0)
	s_barrier
	ds_read_b128 v[80:83], v181 offset:39936
	ds_read_b128 v[96:99], v181 offset:46592
	v_cmp_lt_f32_e32 vcc, s59, v221
	s_cbranch_vccz .LBB0_990
	v_mov_b32_e32 v222, v221
	v_mov_b32_e32 v223, v221
	s_nop 1
	v_permlane32_swap_b32_e32 v222, v223
	v_add_f32_e32 v222, v222, v223
	v_log_f32_e32 v222, v222
	s_nop 0
	v_max_f32_e32 v33, 0, v222
	v_exp_f32_e64 v34, -v33
	v_add_f32_e32 v212, v212, v33
	v_xor_b32_e32 v32, 0x80000000, v212
	v_sub_f32_e32 v127, v127, v33
	v_pk_mul_f32 v[14:15], v[14:15], v[34:35] op_sel_hi:[1,0]
	v_pk_mul_f32 v[12:13], v[12:13], v[34:35] op_sel_hi:[1,0]
	v_pk_mul_f32 v[10:11], v[10:11], v[34:35] op_sel_hi:[1,0]
	v_pk_mul_f32 v[8:9], v[8:9], v[34:35] op_sel_hi:[1,0]
	v_pk_mul_f32 v[6:7], v[6:7], v[34:35] op_sel_hi:[1,0]
	v_pk_mul_f32 v[4:5], v[4:5], v[34:35] op_sel_hi:[1,0]
	v_pk_mul_f32 v[2:3], v[2:3], v[34:35] op_sel_hi:[1,0]
	v_pk_mul_f32 v[0:1], v[0:1], v[34:35] op_sel_hi:[1,0]
	v_pk_mul_f32 v[30:31], v[30:31], v[34:35] op_sel_hi:[1,0]
	v_pk_mul_f32 v[28:29], v[28:29], v[34:35] op_sel_hi:[1,0]
	v_pk_mul_f32 v[26:27], v[26:27], v[34:35] op_sel_hi:[1,0]
	v_pk_mul_f32 v[24:25], v[24:25], v[34:35] op_sel_hi:[1,0]
	v_pk_mul_f32 v[22:23], v[22:23], v[34:35] op_sel_hi:[1,0]
	v_pk_mul_f32 v[20:21], v[20:21], v[34:35] op_sel_hi:[1,0]
	v_pk_mul_f32 v[18:19], v[18:19], v[34:35] op_sel_hi:[1,0]
	v_pk_mul_f32 v[16:17], v[16:17], v[34:35] op_sel_hi:[1,0]
	v_sub_f32_e32 v126, v126, v33
	v_sub_f32_e32 v125, v125, v33
	v_sub_f32_e32 v124, v124, v33
	v_sub_f32_e32 v123, v123, v33
	v_sub_f32_e32 v122, v122, v33
	v_sub_f32_e32 v121, v121, v33
	v_sub_f32_e32 v120, v120, v33
	v_sub_f32_e32 v119, v119, v33
	v_sub_f32_e32 v118, v118, v33
	v_sub_f32_e32 v117, v117, v33
	v_sub_f32_e32 v116, v116, v33
	v_sub_f32_e32 v115, v115, v33
	v_sub_f32_e32 v114, v114, v33
	v_sub_f32_e32 v113, v113, v33
	v_sub_f32_e32 v112, v112, v33
	v_sub_f32_e32 v79, v79, v33
	v_sub_f32_e32 v78, v78, v33
	v_sub_f32_e32 v77, v77, v33
	v_sub_f32_e32 v76, v76, v33
	v_sub_f32_e32 v75, v75, v33
	v_sub_f32_e32 v74, v74, v33
	v_sub_f32_e32 v73, v73, v33
	v_sub_f32_e32 v72, v72, v33
	v_sub_f32_e32 v71, v71, v33
	v_sub_f32_e32 v70, v70, v33
	v_sub_f32_e32 v69, v69, v33
	v_sub_f32_e32 v68, v68, v33
	v_sub_f32_e32 v67, v67, v33
	v_sub_f32_e32 v66, v66, v33
	v_sub_f32_e32 v65, v65, v33
	v_sub_f32_e32 v64, v64, v33
	v_mul_f32_e32 v102, v102, v34
	v_mov_b32_e32 v33, v32
	v_mov_b32_e32 v34, v32
	v_mov_b32_e32 v35, v32
	v_mov_b32_e32 v36, v32
	v_mov_b32_e32 v37, v32
	v_mov_b32_e32 v38, v32
	v_mov_b32_e32 v39, v32
	v_mov_b32_e32 v40, v32
	v_mov_b32_e32 v41, v32
	v_mov_b32_e32 v42, v32
	v_mov_b32_e32 v43, v32
	v_mov_b32_e32 v44, v32
	v_mov_b32_e32 v45, v32
	v_mov_b32_e32 v46, v32
	v_mov_b32_e32 v47, v32
	v_mov_b32_e32 v48, v32
	v_mov_b32_e32 v49, v32
	v_mov_b32_e32 v50, v32
	v_mov_b32_e32 v51, v32
	v_mov_b32_e32 v52, v32
	v_mov_b32_e32 v53, v32
	v_mov_b32_e32 v54, v32
	v_mov_b32_e32 v55, v32
	v_mov_b32_e32 v56, v32
	v_mov_b32_e32 v57, v32
	v_mov_b32_e32 v58, v32
	v_mov_b32_e32 v59, v32
	v_mov_b32_e32 v60, v32
	v_mov_b32_e32 v61, v32
	v_mov_b32_e32 v62, v32
	v_mov_b32_e32 v63, v32

.LBB0_994:
	ds_read_b128 v[104:107], v181 offset:39968
	ds_read_b128 v[108:111], v181 offset:46624
	s_waitcnt lgkmcnt(3)
	v_mfma_f32_32x32x16_bf16 v[128:143], v[80:83], v[144:147], v[32:47]
	v_exp_f32_e32 v103, v112
	v_exp_f32_e32 v213, v113
	v_exp_f32_e32 v214, v114
	v_exp_f32_e32 v215, v115
	v_exp_f32_e32 v116, v116
	v_exp_f32_e32 v117, v117
	s_waitcnt lgkmcnt(2)
	v_mfma_f32_32x32x16_bf16 v[80:95], v[96:99], v[144:147], v[32:47]
	ds_read_b128 v[96:99], v181 offset:40000
	ds_read_b128 v[112:115], v181 offset:46656
	s_waitcnt lgkmcnt(3)
	v_mfma_f32_32x32x16_bf16 v[128:143], v[104:107], v[148:151], v[128:143]
	v_cvt_pk_bf16_f32 v104, v103, v213
	v_add_f32_e32 v103, v214, v103
	v_add_f32_e32 v106, v215, v213
	v_add_f32_e32 v103, v116, v103
	s_waitcnt lgkmcnt(2)
	v_mfma_f32_32x32x16_bf16 v[80:95], v[108:111], v[148:151], v[80:95]
	v_add_f32_e32 v107, v117, v106
	v_exp_f32_e32 v216, v118
	v_exp_f32_e32 v217, v119
	v_exp_f32_e32 v120, v120
	v_exp_f32_e32 v121, v121
	v_exp_f32_e32 v122, v122
	v_exp_f32_e32 v123, v123
	v_cvt_pk_bf16_f32 v105, v214, v215
	v_cvt_pk_bf16_f32 v106, v116, v117
	ds_read_b128 v[108:111], v181 offset:40032
	ds_read_b128 v[116:119], v181 offset:46688
	s_waitcnt lgkmcnt(3)
	v_mfma_f32_32x32x16_bf16 v[128:143], v[96:99], v[152:155], v[128:143]
	v_add_f32_e32 v96, v216, v103
	v_add_f32_e32 v97, v217, v107
	v_add_f32_e32 v98, v120, v96
	v_add_f32_e32 v97, v121, v97
	v_add_f32_e32 v98, v122, v98
	v_add_f32_e32 v99, v123, v97
	s_waitcnt lgkmcnt(2)
	v_mfma_f32_32x32x16_bf16 v[80:95], v[112:115], v[152:155], v[80:95]
	v_exp_f32_e32 v124, v124
	v_exp_f32_e32 v125, v125
	v_exp_f32_e32 v126, v126
	v_exp_f32_e32 v127, v127
	v_cvt_pk_bf16_f32 v107, v216, v217
	v_cvt_pk_bf16_f32 v96, v120, v121
	v_cvt_pk_bf16_f32 v97, v122, v123
	ds_read_b128 v[112:115], v181 offset:40064
	ds_read_b128 v[120:123], v181 offset:46720
	s_waitcnt lgkmcnt(3)
	v_mfma_f32_32x32x16_bf16 v[128:143], v[108:111], v[156:159], v[128:143]
	v_exp_f32_e32 v103, v64
	v_exp_f32_e32 v213, v65
	v_add_f32_e32 v64, v124, v98
	v_add_f32_e32 v65, v125, v99
	v_exp_f32_e32 v216, v68
	v_exp_f32_e32 v217, v69
	s_waitcnt lgkmcnt(2)
	v_mfma_f32_32x32x16_bf16 v[80:95], v[116:119], v[156:159], v[80:95]
	v_add_f32_e32 v68, v126, v64
	v_add_f32_e32 v69, v127, v65
	v_exp_f32_e32 v214, v66
	v_exp_f32_e32 v215, v67
	v_cvt_pk_bf16_f32 v98, v124, v125
	v_cvt_pk_bf16_f32 v99, v126, v127
	ds_read_b128 v[64:67], v181 offset:40096
	ds_read_b128 v[108:111], v181 offset:46752
	s_waitcnt lgkmcnt(3)
	v_mfma_f32_32x32x16_bf16 v[128:143], v[112:115], v[160:163], v[128:143]
	v_exp_f32_e32 v118, v73
	v_exp_f32_e32 v116, v70
	v_add_f32_e32 v70, v103, v68
	v_add_f32_e32 v69, v213, v69
	v_exp_f32_e32 v117, v72
	v_add_f32_e32 v70, v214, v70
	s_waitcnt lgkmcnt(2)
	v_mfma_f32_32x32x16_bf16 v[80:95], v[120:123], v[160:163], v[80:95]
	v_add_f32_e32 v72, v215, v69
	v_cvt_pk_bf16_f32 v68, v103, v213
	v_add_f32_e32 v103, v216, v70
	v_add_f32_e32 v120, v217, v72
	v_exp_f32_e32 v71, v71
	v_exp_f32_e32 v119, v74
	v_exp_f32_e32 v124, v75
	v_cvt_pk_bf16_f32 v69, v214, v215
	v_cvt_pk_bf16_f32 v70, v216, v217
	ds_read_b128 v[72:75], v211 offset:18432
	ds_read_b128 v[112:115], v211 offset:23040
	s_waitcnt lgkmcnt(3)
	v_mfma_f32_32x32x16_bf16 v[128:143], v[64:67], v[164:167], v[128:143]
	v_add_f32_e32 v64, v116, v103
	v_add_f32_e32 v65, v71, v120
	v_add_f32_e32 v66, v117, v64
	v_add_f32_e32 v65, v118, v65
	v_add_f32_e32 v66, v119, v66
	v_add_f32_e32 v67, v124, v65
	s_waitcnt lgkmcnt(2)
	v_mfma_f32_32x32x16_bf16 v[80:95], v[108:111], v[164:167], v[80:95]
	v_exp_f32_e32 v121, v76
	v_exp_f32_e32 v122, v77
	v_exp_f32_e32 v123, v78
	v_exp_f32_e32 v125, v79
	v_cvt_pk_bf16_f32 v71, v116, v71
	v_cvt_pk_bf16_f32 v64, v117, v118
	v_cvt_pk_bf16_f32 v65, v119, v124
	ds_read_b128 v[76:79], v211 offset:18464
	ds_read_b128 v[108:111], v211 offset:23072
	s_waitcnt lgkmcnt(3)
	v_mfma_f32_32x32x16_bf16 v[0:15], v[72:75], v[104:107], v[0:15]
	v_add_f32_e32 v72, v121, v66
	v_add_f32_e32 v67, v122, v67
	v_add_f32_e32 v103, v123, v72
	v_add_f32_e32 v116, v125, v67
	v_cvt_pk_bf16_f32 v66, v121, v122
	v_cvt_pk_bf16_f32 v67, v123, v125
	s_waitcnt lgkmcnt(2)
	v_mfma_f32_32x32x16_bf16 v[16:31], v[112:115], v[104:107], v[16:31]
	ds_read_b128 v[72:75], v211 offset:18496
	s_waitcnt lgkmcnt(2)
	v_mfma_f32_32x32x16_bf16 v[0:15], v[76:79], v[96:99], v[0:15]
	ds_read_b128 v[76:79], v211 offset:23104
	s_waitcnt lgkmcnt(2)
	v_mfma_f32_32x32x16_bf16 v[16:31], v[108:111], v[96:99], v[16:31]
	ds_read_b128 v[96:99], v211 offset:18528
	ds_read_b128 v[104:107], v211 offset:23136
	s_waitcnt lgkmcnt(3)
	v_mfma_f32_32x32x16_bf16 v[0:15], v[72:75], v[68:71], v[0:15]
	s_waitcnt lgkmcnt(2)
	v_mfma_f32_32x32x16_bf16 v[16:31], v[76:79], v[68:71], v[16:31]
	s_waitcnt lgkmcnt(1)
	v_mfma_f32_32x32x16_bf16 v[0:15], v[96:99], v[64:67], v[0:15]
	v_add_f32_e32 v221, v103, v116
	v_add_f32_e32 v118, v102, v221
	s_waitcnt lgkmcnt(0)
	v_mfma_f32_32x32x16_bf16 v[16:31], v[104:107], v[64:67], v[16:31]
	ds_read_b128 v[64:67], v181
	ds_read_b128 v[112:115], v181 offset:6656
	v_cmp_lt_f32_e32 vcc, s59, v221
	s_cbranch_vccz .LBB0_996
	v_mov_b32_e32 v222, v221
	v_mov_b32_e32 v223, v221
	s_nop 1
	v_permlane32_swap_b32_e32 v222, v223
	v_add_f32_e32 v222, v222, v223
	v_log_f32_e32 v222, v222
	s_nop 0
	v_max_f32_e32 v33, 0, v222
	v_exp_f32_e64 v34, -v33
	v_add_f32_e32 v212, v212, v33
	v_xor_b32_e32 v32, 0x80000000, v212
	v_sub_f32_e32 v143, v143, v33
	v_pk_mul_f32 v[14:15], v[14:15], v[34:35] op_sel_hi:[1,0]
	v_pk_mul_f32 v[12:13], v[12:13], v[34:35] op_sel_hi:[1,0]
	v_pk_mul_f32 v[10:11], v[10:11], v[34:35] op_sel_hi:[1,0]
	v_pk_mul_f32 v[8:9], v[8:9], v[34:35] op_sel_hi:[1,0]
	v_pk_mul_f32 v[6:7], v[6:7], v[34:35] op_sel_hi:[1,0]
	v_pk_mul_f32 v[4:5], v[4:5], v[34:35] op_sel_hi:[1,0]
	v_pk_mul_f32 v[2:3], v[2:3], v[34:35] op_sel_hi:[1,0]
	v_pk_mul_f32 v[0:1], v[0:1], v[34:35] op_sel_hi:[1,0]
	v_pk_mul_f32 v[30:31], v[30:31], v[34:35] op_sel_hi:[1,0]
	v_pk_mul_f32 v[28:29], v[28:29], v[34:35] op_sel_hi:[1,0]
	v_pk_mul_f32 v[26:27], v[26:27], v[34:35] op_sel_hi:[1,0]
	v_pk_mul_f32 v[24:25], v[24:25], v[34:35] op_sel_hi:[1,0]
	v_pk_mul_f32 v[22:23], v[22:23], v[34:35] op_sel_hi:[1,0]
	v_pk_mul_f32 v[20:21], v[20:21], v[34:35] op_sel_hi:[1,0]
	v_pk_mul_f32 v[18:19], v[18:19], v[34:35] op_sel_hi:[1,0]
	v_pk_mul_f32 v[16:17], v[16:17], v[34:35] op_sel_hi:[1,0]
	v_sub_f32_e32 v142, v142, v33
	v_sub_f32_e32 v141, v141, v33
	v_sub_f32_e32 v140, v140, v33
	v_sub_f32_e32 v139, v139, v33
	v_sub_f32_e32 v138, v138, v33
	v_sub_f32_e32 v137, v137, v33
	v_sub_f32_e32 v136, v136, v33
	v_sub_f32_e32 v135, v135, v33
	v_sub_f32_e32 v134, v134, v33
	v_sub_f32_e32 v133, v133, v33
	v_sub_f32_e32 v132, v132, v33
	v_sub_f32_e32 v131, v131, v33
	v_sub_f32_e32 v130, v130, v33
	v_sub_f32_e32 v129, v129, v33
	v_sub_f32_e32 v128, v128, v33
	v_sub_f32_e32 v95, v95, v33
	v_sub_f32_e32 v94, v94, v33
	v_sub_f32_e32 v93, v93, v33
	v_sub_f32_e32 v92, v92, v33
	v_sub_f32_e32 v91, v91, v33
	v_sub_f32_e32 v90, v90, v33
	v_sub_f32_e32 v89, v89, v33
	v_sub_f32_e32 v88, v88, v33
	v_sub_f32_e32 v87, v87, v33
	v_sub_f32_e32 v86, v86, v33
	v_sub_f32_e32 v85, v85, v33
	v_sub_f32_e32 v84, v84, v33
	v_sub_f32_e32 v83, v83, v33
	v_sub_f32_e32 v82, v82, v33
	v_sub_f32_e32 v81, v81, v33
	v_sub_f32_e32 v80, v80, v33
	v_mul_f32_e32 v118, v118, v34
	v_mov_b32_e32 v33, v32
	v_mov_b32_e32 v34, v32
	v_mov_b32_e32 v35, v32
	v_mov_b32_e32 v36, v32
	v_mov_b32_e32 v37, v32
	v_mov_b32_e32 v38, v32
	v_mov_b32_e32 v39, v32
	v_mov_b32_e32 v40, v32
	v_mov_b32_e32 v41, v32
	v_mov_b32_e32 v42, v32
	v_mov_b32_e32 v43, v32
	v_mov_b32_e32 v44, v32
	v_mov_b32_e32 v45, v32
	v_mov_b32_e32 v46, v32
	v_mov_b32_e32 v47, v32
	v_mov_b32_e32 v48, v32
	v_mov_b32_e32 v49, v32
	v_mov_b32_e32 v50, v32
	v_mov_b32_e32 v51, v32
	v_mov_b32_e32 v52, v32
	v_mov_b32_e32 v53, v32
	v_mov_b32_e32 v54, v32
	v_mov_b32_e32 v55, v32
	v_mov_b32_e32 v56, v32
	v_mov_b32_e32 v57, v32
	v_mov_b32_e32 v58, v32
	v_mov_b32_e32 v59, v32
	v_mov_b32_e32 v60, v32
	v_mov_b32_e32 v61, v32
	v_mov_b32_e32 v62, v32
	v_mov_b32_e32 v63, v32

.LBB0_1000:
	ds_read_b128 v[120:123], v181 offset:32
	ds_read_b128 v[124:127], v181 offset:6688
	s_waitcnt lgkmcnt(3)
	v_mfma_f32_32x32x16_bf16 v[96:111], v[64:67], v[144:147], v[32:47]
	v_exp_f32_e32 v119, v128
	v_exp_f32_e32 v213, v129
	v_exp_f32_e32 v214, v130
	v_exp_f32_e32 v215, v131
	v_exp_f32_e32 v132, v132
	v_exp_f32_e32 v133, v133
	s_waitcnt lgkmcnt(2)
	v_mfma_f32_32x32x16_bf16 v[64:79], v[112:115], v[144:147], v[32:47]
	ds_read_b128 v[112:115], v181 offset:64
	ds_read_b128 v[128:131], v181 offset:6720
	s_waitcnt lgkmcnt(3)
	v_mfma_f32_32x32x16_bf16 v[96:111], v[120:123], v[148:151], v[96:111]
	v_cvt_pk_bf16_f32 v120, v119, v213
	v_add_f32_e32 v119, v214, v119
	v_add_f32_e32 v122, v215, v213
	v_add_f32_e32 v119, v132, v119
	s_waitcnt lgkmcnt(2)
	v_mfma_f32_32x32x16_bf16 v[64:79], v[124:127], v[148:151], v[64:79]
	v_add_f32_e32 v123, v133, v122
	v_exp_f32_e32 v216, v134
	v_exp_f32_e32 v217, v135
	v_exp_f32_e32 v136, v136
	v_exp_f32_e32 v137, v137
	v_exp_f32_e32 v138, v138
	v_exp_f32_e32 v139, v139
	v_cvt_pk_bf16_f32 v121, v214, v215
	v_cvt_pk_bf16_f32 v122, v132, v133
	ds_read_b128 v[124:127], v181 offset:96
	ds_read_b128 v[132:135], v181 offset:6752
	s_waitcnt lgkmcnt(3)
	v_mfma_f32_32x32x16_bf16 v[96:111], v[112:115], v[152:155], v[96:111]
	v_add_f32_e32 v112, v216, v119
	v_add_f32_e32 v113, v217, v123
	v_add_f32_e32 v114, v136, v112
	v_add_f32_e32 v113, v137, v113
	v_add_f32_e32 v114, v138, v114
	v_add_f32_e32 v115, v139, v113
	s_waitcnt lgkmcnt(2)
	v_mfma_f32_32x32x16_bf16 v[64:79], v[128:131], v[152:155], v[64:79]
	v_exp_f32_e32 v140, v140
	v_exp_f32_e32 v141, v141
	v_exp_f32_e32 v142, v142
	v_exp_f32_e32 v143, v143
	v_cvt_pk_bf16_f32 v123, v216, v217
	v_cvt_pk_bf16_f32 v112, v136, v137
	v_cvt_pk_bf16_f32 v113, v138, v139
	ds_read_b128 v[128:131], v181 offset:128
	ds_read_b128 v[136:139], v181 offset:6784
	s_waitcnt lgkmcnt(3)
	v_mfma_f32_32x32x16_bf16 v[96:111], v[124:127], v[156:159], v[96:111]
	v_exp_f32_e32 v119, v80
	v_exp_f32_e32 v213, v81
	v_add_f32_e32 v80, v140, v114
	v_add_f32_e32 v81, v141, v115
	v_exp_f32_e32 v216, v84
	v_exp_f32_e32 v217, v85
	s_waitcnt lgkmcnt(2)
	v_mfma_f32_32x32x16_bf16 v[64:79], v[132:135], v[156:159], v[64:79]
	v_add_f32_e32 v84, v142, v80
	v_add_f32_e32 v85, v143, v81
	v_exp_f32_e32 v214, v82
	v_exp_f32_e32 v215, v83
	v_cvt_pk_bf16_f32 v114, v140, v141
	v_cvt_pk_bf16_f32 v115, v142, v143
	ds_read_b128 v[80:83], v181 offset:160
	ds_read_b128 v[124:127], v181 offset:6816
	s_waitcnt lgkmcnt(3)
	v_mfma_f32_32x32x16_bf16 v[96:111], v[128:131], v[160:163], v[96:111]
	v_exp_f32_e32 v132, v86
	v_add_f32_e32 v86, v119, v84
	v_add_f32_e32 v85, v213, v85
	v_exp_f32_e32 v133, v88
	v_add_f32_e32 v86, v214, v86
	v_add_f32_e32 v88, v215, v85
	s_waitcnt lgkmcnt(2)
	v_mfma_f32_32x32x16_bf16 v[64:79], v[136:139], v[160:163], v[64:79]
	v_cvt_pk_bf16_f32 v84, v119, v213
	v_add_f32_e32 v119, v216, v86
	v_add_f32_e32 v136, v217, v88
	v_exp_f32_e32 v87, v87
	v_exp_f32_e32 v134, v89
	v_exp_f32_e32 v135, v90
	v_exp_f32_e32 v140, v91
	v_cvt_pk_bf16_f32 v85, v214, v215
	v_cvt_pk_bf16_f32 v86, v216, v217
	ds_read_b128 v[88:91], v211 offset:27648
	ds_read_b128 v[128:131], v211 offset:32256
	s_waitcnt lgkmcnt(3)
	v_mfma_f32_32x32x16_bf16 v[96:111], v[80:83], v[164:167], v[96:111]
	v_add_f32_e32 v80, v132, v119
	v_add_f32_e32 v81, v87, v136
	v_add_f32_e32 v82, v133, v80
	v_add_f32_e32 v81, v134, v81
	v_add_f32_e32 v82, v135, v82
	v_add_f32_e32 v83, v140, v81
	s_waitcnt lgkmcnt(2)
	v_mfma_f32_32x32x16_bf16 v[64:79], v[124:127], v[164:167], v[64:79]
	v_exp_f32_e32 v137, v92
	v_exp_f32_e32 v138, v93
	v_exp_f32_e32 v139, v94
	v_exp_f32_e32 v141, v95
	v_cvt_pk_bf16_f32 v87, v132, v87
	v_cvt_pk_bf16_f32 v80, v133, v134
	v_cvt_pk_bf16_f32 v81, v135, v140
	ds_read_b128 v[92:95], v211 offset:27680
	ds_read_b128 v[124:127], v211 offset:32288
	s_waitcnt lgkmcnt(3)
	v_mfma_f32_32x32x16_bf16 v[0:15], v[88:91], v[120:123], v[0:15]
	v_add_f32_e32 v88, v137, v82
	v_add_f32_e32 v83, v138, v83
	v_add_f32_e32 v119, v139, v88
	v_add_f32_e32 v132, v141, v83
	v_cvt_pk_bf16_f32 v82, v137, v138
	v_cvt_pk_bf16_f32 v83, v139, v141
	s_waitcnt lgkmcnt(2)
	v_mfma_f32_32x32x16_bf16 v[16:31], v[128:131], v[120:123], v[16:31]
	ds_read_b128 v[88:91], v211 offset:27712
	s_waitcnt lgkmcnt(2)
	v_mfma_f32_32x32x16_bf16 v[0:15], v[92:95], v[112:115], v[0:15]
	ds_read_b128 v[92:95], v211 offset:32320
	s_waitcnt lgkmcnt(2)
	v_mfma_f32_32x32x16_bf16 v[16:31], v[124:127], v[112:115], v[16:31]
	ds_read_b128 v[112:115], v211 offset:27744
	ds_read_b128 v[120:123], v211 offset:32352
	s_waitcnt lgkmcnt(3)
	v_mfma_f32_32x32x16_bf16 v[0:15], v[88:91], v[84:87], v[0:15]
	s_waitcnt lgkmcnt(2)
	v_mfma_f32_32x32x16_bf16 v[16:31], v[92:95], v[84:87], v[16:31]
	s_waitcnt lgkmcnt(1)
	v_mfma_f32_32x32x16_bf16 v[0:15], v[112:115], v[80:83], v[0:15]
	v_add_f32_e32 v221, v119, v132
	v_add_f32_e32 v118, v118, v221
	s_waitcnt lgkmcnt(0)
	v_mfma_f32_32x32x16_bf16 v[16:31], v[120:123], v[80:83], v[16:31]
	s_waitcnt vmcnt(0)
	s_barrier
	ds_read_b128 v[80:83], v181 offset:13312
	ds_read_b128 v[112:115], v181 offset:19968
	v_cmp_lt_f32_e32 vcc, s59, v221
	s_cbranch_vccz .LBB0_1002
	v_mov_b32_e32 v222, v221
	v_mov_b32_e32 v223, v221
	s_nop 1
	v_permlane32_swap_b32_e32 v222, v223
	v_add_f32_e32 v222, v222, v223
	v_log_f32_e32 v222, v222
	s_nop 0
	v_max_f32_e32 v33, 0, v222
	v_exp_f32_e64 v34, -v33
	v_add_f32_e32 v212, v212, v33
	v_xor_b32_e32 v32, 0x80000000, v212
	v_sub_f32_e32 v111, v111, v33
	v_pk_mul_f32 v[14:15], v[14:15], v[34:35] op_sel_hi:[1,0]
	v_pk_mul_f32 v[12:13], v[12:13], v[34:35] op_sel_hi:[1,0]
	v_pk_mul_f32 v[10:11], v[10:11], v[34:35] op_sel_hi:[1,0]
	v_pk_mul_f32 v[8:9], v[8:9], v[34:35] op_sel_hi:[1,0]
	v_pk_mul_f32 v[6:7], v[6:7], v[34:35] op_sel_hi:[1,0]
	v_pk_mul_f32 v[4:5], v[4:5], v[34:35] op_sel_hi:[1,0]
	v_pk_mul_f32 v[2:3], v[2:3], v[34:35] op_sel_hi:[1,0]
	v_pk_mul_f32 v[0:1], v[0:1], v[34:35] op_sel_hi:[1,0]
	v_pk_mul_f32 v[30:31], v[30:31], v[34:35] op_sel_hi:[1,0]
	v_pk_mul_f32 v[28:29], v[28:29], v[34:35] op_sel_hi:[1,0]
	v_pk_mul_f32 v[26:27], v[26:27], v[34:35] op_sel_hi:[1,0]
	v_pk_mul_f32 v[24:25], v[24:25], v[34:35] op_sel_hi:[1,0]
	v_pk_mul_f32 v[22:23], v[22:23], v[34:35] op_sel_hi:[1,0]
	v_pk_mul_f32 v[20:21], v[20:21], v[34:35] op_sel_hi:[1,0]
	v_pk_mul_f32 v[18:19], v[18:19], v[34:35] op_sel_hi:[1,0]
	v_pk_mul_f32 v[16:17], v[16:17], v[34:35] op_sel_hi:[1,0]
	v_sub_f32_e32 v110, v110, v33
	v_sub_f32_e32 v109, v109, v33
	v_sub_f32_e32 v108, v108, v33
	v_sub_f32_e32 v107, v107, v33
	v_sub_f32_e32 v106, v106, v33
	v_sub_f32_e32 v105, v105, v33
	v_sub_f32_e32 v104, v104, v33
	v_sub_f32_e32 v103, v103, v33
	v_sub_f32_e32 v102, v102, v33
	v_sub_f32_e32 v101, v101, v33
	v_sub_f32_e32 v100, v100, v33
	v_sub_f32_e32 v99, v99, v33
	v_sub_f32_e32 v98, v98, v33
	v_sub_f32_e32 v97, v97, v33
	v_sub_f32_e32 v96, v96, v33
	v_sub_f32_e32 v79, v79, v33
	v_sub_f32_e32 v78, v78, v33
	v_sub_f32_e32 v77, v77, v33
	v_sub_f32_e32 v76, v76, v33
	v_sub_f32_e32 v75, v75, v33
	v_sub_f32_e32 v74, v74, v33
	v_sub_f32_e32 v73, v73, v33
	v_sub_f32_e32 v72, v72, v33
	v_sub_f32_e32 v71, v71, v33
	v_sub_f32_e32 v70, v70, v33
	v_sub_f32_e32 v69, v69, v33
	v_sub_f32_e32 v68, v68, v33
	v_sub_f32_e32 v67, v67, v33
	v_sub_f32_e32 v66, v66, v33
	v_sub_f32_e32 v65, v65, v33
	v_sub_f32_e32 v64, v64, v33
	v_mul_f32_e32 v118, v118, v34
	v_mov_b32_e32 v33, v32
	v_mov_b32_e32 v34, v32
	v_mov_b32_e32 v35, v32
	v_mov_b32_e32 v36, v32
	v_mov_b32_e32 v37, v32
	v_mov_b32_e32 v38, v32
	v_mov_b32_e32 v39, v32
	v_mov_b32_e32 v40, v32
	v_mov_b32_e32 v41, v32
	v_mov_b32_e32 v42, v32
	v_mov_b32_e32 v43, v32
	v_mov_b32_e32 v44, v32
	v_mov_b32_e32 v45, v32
	v_mov_b32_e32 v46, v32
	v_mov_b32_e32 v47, v32
	v_mov_b32_e32 v48, v32
	v_mov_b32_e32 v49, v32
	v_mov_b32_e32 v50, v32
	v_mov_b32_e32 v51, v32
	v_mov_b32_e32 v52, v32
	v_mov_b32_e32 v53, v32
	v_mov_b32_e32 v54, v32
	v_mov_b32_e32 v55, v32
	v_mov_b32_e32 v56, v32
	v_mov_b32_e32 v57, v32
	v_mov_b32_e32 v58, v32
	v_mov_b32_e32 v59, v32
	v_mov_b32_e32 v60, v32
	v_mov_b32_e32 v61, v32
	v_mov_b32_e32 v62, v32
	v_mov_b32_e32 v63, v32

.LBB0_1006:
	ds_read_b128 v[138:141], v181 offset:13344
	ds_read_b128 v[214:217], v181 offset:20000
	s_waitcnt lgkmcnt(3)
	v_mfma_f32_32x32x16_bf16 v[122:137], v[80:83], v[144:147], v[32:47]
	v_exp_f32_e32 v116, v96
	v_exp_f32_e32 v117, v97
	v_exp_f32_e32 v119, v98
	v_exp_f32_e32 v120, v99
	v_exp_f32_e32 v121, v100
	v_exp_f32_e32 v142, v101
	s_waitcnt lgkmcnt(2)
	v_mfma_f32_32x32x16_bf16 v[80:95], v[112:115], v[144:147], v[32:47]
	ds_read_b128 v[96:99], v181 offset:13376
	ds_read_b128 v[112:115], v181 offset:20032
	s_waitcnt lgkmcnt(3)
	v_mfma_f32_32x32x16_bf16 v[122:137], v[138:141], v[148:151], v[122:137]
	v_exp_f32_e32 v143, v102
	v_exp_f32_e32 v213, v104
	v_add_f32_e32 v104, v119, v116
	v_add_f32_e32 v102, v120, v117
	s_waitcnt lgkmcnt(2)
	v_mfma_f32_32x32x16_bf16 v[80:95], v[214:217], v[148:151], v[80:95]
	v_cvt_pk_bf16_f32 v100, v116, v117
	v_add_f32_e32 v116, v121, v104
	v_add_f32_e32 v117, v142, v102
	v_exp_f32_e32 v103, v103
	v_exp_f32_e32 v218, v105
	v_exp_f32_e32 v219, v106
	v_exp_f32_e32 v220, v107
	v_cvt_pk_bf16_f32 v101, v119, v120
	v_cvt_pk_bf16_f32 v102, v121, v142
	ds_read_b128 v[104:107], v181 offset:13408
	ds_read_b128 v[138:141], v181 offset:20064
	s_waitcnt lgkmcnt(3)
	v_mfma_f32_32x32x16_bf16 v[122:137], v[96:99], v[152:155], v[122:137]
	v_add_f32_e32 v96, v143, v116
	v_add_f32_e32 v97, v103, v117
	v_add_f32_e32 v98, v213, v96
	v_add_f32_e32 v97, v218, v97
	v_add_f32_e32 v98, v219, v98
	v_add_f32_e32 v99, v220, v97
	s_waitcnt lgkmcnt(2)
	v_mfma_f32_32x32x16_bf16 v[80:95], v[112:115], v[152:155], v[80:95]
	v_exp_f32_e32 v119, v108
	v_exp_f32_e32 v120, v109
	v_exp_f32_e32 v121, v110
	v_exp_f32_e32 v142, v111
	v_cvt_pk_bf16_f32 v103, v143, v103
	v_cvt_pk_bf16_f32 v96, v213, v218
	v_cvt_pk_bf16_f32 v97, v219, v220
	ds_read_b128 v[108:111], v181 offset:13440
	ds_read_b128 v[112:115], v181 offset:20096
	s_waitcnt lgkmcnt(3)
	v_mfma_f32_32x32x16_bf16 v[122:137], v[104:107], v[156:159], v[122:137]
	v_exp_f32_e32 v116, v64
	v_exp_f32_e32 v117, v65
	v_add_f32_e32 v64, v119, v98
	v_add_f32_e32 v65, v120, v99
	v_exp_f32_e32 v214, v68
	v_exp_f32_e32 v215, v69
	s_waitcnt lgkmcnt(2)
	v_mfma_f32_32x32x16_bf16 v[80:95], v[138:141], v[156:159], v[80:95]
	v_add_f32_e32 v68, v121, v64
	v_add_f32_e32 v69, v142, v65
	v_exp_f32_e32 v143, v66
	v_exp_f32_e32 v213, v67
	v_cvt_pk_bf16_f32 v98, v119, v120
	v_cvt_pk_bf16_f32 v99, v121, v142
	ds_read_b128 v[64:67], v181 offset:13472
	ds_read_b128 v[104:107], v181 offset:20128
	s_waitcnt lgkmcnt(3)
	v_mfma_f32_32x32x16_bf16 v[122:137], v[108:111], v[160:163], v[122:137]
	v_exp_f32_e32 v119, v70
	v_add_f32_e32 v70, v116, v68
	v_add_f32_e32 v69, v117, v69
	v_exp_f32_e32 v120, v72
	v_add_f32_e32 v70, v143, v70
	v_add_f32_e32 v72, v213, v69
	s_waitcnt lgkmcnt(2)
	v_mfma_f32_32x32x16_bf16 v[80:95], v[112:115], v[160:163], v[80:95]
	v_add_f32_e32 v112, v214, v70
	v_add_f32_e32 v113, v215, v72
	v_exp_f32_e32 v71, v71
	v_exp_f32_e32 v121, v73
	v_exp_f32_e32 v138, v74
	v_exp_f32_e32 v139, v75
	v_cvt_pk_bf16_f32 v68, v116, v117
	v_cvt_pk_bf16_f32 v69, v143, v213
	v_cvt_pk_bf16_f32 v70, v214, v215
	ds_read_b128 v[72:75], v210 offset:53248
	ds_read_b128 v[108:111], v210 offset:57856
	s_waitcnt lgkmcnt(3)
	v_mfma_f32_32x32x16_bf16 v[122:137], v[64:67], v[164:167], v[122:137]
	v_add_f32_e32 v64, v119, v112
	v_add_f32_e32 v65, v71, v113
	v_add_f32_e32 v66, v120, v64
	v_add_f32_e32 v65, v121, v65
	v_add_f32_e32 v66, v138, v66
	v_add_f32_e32 v67, v139, v65
	s_waitcnt lgkmcnt(2)
	v_mfma_f32_32x32x16_bf16 v[80:95], v[104:107], v[164:167], v[80:95]
	v_exp_f32_e32 v114, v76
	v_exp_f32_e32 v115, v77
	v_exp_f32_e32 v116, v78
	v_exp_f32_e32 v117, v79
	v_cvt_pk_bf16_f32 v71, v119, v71
	v_cvt_pk_bf16_f32 v64, v120, v121
	v_cvt_pk_bf16_f32 v65, v138, v139
	ds_read_b128 v[76:79], v210 offset:53280
	ds_read_b128 v[104:107], v210 offset:57888
	s_waitcnt lgkmcnt(3)
	v_mfma_f32_32x32x16_bf16 v[0:15], v[72:75], v[100:103], v[0:15]
	v_add_f32_e32 v72, v114, v66
	v_add_f32_e32 v67, v115, v67
	v_add_f32_e32 v112, v116, v72
	v_add_f32_e32 v113, v117, v67
	v_cvt_pk_bf16_f32 v66, v114, v115
	v_cvt_pk_bf16_f32 v67, v116, v117
	s_waitcnt lgkmcnt(2)
	v_mfma_f32_32x32x16_bf16 v[16:31], v[108:111], v[100:103], v[16:31]
	ds_read_b128 v[72:75], v210 offset:53312
	s_waitcnt lgkmcnt(2)
	v_mfma_f32_32x32x16_bf16 v[0:15], v[76:79], v[96:99], v[0:15]
	ds_read_b128 v[76:79], v210 offset:57920
	s_waitcnt lgkmcnt(2)
	v_mfma_f32_32x32x16_bf16 v[16:31], v[104:107], v[96:99], v[16:31]
	ds_read_b128 v[96:99], v210 offset:53344
	ds_read_b128 v[102:105], v210 offset:57952
	s_waitcnt lgkmcnt(3)
	v_mfma_f32_32x32x16_bf16 v[0:15], v[72:75], v[68:71], v[0:15]
	s_waitcnt lgkmcnt(2)
	v_mfma_f32_32x32x16_bf16 v[16:31], v[76:79], v[68:71], v[16:31]
	s_waitcnt lgkmcnt(1)
	v_mfma_f32_32x32x16_bf16 v[0:15], v[96:99], v[64:67], v[0:15]
	v_add_f32_e32 v221, v112, v113
	v_add_f32_e32 v100, v118, v221
	s_waitcnt lgkmcnt(0)
	v_mfma_f32_32x32x16_bf16 v[16:31], v[102:105], v[64:67], v[16:31]
	ds_read_b128 v[64:67], v181 offset:26624
	ds_read_b128 v[96:99], v181 offset:33280
	v_cmp_lt_f32_e32 vcc, s59, v221
	s_cbranch_vccz .LBB0_1008
	v_mov_b32_e32 v222, v221
	v_mov_b32_e32 v223, v221
	s_nop 1
	v_permlane32_swap_b32_e32 v222, v223
	v_add_f32_e32 v222, v222, v223
	v_log_f32_e32 v222, v222
	s_nop 0
	v_max_f32_e32 v33, 0, v222
	v_exp_f32_e64 v34, -v33
	v_add_f32_e32 v212, v212, v33
	v_xor_b32_e32 v32, 0x80000000, v212
	v_sub_f32_e32 v137, v137, v33
	v_pk_mul_f32 v[14:15], v[14:15], v[34:35] op_sel_hi:[1,0]
	v_pk_mul_f32 v[12:13], v[12:13], v[34:35] op_sel_hi:[1,0]
	v_pk_mul_f32 v[10:11], v[10:11], v[34:35] op_sel_hi:[1,0]
	v_pk_mul_f32 v[8:9], v[8:9], v[34:35] op_sel_hi:[1,0]
	v_pk_mul_f32 v[6:7], v[6:7], v[34:35] op_sel_hi:[1,0]
	v_pk_mul_f32 v[4:5], v[4:5], v[34:35] op_sel_hi:[1,0]
	v_pk_mul_f32 v[2:3], v[2:3], v[34:35] op_sel_hi:[1,0]
	v_pk_mul_f32 v[0:1], v[0:1], v[34:35] op_sel_hi:[1,0]
	v_pk_mul_f32 v[30:31], v[30:31], v[34:35] op_sel_hi:[1,0]
	v_pk_mul_f32 v[28:29], v[28:29], v[34:35] op_sel_hi:[1,0]
	v_pk_mul_f32 v[26:27], v[26:27], v[34:35] op_sel_hi:[1,0]
	v_pk_mul_f32 v[24:25], v[24:25], v[34:35] op_sel_hi:[1,0]
	v_pk_mul_f32 v[22:23], v[22:23], v[34:35] op_sel_hi:[1,0]
	v_pk_mul_f32 v[20:21], v[20:21], v[34:35] op_sel_hi:[1,0]
	v_pk_mul_f32 v[18:19], v[18:19], v[34:35] op_sel_hi:[1,0]
	v_pk_mul_f32 v[16:17], v[16:17], v[34:35] op_sel_hi:[1,0]
	v_sub_f32_e32 v136, v136, v33
	v_sub_f32_e32 v135, v135, v33
	v_sub_f32_e32 v134, v134, v33
	v_sub_f32_e32 v133, v133, v33
	v_sub_f32_e32 v132, v132, v33
	v_sub_f32_e32 v131, v131, v33
	v_sub_f32_e32 v130, v130, v33
	v_sub_f32_e32 v129, v129, v33
	v_sub_f32_e32 v128, v128, v33
	v_sub_f32_e32 v127, v127, v33
	v_sub_f32_e32 v126, v126, v33
	v_sub_f32_e32 v125, v125, v33
	v_sub_f32_e32 v124, v124, v33
	v_sub_f32_e32 v123, v123, v33
	v_sub_f32_e32 v122, v122, v33
	v_sub_f32_e32 v95, v95, v33
	v_sub_f32_e32 v94, v94, v33
	v_sub_f32_e32 v93, v93, v33
	v_sub_f32_e32 v92, v92, v33
	v_sub_f32_e32 v91, v91, v33
	v_sub_f32_e32 v90, v90, v33
	v_sub_f32_e32 v89, v89, v33
	v_sub_f32_e32 v88, v88, v33
	v_sub_f32_e32 v87, v87, v33
	v_sub_f32_e32 v86, v86, v33
	v_sub_f32_e32 v85, v85, v33
	v_sub_f32_e32 v84, v84, v33
	v_sub_f32_e32 v83, v83, v33
	v_sub_f32_e32 v82, v82, v33
	v_sub_f32_e32 v81, v81, v33
	v_sub_f32_e32 v80, v80, v33
	v_mul_f32_e32 v100, v100, v34
	v_mov_b32_e32 v33, v32
	v_mov_b32_e32 v34, v32
	v_mov_b32_e32 v35, v32
	v_mov_b32_e32 v36, v32
	v_mov_b32_e32 v37, v32
	v_mov_b32_e32 v38, v32
	v_mov_b32_e32 v39, v32
	v_mov_b32_e32 v40, v32
	v_mov_b32_e32 v41, v32
	v_mov_b32_e32 v42, v32
	v_mov_b32_e32 v43, v32
	v_mov_b32_e32 v44, v32
	v_mov_b32_e32 v45, v32
	v_mov_b32_e32 v46, v32
	v_mov_b32_e32 v47, v32
	v_mov_b32_e32 v48, v32
	v_mov_b32_e32 v49, v32
	v_mov_b32_e32 v50, v32
	v_mov_b32_e32 v51, v32
	v_mov_b32_e32 v52, v32
	v_mov_b32_e32 v53, v32
	v_mov_b32_e32 v54, v32
	v_mov_b32_e32 v55, v32
	v_mov_b32_e32 v56, v32
	v_mov_b32_e32 v57, v32
	v_mov_b32_e32 v58, v32
	v_mov_b32_e32 v59, v32
	v_mov_b32_e32 v60, v32
	v_mov_b32_e32 v61, v32
	v_mov_b32_e32 v62, v32
	v_mov_b32_e32 v63, v32

.LBB0_1012:
	ds_read_b128 v[102:105], v181 offset:26656
	ds_read_b128 v[138:141], v181 offset:33312
	s_waitcnt lgkmcnt(3)
	v_mfma_f32_32x32x16_bf16 v[106:121], v[64:67], v[144:147], v[32:47]
	v_exp_f32_e32 v101, v122
	v_exp_f32_e32 v142, v123
	v_exp_f32_e32 v143, v124
	v_exp_f32_e32 v202, v125
	v_exp_f32_e32 v126, v126
	v_exp_f32_e32 v127, v127
	s_waitcnt lgkmcnt(2)
	v_mfma_f32_32x32x16_bf16 v[64:79], v[96:99], v[144:147], v[32:47]
	ds_read_b128 v[96:99], v181 offset:26688
	ds_read_b128 v[122:125], v181 offset:33344
	s_waitcnt lgkmcnt(3)
	v_mfma_f32_32x32x16_bf16 v[106:121], v[102:105], v[148:151], v[106:121]
	v_cvt_pk_bf16_f32 v102, v101, v142
	v_add_f32_e32 v101, v143, v101
	v_add_f32_e32 v104, v202, v142
	v_add_f32_e32 v101, v126, v101
	s_waitcnt lgkmcnt(2)
	v_mfma_f32_32x32x16_bf16 v[64:79], v[138:141], v[148:151], v[64:79]
	v_add_f32_e32 v105, v127, v104
	v_exp_f32_e32 v203, v128
	v_exp_f32_e32 v204, v129
	v_exp_f32_e32 v205, v130
	v_exp_f32_e32 v213, v131
	v_exp_f32_e32 v214, v132
	v_exp_f32_e32 v215, v133
	v_cvt_pk_bf16_f32 v103, v143, v202
	v_cvt_pk_bf16_f32 v104, v126, v127
	ds_read_b128 v[126:129], v181 offset:26720
	ds_read_b128 v[130:133], v181 offset:33376
	s_waitcnt lgkmcnt(3)
	v_mfma_f32_32x32x16_bf16 v[106:121], v[96:99], v[152:155], v[106:121]
	v_add_f32_e32 v96, v203, v101
	v_add_f32_e32 v97, v204, v105
	v_add_f32_e32 v98, v205, v96
	v_add_f32_e32 v97, v213, v97
	v_add_f32_e32 v98, v214, v98
	v_add_f32_e32 v99, v215, v97
	s_waitcnt lgkmcnt(2)
	v_mfma_f32_32x32x16_bf16 v[64:79], v[122:125], v[152:155], v[64:79]
	v_exp_f32_e32 v138, v134
	v_exp_f32_e32 v139, v135
	v_exp_f32_e32 v140, v136
	v_exp_f32_e32 v141, v137
	v_cvt_pk_bf16_f32 v105, v203, v204
	v_cvt_pk_bf16_f32 v96, v205, v213
	v_cvt_pk_bf16_f32 v97, v214, v215
	ds_read_b128 v[122:125], v181 offset:26752
	ds_read_b128 v[134:137], v181 offset:33408
	s_waitcnt lgkmcnt(3)
	v_mfma_f32_32x32x16_bf16 v[106:121], v[126:129], v[156:159], v[106:121]
	v_exp_f32_e32 v101, v80
	v_exp_f32_e32 v142, v81
	v_add_f32_e32 v80, v138, v98
	v_add_f32_e32 v81, v139, v99
	v_exp_f32_e32 v203, v84
	v_exp_f32_e32 v204, v85
	s_waitcnt lgkmcnt(2)
	v_mfma_f32_32x32x16_bf16 v[64:79], v[130:133], v[156:159], v[64:79]
	v_add_f32_e32 v84, v140, v80
	v_add_f32_e32 v85, v141, v81
	v_exp_f32_e32 v143, v82
	v_exp_f32_e32 v202, v83
	v_cvt_pk_bf16_f32 v98, v138, v139
	v_cvt_pk_bf16_f32 v99, v140, v141
	ds_read_b128 v[80:83], v181 offset:26784
	ds_read_b128 v[126:129], v181 offset:33440
	s_waitcnt lgkmcnt(3)
	v_mfma_f32_32x32x16_bf16 v[106:121], v[122:125], v[160:163], v[106:121]
	v_exp_f32_e32 v87, v87
	v_exp_f32_e32 v130, v86
	v_add_f32_e32 v86, v101, v84
	v_add_f32_e32 v85, v142, v85
	v_exp_f32_e32 v131, v88
	v_add_f32_e32 v86, v143, v86
	s_waitcnt lgkmcnt(2)
	v_mfma_f32_32x32x16_bf16 v[64:79], v[134:137], v[160:163], v[64:79]
	v_add_f32_e32 v88, v202, v85
	v_cvt_pk_bf16_f32 v84, v101, v142
	v_add_f32_e32 v101, v203, v86
	v_add_f32_e32 v134, v204, v88
	v_exp_f32_e32 v132, v89
	v_exp_f32_e32 v133, v90
	v_exp_f32_e32 v138, v91
	v_cvt_pk_bf16_f32 v85, v143, v202
	v_cvt_pk_bf16_f32 v86, v203, v204
	ds_read_b128 v[88:91], v210 offset:62464
	ds_read_b128 v[122:125], v211 offset:13824
	s_waitcnt lgkmcnt(3)
	v_mfma_f32_32x32x16_bf16 v[106:121], v[80:83], v[164:167], v[106:121]
	v_add_f32_e32 v80, v130, v101
	v_add_f32_e32 v81, v87, v134
	v_add_f32_e32 v82, v131, v80
	v_add_f32_e32 v81, v132, v81
	v_add_f32_e32 v82, v133, v82
	v_add_f32_e32 v83, v138, v81
	s_waitcnt lgkmcnt(2)
	v_mfma_f32_32x32x16_bf16 v[64:79], v[126:129], v[164:167], v[64:79]
	v_exp_f32_e32 v135, v92
	v_exp_f32_e32 v136, v93
	v_exp_f32_e32 v137, v94
	v_exp_f32_e32 v139, v95
	v_cvt_pk_bf16_f32 v87, v130, v87
	v_cvt_pk_bf16_f32 v80, v131, v132
	v_cvt_pk_bf16_f32 v81, v133, v138
	ds_read_b128 v[92:95], v210 offset:62496
	ds_read_b128 v[126:129], v211 offset:13856
	s_waitcnt lgkmcnt(3)
	v_mfma_f32_32x32x16_bf16 v[0:15], v[88:91], v[102:105], v[0:15]
	v_add_f32_e32 v88, v135, v82
	v_add_f32_e32 v83, v136, v83
	v_add_f32_e32 v101, v137, v88
	v_add_f32_e32 v130, v139, v83
	v_cvt_pk_bf16_f32 v82, v135, v136
	v_cvt_pk_bf16_f32 v83, v137, v139
	s_waitcnt lgkmcnt(2)
	v_mfma_f32_32x32x16_bf16 v[16:31], v[122:125], v[102:105], v[16:31]
	ds_read_b128 v[88:91], v210 offset:62528
	s_waitcnt lgkmcnt(2)
	v_mfma_f32_32x32x16_bf16 v[0:15], v[92:95], v[96:99], v[0:15]
	ds_read_b128 v[92:95], v211 offset:13888
	s_waitcnt lgkmcnt(2)
	v_mfma_f32_32x32x16_bf16 v[16:31], v[126:129], v[96:99], v[16:31]
	ds_read_b128 v[96:99], v210 offset:62560
	ds_read_b128 v[102:105], v211 offset:13920
	s_waitcnt lgkmcnt(3)
	v_mfma_f32_32x32x16_bf16 v[0:15], v[88:91], v[84:87], v[0:15]
	s_waitcnt lgkmcnt(2)
	v_mfma_f32_32x32x16_bf16 v[16:31], v[92:95], v[84:87], v[16:31]
	s_waitcnt lgkmcnt(1)
	v_mfma_f32_32x32x16_bf16 v[0:15], v[96:99], v[80:83], v[0:15]
	v_add_f32_e32 v221, v101, v130
	v_add_f32_e32 v88, v100, v221
	s_waitcnt lgkmcnt(0)
	v_mfma_f32_32x32x16_bf16 v[16:31], v[102:105], v[80:83], v[16:31]
	s_waitcnt vmcnt(0)
	s_barrier
	ds_read_b128 v[84:87], v181 offset:39936
	ds_read_b128 v[80:83], v181 offset:46592
	v_cmp_lt_f32_e32 vcc, s59, v221
	s_cbranch_vccz .LBB0_1014
	v_mov_b32_e32 v222, v221
	v_mov_b32_e32 v223, v221
	s_nop 1
	v_permlane32_swap_b32_e32 v222, v223
	v_add_f32_e32 v222, v222, v223
	v_log_f32_e32 v222, v222
	s_nop 0
	v_max_f32_e32 v33, 0, v222
	v_exp_f32_e64 v34, -v33
	v_add_f32_e32 v212, v212, v33
	v_xor_b32_e32 v32, 0x80000000, v212
	v_sub_f32_e32 v121, v121, v33
	v_pk_mul_f32 v[14:15], v[14:15], v[34:35] op_sel_hi:[1,0]
	v_pk_mul_f32 v[12:13], v[12:13], v[34:35] op_sel_hi:[1,0]
	v_pk_mul_f32 v[10:11], v[10:11], v[34:35] op_sel_hi:[1,0]
	v_pk_mul_f32 v[8:9], v[8:9], v[34:35] op_sel_hi:[1,0]
	v_pk_mul_f32 v[6:7], v[6:7], v[34:35] op_sel_hi:[1,0]
	v_pk_mul_f32 v[4:5], v[4:5], v[34:35] op_sel_hi:[1,0]
	v_pk_mul_f32 v[2:3], v[2:3], v[34:35] op_sel_hi:[1,0]
	v_pk_mul_f32 v[0:1], v[0:1], v[34:35] op_sel_hi:[1,0]
	v_pk_mul_f32 v[30:31], v[30:31], v[34:35] op_sel_hi:[1,0]
	v_pk_mul_f32 v[28:29], v[28:29], v[34:35] op_sel_hi:[1,0]
	v_pk_mul_f32 v[26:27], v[26:27], v[34:35] op_sel_hi:[1,0]
	v_pk_mul_f32 v[24:25], v[24:25], v[34:35] op_sel_hi:[1,0]
	v_pk_mul_f32 v[22:23], v[22:23], v[34:35] op_sel_hi:[1,0]
	v_pk_mul_f32 v[20:21], v[20:21], v[34:35] op_sel_hi:[1,0]
	v_pk_mul_f32 v[18:19], v[18:19], v[34:35] op_sel_hi:[1,0]
	v_pk_mul_f32 v[16:17], v[16:17], v[34:35] op_sel_hi:[1,0]
	v_sub_f32_e32 v120, v120, v33
	v_sub_f32_e32 v119, v119, v33
	v_sub_f32_e32 v118, v118, v33
	v_sub_f32_e32 v117, v117, v33
	v_sub_f32_e32 v116, v116, v33
	v_sub_f32_e32 v115, v115, v33
	v_sub_f32_e32 v114, v114, v33
	v_sub_f32_e32 v113, v113, v33
	v_sub_f32_e32 v112, v112, v33
	v_sub_f32_e32 v111, v111, v33
	v_sub_f32_e32 v110, v110, v33
	v_sub_f32_e32 v109, v109, v33
	v_sub_f32_e32 v108, v108, v33
	v_sub_f32_e32 v107, v107, v33
	v_sub_f32_e32 v106, v106, v33
	v_sub_f32_e32 v79, v79, v33
	v_sub_f32_e32 v78, v78, v33
	v_sub_f32_e32 v77, v77, v33
	v_sub_f32_e32 v76, v76, v33
	v_sub_f32_e32 v75, v75, v33
	v_sub_f32_e32 v74, v74, v33
	v_sub_f32_e32 v73, v73, v33
	v_sub_f32_e32 v72, v72, v33
	v_sub_f32_e32 v71, v71, v33
	v_sub_f32_e32 v70, v70, v33
	v_sub_f32_e32 v69, v69, v33
	v_sub_f32_e32 v68, v68, v33
	v_sub_f32_e32 v67, v67, v33
	v_sub_f32_e32 v66, v66, v33
	v_sub_f32_e32 v65, v65, v33
	v_sub_f32_e32 v64, v64, v33
	v_mul_f32_e32 v88, v88, v34
	v_mov_b32_e32 v33, v32
	v_mov_b32_e32 v34, v32
	v_mov_b32_e32 v35, v32
	v_mov_b32_e32 v36, v32
	v_mov_b32_e32 v37, v32
	v_mov_b32_e32 v38, v32
	v_mov_b32_e32 v39, v32
	v_mov_b32_e32 v40, v32
	v_mov_b32_e32 v41, v32
	v_mov_b32_e32 v42, v32
	v_mov_b32_e32 v43, v32
	v_mov_b32_e32 v44, v32
	v_mov_b32_e32 v45, v32
	v_mov_b32_e32 v46, v32
	v_mov_b32_e32 v47, v32
	v_mov_b32_e32 v48, v32
	v_mov_b32_e32 v49, v32
	v_mov_b32_e32 v50, v32
	v_mov_b32_e32 v51, v32
	v_mov_b32_e32 v52, v32
	v_mov_b32_e32 v53, v32
	v_mov_b32_e32 v54, v32
	v_mov_b32_e32 v55, v32
	v_mov_b32_e32 v56, v32
	v_mov_b32_e32 v57, v32
	v_mov_b32_e32 v58, v32
	v_mov_b32_e32 v59, v32
	v_mov_b32_e32 v60, v32
	v_mov_b32_e32 v61, v32
	v_mov_b32_e32 v62, v32
	v_mov_b32_e32 v63, v32

.LBB0_1018:
	s_waitcnt lgkmcnt(1)
	v_mfma_f32_32x32x16_bf16 v[122:137], v[84:87], v[144:147], v[32:47]
	v_exp_f32_e32 v89, v106
	v_exp_f32_e32 v94, v107
	v_exp_f32_e32 v95, v108
	v_exp_f32_e32 v142, v109
	v_exp_f32_e32 v143, v110
	v_exp_f32_e32 v202, v111
	ds_read_b128 v[84:87], v181 offset:39968
	ds_read_b128 v[90:93], v181 offset:46624
	s_waitcnt lgkmcnt(2)
	v_mfma_f32_32x32x16_bf16 v[96:111], v[80:83], v[144:147], v[32:47]
	ds_read_b128 v[80:83], v181 offset:40000
	ds_read_b128 v[138:141], v181 offset:46656
	s_waitcnt lgkmcnt(3)
	v_mfma_f32_32x32x16_bf16 v[122:137], v[84:87], v[148:151], v[122:137]
	v_exp_f32_e32 v116, v116
	v_add_f32_e32 v87, v95, v89
	v_add_f32_e32 v86, v142, v94
	v_cvt_pk_bf16_f32 v84, v89, v94
	s_waitcnt lgkmcnt(2)
	v_mfma_f32_32x32x16_bf16 v[96:111], v[90:93], v[148:151], v[96:111]
	v_add_f32_e32 v87, v143, v87
	v_add_f32_e32 v89, v202, v86
	v_exp_f32_e32 v203, v112
	v_exp_f32_e32 v204, v113
	v_exp_f32_e32 v205, v114
	v_exp_f32_e32 v213, v115
	v_exp_f32_e32 v117, v117
	v_cvt_pk_bf16_f32 v85, v95, v142
	v_cvt_pk_bf16_f32 v86, v143, v202
	ds_read_b128 v[90:93], v181 offset:40032
	ds_read_b128 v[112:115], v181 offset:46688
	s_waitcnt lgkmcnt(3)
	v_mfma_f32_32x32x16_bf16 v[122:137], v[80:83], v[152:155], v[122:137]
	v_add_f32_e32 v80, v203, v87
	v_add_f32_e32 v81, v204, v89
	v_add_f32_e32 v82, v205, v80
	v_add_f32_e32 v81, v213, v81
	v_add_f32_e32 v82, v116, v82
	v_add_f32_e32 v83, v117, v81
	s_waitcnt lgkmcnt(2)
	v_mfma_f32_32x32x16_bf16 v[96:111], v[138:141], v[152:155], v[96:111]
	v_exp_f32_e32 v94, v118
	v_exp_f32_e32 v95, v119
	v_exp_f32_e32 v120, v120
	v_exp_f32_e32 v121, v121
	v_cvt_pk_bf16_f32 v87, v203, v204
	v_cvt_pk_bf16_f32 v80, v205, v213
	v_cvt_pk_bf16_f32 v81, v116, v117
	ds_read_b128 v[116:119], v181 offset:40064
	ds_read_b128 v[138:141], v181 offset:46720
	s_waitcnt lgkmcnt(3)
	v_mfma_f32_32x32x16_bf16 v[122:137], v[90:93], v[156:159], v[122:137]
	v_exp_f32_e32 v89, v64
	v_exp_f32_e32 v142, v65
	v_add_f32_e32 v64, v94, v82
	v_add_f32_e32 v65, v95, v83
	v_exp_f32_e32 v203, v68
	v_exp_f32_e32 v204, v69
	s_waitcnt lgkmcnt(2)
	v_mfma_f32_32x32x16_bf16 v[96:111], v[112:115], v[156:159], v[96:111]
	v_add_f32_e32 v68, v120, v64
	v_add_f32_e32 v69, v121, v65
	v_exp_f32_e32 v143, v66
	v_exp_f32_e32 v202, v67
	v_cvt_pk_bf16_f32 v82, v94, v95
	v_cvt_pk_bf16_f32 v83, v120, v121
	ds_read_b128 v[64:67], v181 offset:40096
	ds_read_b128 v[90:93], v181 offset:46752
	s_waitcnt lgkmcnt(3)
	v_mfma_f32_32x32x16_bf16 v[122:137], v[116:119], v[160:163], v[122:137]
	v_exp_f32_e32 v116, v74
	v_exp_f32_e32 v94, v70
	v_add_f32_e32 v70, v89, v68
	v_add_f32_e32 v69, v142, v69
	v_exp_f32_e32 v95, v72
	v_add_f32_e32 v70, v143, v70
	s_waitcnt lgkmcnt(2)
	v_mfma_f32_32x32x16_bf16 v[96:111], v[138:141], v[160:163], v[96:111]
	v_add_f32_e32 v72, v202, v69
	v_cvt_pk_bf16_f32 v68, v89, v142
	v_add_f32_e32 v89, v203, v70
	v_add_f32_e32 v118, v204, v72
	v_exp_f32_e32 v71, v71
	v_exp_f32_e32 v120, v73
	v_exp_f32_e32 v117, v75
	v_cvt_pk_bf16_f32 v69, v143, v202
	v_cvt_pk_bf16_f32 v70, v203, v204
	ds_read_b128 v[72:75], v211 offset:18432
	ds_read_b128 v[112:115], v211 offset:23040
	s_waitcnt lgkmcnt(3)
	v_mfma_f32_32x32x16_bf16 v[122:137], v[64:67], v[164:167], v[122:137]
	v_add_f32_e32 v64, v94, v89
	v_add_f32_e32 v65, v71, v118
	v_add_f32_e32 v66, v95, v64
	v_add_f32_e32 v65, v120, v65
	v_add_f32_e32 v66, v116, v66
	v_add_f32_e32 v67, v117, v65
	s_waitcnt lgkmcnt(2)
	v_mfma_f32_32x32x16_bf16 v[96:111], v[90:93], v[164:167], v[96:111]
	v_exp_f32_e32 v119, v76
	v_exp_f32_e32 v121, v77
	v_exp_f32_e32 v138, v78
	v_exp_f32_e32 v139, v79
	v_cvt_pk_bf16_f32 v71, v94, v71
	v_cvt_pk_bf16_f32 v64, v95, v120
	v_cvt_pk_bf16_f32 v65, v116, v117
	ds_read_b128 v[76:79], v211 offset:18464
	ds_read_b128 v[90:93], v211 offset:23072
	s_waitcnt lgkmcnt(3)
	v_mfma_f32_32x32x16_bf16 v[0:15], v[72:75], v[84:87], v[0:15]
	v_add_f32_e32 v72, v119, v66
	v_add_f32_e32 v67, v121, v67
	v_add_f32_e32 v89, v138, v72
	v_add_f32_e32 v94, v139, v67
	v_cvt_pk_bf16_f32 v66, v119, v121
	v_cvt_pk_bf16_f32 v67, v138, v139
	s_waitcnt lgkmcnt(2)
	v_mfma_f32_32x32x16_bf16 v[16:31], v[112:115], v[84:87], v[16:31]
	ds_read_b128 v[72:75], v211 offset:18496
	s_waitcnt lgkmcnt(2)
	v_mfma_f32_32x32x16_bf16 v[0:15], v[76:79], v[80:83], v[0:15]
	ds_read_b128 v[76:79], v211 offset:23104
	s_waitcnt lgkmcnt(2)
	v_mfma_f32_32x32x16_bf16 v[16:31], v[90:93], v[80:83], v[16:31]
	ds_read_b128 v[80:83], v211 offset:18528
	ds_read_b128 v[84:87], v211 offset:23136
	s_waitcnt lgkmcnt(3)
	v_mfma_f32_32x32x16_bf16 v[0:15], v[72:75], v[68:71], v[0:15]
	s_waitcnt lgkmcnt(2)
	v_mfma_f32_32x32x16_bf16 v[16:31], v[76:79], v[68:71], v[16:31]
	s_waitcnt lgkmcnt(1)
	v_mfma_f32_32x32x16_bf16 v[0:15], v[80:83], v[64:67], v[0:15]
	v_add_f32_e32 v221, v89, v94
	v_add_f32_e32 v116, v88, v221
	s_waitcnt lgkmcnt(0)
	v_mfma_f32_32x32x16_bf16 v[16:31], v[84:87], v[64:67], v[16:31]
	ds_read_b128 v[64:67], v181
	ds_read_b128 v[112:115], v181 offset:6656
	v_cmp_lt_f32_e32 vcc, s59, v221
	s_cbranch_vccz .LBB0_1020
	v_mov_b32_e32 v222, v221
	v_mov_b32_e32 v223, v221
	s_nop 1
	v_permlane32_swap_b32_e32 v222, v223
	v_add_f32_e32 v222, v222, v223
	v_log_f32_e32 v222, v222
	s_nop 0
	v_max_f32_e32 v33, 0, v222
	v_exp_f32_e64 v34, -v33
	v_add_f32_e32 v212, v212, v33
	v_xor_b32_e32 v32, 0x80000000, v212
	v_sub_f32_e32 v137, v137, v33
	v_pk_mul_f32 v[14:15], v[14:15], v[34:35] op_sel_hi:[1,0]
	v_pk_mul_f32 v[12:13], v[12:13], v[34:35] op_sel_hi:[1,0]
	v_pk_mul_f32 v[10:11], v[10:11], v[34:35] op_sel_hi:[1,0]
	v_pk_mul_f32 v[8:9], v[8:9], v[34:35] op_sel_hi:[1,0]
	v_pk_mul_f32 v[6:7], v[6:7], v[34:35] op_sel_hi:[1,0]
	v_pk_mul_f32 v[4:5], v[4:5], v[34:35] op_sel_hi:[1,0]
	v_pk_mul_f32 v[2:3], v[2:3], v[34:35] op_sel_hi:[1,0]
	v_pk_mul_f32 v[0:1], v[0:1], v[34:35] op_sel_hi:[1,0]
	v_pk_mul_f32 v[30:31], v[30:31], v[34:35] op_sel_hi:[1,0]
	v_pk_mul_f32 v[28:29], v[28:29], v[34:35] op_sel_hi:[1,0]
	v_pk_mul_f32 v[26:27], v[26:27], v[34:35] op_sel_hi:[1,0]
	v_pk_mul_f32 v[24:25], v[24:25], v[34:35] op_sel_hi:[1,0]
	v_pk_mul_f32 v[22:23], v[22:23], v[34:35] op_sel_hi:[1,0]
	v_pk_mul_f32 v[20:21], v[20:21], v[34:35] op_sel_hi:[1,0]
	v_pk_mul_f32 v[18:19], v[18:19], v[34:35] op_sel_hi:[1,0]
	v_pk_mul_f32 v[16:17], v[16:17], v[34:35] op_sel_hi:[1,0]
	v_sub_f32_e32 v136, v136, v33
	v_sub_f32_e32 v135, v135, v33
	v_sub_f32_e32 v134, v134, v33
	v_sub_f32_e32 v133, v133, v33
	v_sub_f32_e32 v132, v132, v33
	v_sub_f32_e32 v131, v131, v33
	v_sub_f32_e32 v130, v130, v33
	v_sub_f32_e32 v129, v129, v33
	v_sub_f32_e32 v128, v128, v33
	v_sub_f32_e32 v127, v127, v33
	v_sub_f32_e32 v126, v126, v33
	v_sub_f32_e32 v125, v125, v33
	v_sub_f32_e32 v124, v124, v33
	v_sub_f32_e32 v123, v123, v33
	v_sub_f32_e32 v122, v122, v33
	v_sub_f32_e32 v111, v111, v33
	v_sub_f32_e32 v110, v110, v33
	v_sub_f32_e32 v109, v109, v33
	v_sub_f32_e32 v108, v108, v33
	v_sub_f32_e32 v107, v107, v33
	v_sub_f32_e32 v106, v106, v33
	v_sub_f32_e32 v105, v105, v33
	v_sub_f32_e32 v104, v104, v33
	v_sub_f32_e32 v103, v103, v33
	v_sub_f32_e32 v102, v102, v33
	v_sub_f32_e32 v101, v101, v33
	v_sub_f32_e32 v100, v100, v33
	v_sub_f32_e32 v99, v99, v33
	v_sub_f32_e32 v98, v98, v33
	v_sub_f32_e32 v97, v97, v33
	v_sub_f32_e32 v96, v96, v33
	v_mul_f32_e32 v116, v116, v34
	v_mov_b32_e32 v33, v32
	v_mov_b32_e32 v34, v32
	v_mov_b32_e32 v35, v32
	v_mov_b32_e32 v36, v32
	v_mov_b32_e32 v37, v32
	v_mov_b32_e32 v38, v32
	v_mov_b32_e32 v39, v32
	v_mov_b32_e32 v40, v32
	v_mov_b32_e32 v41, v32
	v_mov_b32_e32 v42, v32
	v_mov_b32_e32 v43, v32
	v_mov_b32_e32 v44, v32
	v_mov_b32_e32 v45, v32
	v_mov_b32_e32 v46, v32
	v_mov_b32_e32 v47, v32
	v_mov_b32_e32 v48, v32
	v_mov_b32_e32 v49, v32
	v_mov_b32_e32 v50, v32
	v_mov_b32_e32 v51, v32
	v_mov_b32_e32 v52, v32
	v_mov_b32_e32 v53, v32
	v_mov_b32_e32 v54, v32
	v_mov_b32_e32 v55, v32
	v_mov_b32_e32 v56, v32
	v_mov_b32_e32 v57, v32
	v_mov_b32_e32 v58, v32
	v_mov_b32_e32 v59, v32
	v_mov_b32_e32 v60, v32
	v_mov_b32_e32 v61, v32
	v_mov_b32_e32 v62, v32
	v_mov_b32_e32 v63, v32

; __global__ void __launch_bounds__(512, 2) fwd_kernel(Params P) {
	.amdhsa_kernel _Z10fwd_kernel6Params
		.amdhsa_group_segment_fixed_size 0
		.amdhsa_private_segment_fixed_size 0
		.amdhsa_kernarg_size 440
		.amdhsa_user_sgpr_count 2
		.amdhsa_user_sgpr_dispatch_ptr 0
		.amdhsa_user_sgpr_queue_ptr 0
		.amdhsa_user_sgpr_kernarg_segment_ptr 1
		.amdhsa_user_sgpr_dispatch_id 0
		.amdhsa_user_sgpr_kernarg_preload_length 0
		.amdhsa_user_sgpr_kernarg_preload_offset 0
		.amdhsa_user_sgpr_private_segment_size 0
		.amdhsa_uses_dynamic_stack 0
		.amdhsa_enable_private_segment 0
		.amdhsa_system_sgpr_workgroup_id_x 1
		.amdhsa_system_sgpr_workgroup_id_y 0
		.amdhsa_system_sgpr_workgroup_id_z 0
		.amdhsa_system_sgpr_workgroup_info 0
		.amdhsa_system_vgpr_workitem_id 2
		.amdhsa_next_free_vgpr 245
		.amdhsa_next_free_sgpr 102
		.amdhsa_accum_offset 248
		.amdhsa_reserve_vcc 1
		.amdhsa_float_round_mode_32 0
		.amdhsa_float_round_mode_16_64 0
		.amdhsa_float_denorm_mode_32 3
		.amdhsa_float_denorm_mode_16_64 3
		.amdhsa_dx10_clamp 1
		.amdhsa_ieee_mode 1
		.amdhsa_fp16_overflow 0
		.amdhsa_tg_split 0
		.amdhsa_exception_fp_ieee_invalid_op 0
		.amdhsa_exception_fp_denorm_src 0
		.amdhsa_exception_fp_ieee_div_zero 0
		.amdhsa_exception_fp_ieee_overflow 0
		.amdhsa_exception_fp_ieee_underflow 0
		.amdhsa_exception_fp_ieee_inexact 0
		.amdhsa_exception_int_div_zero 0
	.end_amdhsa_kernel

; __global__ void __launch_bounds__(512, 2) fwd_kernel(Params P) {
amdhsa.kernels:
  - .agpr_count:     0
    .args:
      - .offset:         0
        .size:           184
        .value_kind:     by_value
      - .offset:         184
        .size:           4
        .value_kind:     hidden_block_count_x
      - .offset:         188
        .size:           4
        .value_kind:     hidden_block_count_y
      - .offset:         192
        .size:           4
        .value_kind:     hidden_block_count_z
      - .offset:         196
        .size:           2
        .value_kind:     hidden_group_size_x
      - .offset:         198
        .size:           2
        .value_kind:     hidden_group_size_y
      - .offset:         200
        .size:           2
        .value_kind:     hidden_group_size_z
      - .offset:         202
        .size:           2
        .value_kind:     hidden_remainder_x
      - .offset:         204
        .size:           2
        .value_kind:     hidden_remainder_y
      - .offset:         206
        .size:           2
        .value_kind:     hidden_remainder_z
      - .offset:         224
        .size:           8
        .value_kind:     hidden_global_offset_x
      - .offset:         232
        .size:           8
        .value_kind:     hidden_global_offset_y
      - .offset:         240
        .size:           8
        .value_kind:     hidden_global_offset_z
      - .offset:         248
        .size:           2
        .value_kind:     hidden_grid_dims
      - .offset:         272
        .size:           8
        .value_kind:     hidden_multigrid_sync_arg
      - .offset:         304
        .size:           4
        .value_kind:     hidden_dynamic_lds_size
    .group_segment_fixed_size: 0
    .kernarg_segment_align: 8
    .kernarg_segment_size: 440
    .language:       OpenCL C
    .language_version:
      - 2
      - 0
    .max_flat_workgroup_size: 512
    .name:           _Z10fwd_kernel6Params
    .private_segment_fixed_size: 0
    .sgpr_count:     108
    .sgpr_spill_count: 37
    .symbol:         _Z10fwd_kernel6Params.kd
    .uniform_work_group_size: 1
    .uses_dynamic_stack: false
    .vgpr_count:     245
    .vgpr_spill_count: 0
    .wavefront_size: 64
